# unrolled GEMM k-steps: first fragment ds_reads of the new stage issued before the 8 LDS-DMA issues after each stage barrier (30 sites, DMA address temps renamed)
# speedup vs baseline: 1.0052x; 1.0001x over previous
; #define WAIT_V0() asm volatile("s_waitcnt vmcnt(0)" ::: "memory")
; DI int glds_row(int i) { const int tid = ltid(); return ((tid >> 6) * 4 + i) * 8 + ((tid & 63) >> 3); }
; DI int glds_chunk(int row) { return (ltid() & 7) ^ ((row >> 1) & 7); }
; DI void gemm_core(char* smem, int nk, const char* Ab, const char* Bb, const unsigned (&aoff)[4], const unsigned (&boff)[4],
;                   f32x16 (&acc)[2][2]) {
;     ...
;   auto stage = [&](int buf, int kt) __attribute__((always_inline)) {
;     const char* ak = Ab + kt * 128;
;     const char* bk = Bb + kt * 128;
;     char* sa = smem + buf * STAGE_B + w * 4096;
; #pragma unroll
;     for (int i = 0; i < 4; ++i) {
;       __builtin_amdgcn_global_load_lds((const unsigned*)(ak + aoff[i]), (unsigned*)(sa + i * 1024), 16, 0, 0);
;       __builtin_amdgcn_global_load_lds((const unsigned*)(bk + boff[i]), (unsigned*)(sa + 16384 + i * 1024), 16, 0, 0);
;     }
;   };
;   stage(0, 0);
;   WAIT_V0();
;   __syncthreads();
; DI void phase_up(const Params& P, int layer, char* smem) {
;     ...
;   for (int t0 = blockIdx.x; t0 < MT * NT; t0 += gridDim.x) {
;     const int tl = xcd_tile(t0, MT * NT) - (t0 & 7) * ((MT * NT) >> 3);
;     const int mt = (t0 & 1) * 131 + tl / 11, nt = ((t0 & 7) >> 1) * 11 + tl % 11;
;     const int b = mt / 131, i = mt % 131;
;     const int tb0 = i * 126 - 2;
;     unsigned aoff[4], boff[4];
;     const char* Abase = (const char*)(hn + (size_t)b * S_ * 1024);
;     const unsigned zoff = (unsigned)((P.ws + OFF_ZPAGE) - Abase);
; #pragma unroll
;     for (int q = 0; q < 4; ++q) {
;       const int r = glds_row(q), ch = glds_chunk(r);
;       const int tb = tb0 + r;
;       const bool ok = (tb >= 0) && (tb < S_);
;       aoff[q] = ok ? (unsigned)((tb * 1024 + ch * 8) * 2) : zoff;
;       const int wr = (r < 64) ? (nt * 64 + r) : (DFF + nt * 64 + r - 64);
;       boff[q] = (unsigned)((wr * 1024 + ch * 8) * 2);
;     }
;     f32x16 acc[2][2];
;     gemm_core(smem, 16, Abase, (const char*)wup, aoff, boff, acc);
.LBB0_25:
	s_ashr_i32 s18, s2, 3
	s_and_b32 s19, s18, 0xffffffc0
	s_lshl_b32 s20, s18, 1
	s_bfe_u32 s21, s18, 0x10005
	s_and_b32 s20, s20, 62
	s_or_b32 s19, s21, s19
	s_or_b32 s19, s19, s20
	s_or_b32 s20, s18, 63
	s_cmpk_lt_i32 s20, 0x5a1
	s_cselect_b32 s18, s19, s18
	s_bitcmp1_b32 s2, 0
	s_mul_hi_i32 s20, s18, 0x2e8ba2e9
	s_cselect_b32 s19, 0x83, 0
	s_lshr_b32 s21, s20, 31
	s_ashr_i32 s20, s20, 1
	s_add_i32 s21, s20, s21
	s_add_i32 s20, s21, s19
	s_bfe_u32 s19, s2, 0x20001
	s_mul_i32 s21, s21, 11
	s_mul_i32 s19, s19, 11
	s_sub_i32 s18, s18, s21
	s_add_i32 s21, s18, s19
	s_mul_hi_i32 s18, s20, 0x3e88cb3d
	s_lshr_b32 s19, s18, 31
	s_ashr_i32 s18, s18, 5
	v_mov_b32_e32 v0, v161
	s_add_i32 s68, s18, s19
	s_mul_i32 s18, s68, 0x83
	v_ashrrev_i32_e32 v1, 1, v0
	v_lshrrev_b32_e32 v2, 3, v0
	v_bfe_u32 v0, v0, 3, 3
	s_movk_i32 s3, 0xffe0
	s_sub_i32 s28, s20, s18
	v_and_or_b32 v0, v1, s3, v0
	v_mov_b32_e32 v1, v161
	s_mulk_i32 s28, 0x7e
	s_ashr_i32 s69, s68, 31
	v_bfe_u32 v2, v2, 1, 2
	s_add_i32 s29, s28, -2
	s_lshl_b64 s[22:23], s[68:69], 25
	v_xor_b32_e32 v1, v2, v1
	s_add_u32 s18, s84, s22
	v_lshlrev_b32_e32 v1, 4, v1
	s_addc_u32 s19, s85, s23
	s_sub_i32 s22, 0x1b508000, s22
	s_lshl_b32 s21, s21, 6
	v_add_u32_e32 v2, s29, v0
	v_and_b32_e32 v1, 0x70, v1
	s_movk_i32 s3, 0x4000
	s_add_i32 s23, s21, 0xac0
	v_lshl_or_b32 v3, v2, 11, v1
	v_mov_b32_e32 v4, s22
	v_cmp_gt_u32_e32 vcc, s3, v2
	v_mov_b32_e32 v5, s21
	v_mov_b32_e32 v12, v161
	v_cndmask_b32_e32 v136, v4, v3, vcc
	v_mov_b32_e32 v3, s23
	v_cmp_gt_i32_e32 vcc, 64, v0
	v_lshl_add_u64 v[64:65], s[18:19], 0, v[136:137]
	s_mov_b64 s[4:5], 0x100
	v_cndmask_b32_e32 v2, v3, v5, vcc
	v_add_u32_e32 v0, v2, v0
	v_lshl_or_b32 v76, v0, 11, v1
	v_mov_b32_e32 v0, v161
	s_mov_b64 s[6:7], 0x780
	v_ashrrev_i32_e32 v1, 1, v0
	v_and_b32_e32 v1, 0xffffffe0, v1
	v_bfe_u32 v0, v0, 3, 3
	v_or3_b32 v1, v1, v0, 8
	v_mov_b32_e32 v0, v161
	v_lshrrev_b32_e32 v2, 1, v1
	v_xor_b32_e32 v0, v2, v0
	v_lshlrev_b32_e32 v0, 4, v0
	v_add_u32_e32 v2, s29, v1
	v_and_b32_e32 v6, 0x70, v0
	v_lshl_or_b32 v0, v2, 11, v6
	v_cmp_gt_u32_e32 vcc, s3, v2
	s_nop 1
	v_cndmask_b32_e32 v0, v4, v0, vcc
	v_cmp_gt_i32_e32 vcc, 64, v1
	s_nop 1
	v_cndmask_b32_e32 v2, v3, v5, vcc
	v_add_u32_e32 v1, v2, v1
	v_lshl_or_b32 v77, v1, 11, v6
	v_mov_b32_e32 v1, v161
	s_nop 0
	v_ashrrev_i32_e32 v2, 1, v1
	v_and_b32_e32 v2, 0xffffffe0, v2
	v_lshrrev_b32_e32 v6, 3, v1
	v_bfe_u32 v1, v1, 3, 3
	v_or3_b32 v1, v2, v1, 16
	v_mov_b32_e32 v2, v161
	v_bfe_u32 v6, v6, 1, 2
	v_xor_b32_e32 v2, v6, v2
	v_lshlrev_b32_e32 v2, 4, v2
	v_add_u32_e32 v6, s29, v1
	v_and_b32_e32 v7, 0x70, v2
	v_lshl_or_b32 v2, v6, 11, v7
	v_cmp_gt_u32_e32 vcc, s3, v6
	s_nop 1
	v_cndmask_b32_e32 v2, v4, v2, vcc
	v_cmp_gt_i32_e32 vcc, 64, v1
	s_nop 1
	v_cndmask_b32_e32 v6, v3, v5, vcc
	v_add_u32_e32 v1, v6, v1
	v_lshl_or_b32 v78, v1, 11, v7
	v_mov_b32_e32 v1, v161
	s_nop 0
	v_ashrrev_i32_e32 v6, 1, v1
	v_and_b32_e32 v6, 0xffffffe0, v6
	v_bfe_u32 v1, v1, 3, 3
	v_or3_b32 v1, v6, v1, 24
	v_mov_b32_e32 v6, v161
	v_lshrrev_b32_e32 v7, 1, v1
	v_xor_b32_e32 v6, v7, v6
	v_lshlrev_b32_e32 v6, 4, v6
	v_add_u32_e32 v7, s29, v1
	v_and_b32_e32 v6, 0x70, v6
	v_lshl_or_b32 v8, v7, 11, v6
	v_cmp_gt_u32_e32 vcc, s3, v7
	s_mov_b32 s3, 0x1ffffc0
	v_bfe_u32 v86, v12, 1, 3
	v_cndmask_b32_e32 v4, v4, v8, vcc
	v_cmp_gt_i32_e32 vcc, 64, v1
	v_bfe_u32 v117, v12, 5, 1
	s_nop 0
	v_cndmask_b32_e32 v3, v3, v5, vcc
	v_add_u32_e32 v1, v3, v1
	v_lshl_or_b32 v84, v1, 11, v6
	v_and_b32_e32 v1, 31, v12
	v_lshrrev_b32_e32 v5, 1, v12
	v_and_or_b32 v1, v5, s3, v1
	v_lshlrev_b32_e32 v87, 7, v1
	v_lshlrev_b32_e32 v1, 6, v12
	v_and_b32_e32 v97, 0xfffff000, v1
	v_add_u32_e32 v96, 0x4000, v97
	v_readfirstlane_b32 s84, v97
	s_mov_b32 m0, s84
	v_readfirstlane_b32 s85, v96
	v_or_b32_e32 v98, 0x400, v97
	global_load_lds_dwordx4 v136, s[18:19]
	s_mov_b32 m0, s85
	v_readfirstlane_b32 s86, v98
	v_add_u32_e32 v99, 0x4400, v97
	global_load_lds_dwordx4 v76, s[0:1]
	s_mov_b32 m0, s86
	v_readfirstlane_b32 s87, v99
	v_or_b32_e32 v100, 0x800, v97
	global_load_lds_dwordx4 v0, s[18:19]
	s_mov_b32 m0, s87
	v_readfirstlane_b32 s88, v100
	v_add_u32_e32 v101, 0x4800, v97
	v_lshrrev_b32_e32 v3, 5, v12
	global_load_lds_dwordx4 v77, s[0:1]
	s_mov_b32 m0, s88
	v_readfirstlane_b32 s89, v101
	v_or_b32_e32 v102, 0xc00, v97
	v_bitop3_b32 v3, v3, v86, 1 bitop3:0x6c
	global_load_lds_dwordx4 v2, s[18:19]
	s_mov_b32 m0, s89
	v_readfirstlane_b32 s90, v102
	v_add_u32_e32 v103, 0x4c00, v97
	v_lshlrev_b32_e32 v6, 4, v3
	v_mov_b32_e32 v1, v137
	v_mov_b32_e32 v3, v137
	global_load_lds_dwordx4 v78, s[0:1]
	v_mov_b32_e32 v5, v137
	s_mov_b32 m0, s90
	v_readfirstlane_b32 s91, v103
	v_add_u32_e32 v89, 0x8000, v97
	v_lshl_add_u64 v[66:67], s[18:19], 0, v[0:1]
	v_lshl_add_u64 v[68:69], s[18:19], 0, v[2:3]
	v_lshl_add_u64 v[70:71], s[18:19], 0, v[4:5]
	global_load_lds_dwordx4 v4, s[18:19]
	s_mov_b32 m0, s91
	v_add_u32_e32 v88, 0xc000, v97
	v_readfirstlane_b32 s18, v89
	global_load_lds_dwordx4 v84, s[0:1]
	v_lshl_add_u64 v[0:1], v[64:65], 0, s[94:95]
	s_mov_b32 m0, s18
	v_readfirstlane_b32 s19, v88
	v_add_u32_e32 v90, 0x8400, v97
	global_load_lds_dwordx4 v[0:1], off
	s_mov_b32 m0, s19
	v_readfirstlane_b32 s22, v90
	v_add_u32_e32 v91, 0xc400, v97
	global_load_lds_dwordx4 v76, s[14:15]
	v_lshl_add_u64 v[0:1], v[66:67], 0, s[94:95]
	s_mov_b32 m0, s22
	v_readfirstlane_b32 s23, v91
	v_add_u32_e32 v92, 0x8800, v97
	global_load_lds_dwordx4 v[0:1], off
	s_mov_b32 m0, s23
	v_readfirstlane_b32 s29, v92
	v_add_u32_e32 v93, 0xc800, v97
	global_load_lds_dwordx4 v77, s[14:15]
	v_lshl_add_u64 v[0:1], v[68:69], 0, s[94:95]
	s_mov_b32 m0, s29
	v_readfirstlane_b32 s69, v93
	v_add_u32_e32 v94, 0x8c00, v97
	global_load_lds_dwordx4 v[0:1], off
	s_mov_b32 m0, s69
	v_readfirstlane_b32 s70, v94
	v_add_u32_e32 v95, 0xcc00, v97
	global_load_lds_dwordx4 v78, s[14:15]
	v_lshl_add_u64 v[0:1], v[70:71], 0, s[94:95]
	s_mov_b32 m0, s70
	v_readfirstlane_b32 s71, v95
	global_load_lds_dwordx4 v[0:1], off
	s_mov_b32 m0, s71
	v_or_b32_e32 v79, v87, v6
	global_load_lds_dwordx4 v84, s[14:15]
	s_waitcnt vmcnt(8)
	s_waitcnt vmcnt(8) lgkmcnt(0)
	s_barrier
; #define WAIT_V0() asm volatile("s_waitcnt vmcnt(0)" ::: "memory")
; DI void gemm_core(char* smem, int nk, const char* Ab, const char* Bb, const unsigned (&aoff)[4], const unsigned (&boff)[4],
;                   f32x16 (&acc)[2][2]) {
;     ...
;   auto stage = [&](int buf, int kt) __attribute__((always_inline)) {
;     const char* ak = Ab + kt * 128;
;     const char* bk = Bb + kt * 128;
;     char* sa = smem + buf * STAGE_B + w * 4096;
; #pragma unroll
;     for (int i = 0; i < 4; ++i) {
;       __builtin_amdgcn_global_load_lds((const unsigned*)(ak + aoff[i]), (unsigned*)(sa + i * 1024), 16, 0, 0);
;       __builtin_amdgcn_global_load_lds((const unsigned*)(bk + boff[i]), (unsigned*)(sa + 16384 + i * 1024), 16, 0, 0);
;     }
;   };
;     ...
;   for (int kt = 0; kt < nk; ++kt) {
;     const int cur = kt & 1;
;     if (kt + 1 < nk) stage(cur ^ 1, kt + 1);
;     const char* sb = smem + cur * STAGE_B;
; #pragma unroll
;     for (int ks = 0; ks < 4; ++ks) {
;       bf16x8 af[2], bfr[2];
; #pragma unroll
;       for (int mb = 0; mb < 2; ++mb) af[mb] = *(const bf16x8*)(sb + a_base + mb * 4096 + xo[ks]);
; #pragma unroll
;       for (int nb = 0; nb < 2; ++nb) bfr[nb] = *(const bf16x8*)(sb + b_base + nb * 4096 + xo[ks]);
; #pragma unroll
;       for (int mb = 0; mb < 2; ++mb)
; #pragma unroll
;         for (int nb = 0; nb < 2; ++nb)
;           acc[mb][nb] = __builtin_amdgcn_mfma_f32_32x32x16_bf16(af[mb], bfr[nb], acc[mb][nb], 0, 0, 0);
;     }
;     WAIT_V0();
;     __syncthreads();
;   }
	ds_read_b128 v[0:3], v79
	v_lshlrev_b32_e32 v4, 7, v12
	v_and_b32_e32 v116, 0x2f80, v4
	v_or_b32_e32 v81, v116, v6
	ds_read_b128 v[4:7], v81 offset:16384
	ds_read_b128 v[8:11], v81 offset:20480
	s_waitcnt lgkmcnt(0)
	v_mfma_f32_32x32x16_bf16 v[48:63], v[0:3], v[4:7], 0
	s_mov_b32 m0, s84
	s_mov_b32 s3, 0xfffffc0
	v_mfma_f32_32x32x16_bf16 v[32:47], v[0:3], v[8:11], 0
	ds_read_b128 v[0:3], v79 offset:4096
	s_waitcnt lgkmcnt(0)
	v_mfma_f32_32x32x16_bf16 v[16:31], v[0:3], v[4:7], 0
	v_bitop3_b32 v4, v117, v86, 2 bitop3:0x36
	v_lshlrev_b32_e32 v82, 4, v4
	v_or_b32_e32 v80, v87, v82
	ds_read_b128 v[104:107], v80
	v_or_b32_e32 v83, v116, v82
	ds_read_b128 v[108:111], v83 offset:16384
	ds_read_b128 v[112:115], v83 offset:20480
	s_waitcnt lgkmcnt(0)
	v_mfma_f32_32x32x16_bf16 v[48:63], v[104:107], v[108:111], v[48:63]
	v_bitop3_b32 v82, v117, v86, 4 bitop3:0x36
	v_lshlrev_b32_e32 v85, 4, v82
	v_or_b32_e32 v82, v87, v85
	v_or_b32_e32 v85, v116, v85
	v_bitop3_b32 v86, v117, v86, 6 bitop3:0x36
	v_mfma_f32_32x32x16_bf16 v[32:47], v[104:107], v[112:115], v[32:47]
	ds_read_b128 v[104:107], v80 offset:4096
	v_mfma_f32_32x32x16_bf16 v[0:15], v[0:3], v[8:11], 0
	s_waitcnt lgkmcnt(0)
	v_mfma_f32_32x32x16_bf16 v[16:31], v[104:107], v[108:111], v[16:31]
	ds_read_b128 v[108:111], v85 offset:16384
	v_mfma_f32_32x32x16_bf16 v[0:15], v[104:107], v[112:115], v[0:15]
	ds_read_b128 v[104:107], v82
	ds_read_b128 v[112:115], v85 offset:20480
	s_waitcnt lgkmcnt(0)
	v_mfma_f32_32x32x16_bf16 v[48:63], v[104:107], v[108:111], v[48:63]
	v_mfma_f32_32x32x16_bf16 v[32:47], v[104:107], v[112:115], v[32:47]
	ds_read_b128 v[104:107], v82 offset:4096
	s_waitcnt lgkmcnt(0)
	v_mfma_f32_32x32x16_bf16 v[16:31], v[104:107], v[108:111], v[16:31]
	v_lshlrev_b32_e32 v108, 4, v86
	v_or_b32_e32 v86, v87, v108
	v_or_b32_e32 v87, v116, v108
	ds_read_b128 v[108:111], v87 offset:16384
	v_mfma_f32_32x32x16_bf16 v[0:15], v[104:107], v[112:115], v[0:15]
	ds_read_b128 v[104:107], v86
	ds_read_b128 v[112:115], v87 offset:20480
	s_waitcnt lgkmcnt(0)
	v_mfma_f32_32x32x16_bf16 v[48:63], v[104:107], v[108:111], v[48:63]
	v_mfma_f32_32x32x16_bf16 v[32:47], v[104:107], v[112:115], v[32:47]
	ds_read_b128 v[104:107], v86 offset:4096
	s_waitcnt vmcnt(0)
	s_waitcnt vmcnt(0) lgkmcnt(0)
	s_barrier
	v_mfma_f32_32x32x16_bf16 v[16:31], v[104:107], v[108:111], v[16:31]
	v_mfma_f32_32x32x16_bf16 v[0:15], v[104:107], v[112:115], v[0:15]
	ds_read_b128 v[104:107], v79 offset:32768
	ds_read_b128 v[108:111], v81 offset:49152
	ds_read_b128 v[112:115], v81 offset:53248
	v_lshl_add_u64 v[140:141], v[64:65], 0, s[4:5]
	global_load_lds_dwordx4 v[140:141], off
	s_mov_b32 m0, s85
	v_lshl_add_u64 v[142:143], v[66:67], 0, s[4:5]
	global_load_lds_dwordx4 v76, s[16:17]
	s_mov_b32 m0, s86
	s_nop 0
	global_load_lds_dwordx4 v[142:143], off
	s_mov_b32 m0, s87
	v_lshl_add_u64 v[140:141], v[68:69], 0, s[4:5]
	global_load_lds_dwordx4 v77, s[16:17]
	s_mov_b32 m0, s88
	s_nop 0
	global_load_lds_dwordx4 v[140:141], off
	s_mov_b32 m0, s89
	v_lshl_add_u64 v[142:143], v[70:71], 0, s[4:5]
	global_load_lds_dwordx4 v78, s[16:17]
	s_mov_b32 m0, s90
	s_mov_b64 s[4:5], 0x180
	global_load_lds_dwordx4 v[142:143], off
	s_mov_b32 m0, s91
	s_nop 0
	global_load_lds_dwordx4 v84, s[16:17]
	s_waitcnt lgkmcnt(0)
	v_mfma_f32_32x32x16_bf16 v[48:63], v[104:107], v[108:111], v[48:63]
	s_mov_b32 m0, s18
	v_mfma_f32_32x32x16_bf16 v[32:47], v[104:107], v[112:115], v[32:47]
	ds_read_b128 v[104:107], v79 offset:36864
	s_waitcnt lgkmcnt(0)
	v_mfma_f32_32x32x16_bf16 v[16:31], v[104:107], v[108:111], v[16:31]
	v_mfma_f32_32x32x16_bf16 v[0:15], v[104:107], v[112:115], v[0:15]
	ds_read_b128 v[104:107], v80 offset:32768
	ds_read_b128 v[108:111], v83 offset:49152
	ds_read_b128 v[112:115], v83 offset:53248
	s_waitcnt lgkmcnt(0)
	v_mfma_f32_32x32x16_bf16 v[48:63], v[104:107], v[108:111], v[48:63]
	v_mfma_f32_32x32x16_bf16 v[32:47], v[104:107], v[112:115], v[32:47]
	ds_read_b128 v[104:107], v80 offset:36864
	s_waitcnt lgkmcnt(0)
	v_mfma_f32_32x32x16_bf16 v[16:31], v[104:107], v[108:111], v[16:31]
	v_mfma_f32_32x32x16_bf16 v[0:15], v[104:107], v[112:115], v[0:15]
	ds_read_b128 v[104:107], v82 offset:32768
	ds_read_b128 v[108:111], v85 offset:49152
	ds_read_b128 v[112:115], v85 offset:53248
	s_waitcnt lgkmcnt(0)
	v_mfma_f32_32x32x16_bf16 v[48:63], v[104:107], v[108:111], v[48:63]
	v_mfma_f32_32x32x16_bf16 v[32:47], v[104:107], v[112:115], v[32:47]
	ds_read_b128 v[104:107], v82 offset:36864
	s_waitcnt lgkmcnt(0)
	v_mfma_f32_32x32x16_bf16 v[16:31], v[104:107], v[108:111], v[16:31]
	v_mfma_f32_32x32x16_bf16 v[0:15], v[104:107], v[112:115], v[0:15]
	ds_read_b128 v[104:107], v86 offset:32768
	ds_read_b128 v[108:111], v87 offset:49152
	ds_read_b128 v[112:115], v87 offset:53248
	s_waitcnt lgkmcnt(0)
	v_mfma_f32_32x32x16_bf16 v[48:63], v[104:107], v[108:111], v[48:63]
	v_mfma_f32_32x32x16_bf16 v[32:47], v[104:107], v[112:115], v[32:47]
	ds_read_b128 v[104:107], v86 offset:36864
	s_waitcnt vmcnt(0)
	s_waitcnt vmcnt(0) lgkmcnt(0)
	s_barrier
; #define WAIT_V0() asm volatile("s_waitcnt vmcnt(0)" ::: "memory")
; DI void gemm_core(char* smem, int nk, const char* Ab, const char* Bb, const unsigned (&aoff)[4], const unsigned (&boff)[4],
;                   f32x16 (&acc)[2][2]) {
;     ...
;   auto stage = [&](int buf, int kt) __attribute__((always_inline)) {
;     const char* ak = Ab + kt * 128;
;     const char* bk = Bb + kt * 128;
;     char* sa = smem + buf * STAGE_B + w * 4096;
; #pragma unroll
;     for (int i = 0; i < 4; ++i) {
;       __builtin_amdgcn_global_load_lds((const unsigned*)(ak + aoff[i]), (unsigned*)(sa + i * 1024), 16, 0, 0);
;       __builtin_amdgcn_global_load_lds((const unsigned*)(bk + boff[i]), (unsigned*)(sa + 16384 + i * 1024), 16, 0, 0);
;     }
;   };
;     ...
;   for (int kt = 0; kt < nk; ++kt) {
;     const int cur = kt & 1;
;     if (kt + 1 < nk) stage(cur ^ 1, kt + 1);
;     const char* sb = smem + cur * STAGE_B;
; #pragma unroll
;     for (int ks = 0; ks < 4; ++ks) {
;       bf16x8 af[2], bfr[2];
; #pragma unroll
;       for (int mb = 0; mb < 2; ++mb) af[mb] = *(const bf16x8*)(sb + a_base + mb * 4096 + xo[ks]);
; #pragma unroll
;       for (int nb = 0; nb < 2; ++nb) bfr[nb] = *(const bf16x8*)(sb + b_base + nb * 4096 + xo[ks]);
; #pragma unroll
;       for (int mb = 0; mb < 2; ++mb)
; #pragma unroll
;         for (int nb = 0; nb < 2; ++nb)
;           acc[mb][nb] = __builtin_amdgcn_mfma_f32_32x32x16_bf16(af[mb], bfr[nb], acc[mb][nb], 0, 0, 0);
;     }
;     WAIT_V0();
;     __syncthreads();
;   }
	v_mfma_f32_32x32x16_bf16 v[16:31], v[104:107], v[108:111], v[16:31]
	v_mfma_f32_32x32x16_bf16 v[0:15], v[104:107], v[112:115], v[0:15]
	ds_read_b128 v[104:107], v79
	ds_read_b128 v[108:111], v81 offset:16384
	ds_read_b128 v[112:115], v81 offset:20480
	v_lshl_add_u64 v[140:141], v[64:65], 0, s[4:5]
	global_load_lds_dwordx4 v[140:141], off
	s_mov_b32 m0, s19
	v_lshl_add_u64 v[142:143], v[66:67], 0, s[4:5]
	global_load_lds_dwordx4 v76, s[42:43]
	s_mov_b32 m0, s22
	s_nop 0
	global_load_lds_dwordx4 v[142:143], off
	s_mov_b32 m0, s23
	v_lshl_add_u64 v[140:141], v[68:69], 0, s[4:5]
	global_load_lds_dwordx4 v77, s[42:43]
	s_mov_b32 m0, s29
	s_nop 0
	global_load_lds_dwordx4 v[140:141], off
	s_mov_b32 m0, s69
	v_lshl_add_u64 v[142:143], v[70:71], 0, s[4:5]
	global_load_lds_dwordx4 v78, s[42:43]
	s_mov_b32 m0, s70
	s_mov_b64 s[4:5], 0x280
	global_load_lds_dwordx4 v[142:143], off
	s_mov_b32 m0, s71
	s_nop 0
	global_load_lds_dwordx4 v84, s[42:43]
	s_waitcnt lgkmcnt(0)
	v_mfma_f32_32x32x16_bf16 v[48:63], v[104:107], v[108:111], v[48:63]
	s_mov_b32 m0, s84
	v_mfma_f32_32x32x16_bf16 v[32:47], v[104:107], v[112:115], v[32:47]
	ds_read_b128 v[104:107], v79 offset:4096
	s_waitcnt lgkmcnt(0)
	v_mfma_f32_32x32x16_bf16 v[16:31], v[104:107], v[108:111], v[16:31]
	v_mfma_f32_32x32x16_bf16 v[0:15], v[104:107], v[112:115], v[0:15]
	ds_read_b128 v[104:107], v80
	ds_read_b128 v[108:111], v83 offset:16384
	ds_read_b128 v[112:115], v83 offset:20480
	s_waitcnt lgkmcnt(0)
	v_mfma_f32_32x32x16_bf16 v[48:63], v[104:107], v[108:111], v[48:63]
	v_mfma_f32_32x32x16_bf16 v[32:47], v[104:107], v[112:115], v[32:47]
	ds_read_b128 v[104:107], v80 offset:4096
	s_waitcnt lgkmcnt(0)
	v_mfma_f32_32x32x16_bf16 v[16:31], v[104:107], v[108:111], v[16:31]
	v_mfma_f32_32x32x16_bf16 v[0:15], v[104:107], v[112:115], v[0:15]
	ds_read_b128 v[104:107], v82
	ds_read_b128 v[108:111], v85 offset:16384
	ds_read_b128 v[112:115], v85 offset:20480
	s_waitcnt lgkmcnt(0)
	v_mfma_f32_32x32x16_bf16 v[48:63], v[104:107], v[108:111], v[48:63]
	v_mfma_f32_32x32x16_bf16 v[32:47], v[104:107], v[112:115], v[32:47]
	ds_read_b128 v[104:107], v82 offset:4096
	s_waitcnt lgkmcnt(0)
	v_mfma_f32_32x32x16_bf16 v[16:31], v[104:107], v[108:111], v[16:31]
	v_mfma_f32_32x32x16_bf16 v[0:15], v[104:107], v[112:115], v[0:15]
	ds_read_b128 v[104:107], v86
	ds_read_b128 v[108:111], v87 offset:16384
	ds_read_b128 v[112:115], v87 offset:20480
	s_waitcnt lgkmcnt(0)
	v_mfma_f32_32x32x16_bf16 v[48:63], v[104:107], v[108:111], v[48:63]
	v_mfma_f32_32x32x16_bf16 v[32:47], v[104:107], v[112:115], v[32:47]
	ds_read_b128 v[104:107], v86 offset:4096
	s_waitcnt vmcnt(0)
	s_waitcnt vmcnt(0) lgkmcnt(0)
	s_barrier
	v_mfma_f32_32x32x16_bf16 v[16:31], v[104:107], v[108:111], v[16:31]
	v_mfma_f32_32x32x16_bf16 v[0:15], v[104:107], v[112:115], v[0:15]
	ds_read_b128 v[104:107], v79 offset:32768
	ds_read_b128 v[108:111], v81 offset:49152
	ds_read_b128 v[112:115], v81 offset:53248
	v_lshl_add_u64 v[140:141], v[64:65], 0, s[30:31]
	global_load_lds_dwordx4 v[140:141], off
	s_mov_b32 m0, s85
	v_lshl_add_u64 v[142:143], v[66:67], 0, s[30:31]
	global_load_lds_dwordx4 v76, s[44:45]
	s_mov_b32 m0, s86
	s_nop 0
	global_load_lds_dwordx4 v[142:143], off
	s_mov_b32 m0, s87
	v_lshl_add_u64 v[140:141], v[68:69], 0, s[30:31]
	global_load_lds_dwordx4 v77, s[44:45]
	s_mov_b32 m0, s88
	s_nop 0
	global_load_lds_dwordx4 v[140:141], off
	s_mov_b32 m0, s89
	v_lshl_add_u64 v[142:143], v[70:71], 0, s[30:31]
	global_load_lds_dwordx4 v78, s[44:45]
	s_mov_b32 m0, s90
	s_nop 0
	global_load_lds_dwordx4 v[142:143], off
	s_mov_b32 m0, s91
	s_nop 0
	global_load_lds_dwordx4 v84, s[44:45]
	s_waitcnt lgkmcnt(0)
	v_mfma_f32_32x32x16_bf16 v[48:63], v[104:107], v[108:111], v[48:63]
	s_mov_b32 m0, s18
	v_mfma_f32_32x32x16_bf16 v[32:47], v[104:107], v[112:115], v[32:47]
	ds_read_b128 v[104:107], v79 offset:36864
	s_waitcnt lgkmcnt(0)
	v_mfma_f32_32x32x16_bf16 v[16:31], v[104:107], v[108:111], v[16:31]
	v_mfma_f32_32x32x16_bf16 v[0:15], v[104:107], v[112:115], v[0:15]
	ds_read_b128 v[104:107], v80 offset:32768
	ds_read_b128 v[108:111], v83 offset:49152
	ds_read_b128 v[112:115], v83 offset:53248
	s_waitcnt lgkmcnt(0)
	v_mfma_f32_32x32x16_bf16 v[48:63], v[104:107], v[108:111], v[48:63]
	v_mfma_f32_32x32x16_bf16 v[32:47], v[104:107], v[112:115], v[32:47]
	ds_read_b128 v[104:107], v80 offset:36864
	s_waitcnt lgkmcnt(0)
	v_mfma_f32_32x32x16_bf16 v[16:31], v[104:107], v[108:111], v[16:31]
	v_mfma_f32_32x32x16_bf16 v[0:15], v[104:107], v[112:115], v[0:15]
	ds_read_b128 v[104:107], v82 offset:32768
	ds_read_b128 v[108:111], v85 offset:49152
	ds_read_b128 v[112:115], v85 offset:53248
	s_waitcnt lgkmcnt(0)
	v_mfma_f32_32x32x16_bf16 v[48:63], v[104:107], v[108:111], v[48:63]
	v_mfma_f32_32x32x16_bf16 v[32:47], v[104:107], v[112:115], v[32:47]
	ds_read_b128 v[104:107], v82 offset:36864
	s_waitcnt lgkmcnt(0)
	v_mfma_f32_32x32x16_bf16 v[16:31], v[104:107], v[108:111], v[16:31]
	v_mfma_f32_32x32x16_bf16 v[0:15], v[104:107], v[112:115], v[0:15]
	ds_read_b128 v[104:107], v86 offset:32768
	ds_read_b128 v[108:111], v87 offset:49152
	ds_read_b128 v[112:115], v87 offset:53248
	s_waitcnt lgkmcnt(0)
	v_mfma_f32_32x32x16_bf16 v[48:63], v[104:107], v[108:111], v[48:63]
	v_mfma_f32_32x32x16_bf16 v[32:47], v[104:107], v[112:115], v[32:47]
	ds_read_b128 v[104:107], v86 offset:36864
	s_waitcnt vmcnt(0)
	s_waitcnt vmcnt(0) lgkmcnt(0)
	s_barrier
; #define WAIT_V0() asm volatile("s_waitcnt vmcnt(0)" ::: "memory")
; DI void gemm_core(char* smem, int nk, const char* Ab, const char* Bb, const unsigned (&aoff)[4], const unsigned (&boff)[4],
;                   f32x16 (&acc)[2][2]) {
;     ...
;   auto stage = [&](int buf, int kt) __attribute__((always_inline)) {
;     const char* ak = Ab + kt * 128;
;     const char* bk = Bb + kt * 128;
;     char* sa = smem + buf * STAGE_B + w * 4096;
; #pragma unroll
;     for (int i = 0; i < 4; ++i) {
;       __builtin_amdgcn_global_load_lds((const unsigned*)(ak + aoff[i]), (unsigned*)(sa + i * 1024), 16, 0, 0);
;       __builtin_amdgcn_global_load_lds((const unsigned*)(bk + boff[i]), (unsigned*)(sa + 16384 + i * 1024), 16, 0, 0);
;     }
;   };
;     ...
;   for (int kt = 0; kt < nk; ++kt) {
;     const int cur = kt & 1;
;     if (kt + 1 < nk) stage(cur ^ 1, kt + 1);
;     const char* sb = smem + cur * STAGE_B;
; #pragma unroll
;     for (int ks = 0; ks < 4; ++ks) {
;       bf16x8 af[2], bfr[2];
; #pragma unroll
;       for (int mb = 0; mb < 2; ++mb) af[mb] = *(const bf16x8*)(sb + a_base + mb * 4096 + xo[ks]);
; #pragma unroll
;       for (int nb = 0; nb < 2; ++nb) bfr[nb] = *(const bf16x8*)(sb + b_base + nb * 4096 + xo[ks]);
; #pragma unroll
;       for (int mb = 0; mb < 2; ++mb)
; #pragma unroll
;         for (int nb = 0; nb < 2; ++nb)
;           acc[mb][nb] = __builtin_amdgcn_mfma_f32_32x32x16_bf16(af[mb], bfr[nb], acc[mb][nb], 0, 0, 0);
;     }
;     WAIT_V0();
;     __syncthreads();
;   }
	v_mfma_f32_32x32x16_bf16 v[16:31], v[104:107], v[108:111], v[16:31]
	v_mfma_f32_32x32x16_bf16 v[0:15], v[104:107], v[112:115], v[0:15]
	ds_read_b128 v[104:107], v79
	ds_read_b128 v[108:111], v81 offset:16384
	ds_read_b128 v[112:115], v81 offset:20480
	v_lshl_add_u64 v[140:141], v[64:65], 0, s[4:5]
	global_load_lds_dwordx4 v[140:141], off
	s_mov_b32 m0, s19
	v_lshl_add_u64 v[142:143], v[66:67], 0, s[4:5]
	global_load_lds_dwordx4 v76, s[46:47]
	s_mov_b32 m0, s22
	s_nop 0
	global_load_lds_dwordx4 v[142:143], off
	s_mov_b32 m0, s23
	v_lshl_add_u64 v[140:141], v[68:69], 0, s[4:5]
	global_load_lds_dwordx4 v77, s[46:47]
	s_mov_b32 m0, s29
	s_nop 0
	global_load_lds_dwordx4 v[140:141], off
	s_mov_b32 m0, s69
	v_lshl_add_u64 v[142:143], v[70:71], 0, s[4:5]
	global_load_lds_dwordx4 v78, s[46:47]
	s_mov_b32 m0, s70
	s_mov_b64 s[4:5], 0x300
	global_load_lds_dwordx4 v[142:143], off
	s_mov_b32 m0, s71
	s_nop 0
	global_load_lds_dwordx4 v84, s[46:47]
	s_waitcnt lgkmcnt(0)
	v_mfma_f32_32x32x16_bf16 v[48:63], v[104:107], v[108:111], v[48:63]
	s_mov_b32 m0, s84
	v_mfma_f32_32x32x16_bf16 v[32:47], v[104:107], v[112:115], v[32:47]
	ds_read_b128 v[104:107], v79 offset:4096
	s_waitcnt lgkmcnt(0)
	v_mfma_f32_32x32x16_bf16 v[16:31], v[104:107], v[108:111], v[16:31]
	v_mfma_f32_32x32x16_bf16 v[0:15], v[104:107], v[112:115], v[0:15]
	ds_read_b128 v[104:107], v80
	ds_read_b128 v[108:111], v83 offset:16384
	ds_read_b128 v[112:115], v83 offset:20480
	s_waitcnt lgkmcnt(0)
	v_mfma_f32_32x32x16_bf16 v[48:63], v[104:107], v[108:111], v[48:63]
	v_mfma_f32_32x32x16_bf16 v[32:47], v[104:107], v[112:115], v[32:47]
	ds_read_b128 v[104:107], v80 offset:4096
	s_waitcnt lgkmcnt(0)
	v_mfma_f32_32x32x16_bf16 v[16:31], v[104:107], v[108:111], v[16:31]
	v_mfma_f32_32x32x16_bf16 v[0:15], v[104:107], v[112:115], v[0:15]
	ds_read_b128 v[104:107], v82
	ds_read_b128 v[108:111], v85 offset:16384
	ds_read_b128 v[112:115], v85 offset:20480
	s_waitcnt lgkmcnt(0)
	v_mfma_f32_32x32x16_bf16 v[48:63], v[104:107], v[108:111], v[48:63]
	v_mfma_f32_32x32x16_bf16 v[32:47], v[104:107], v[112:115], v[32:47]
	ds_read_b128 v[104:107], v82 offset:4096
	s_waitcnt lgkmcnt(0)
	v_mfma_f32_32x32x16_bf16 v[16:31], v[104:107], v[108:111], v[16:31]
	v_mfma_f32_32x32x16_bf16 v[0:15], v[104:107], v[112:115], v[0:15]
	ds_read_b128 v[104:107], v86
	ds_read_b128 v[108:111], v87 offset:16384
	ds_read_b128 v[112:115], v87 offset:20480
	s_waitcnt lgkmcnt(0)
	v_mfma_f32_32x32x16_bf16 v[48:63], v[104:107], v[108:111], v[48:63]
	v_mfma_f32_32x32x16_bf16 v[32:47], v[104:107], v[112:115], v[32:47]
	ds_read_b128 v[104:107], v86 offset:4096
	s_waitcnt vmcnt(0)
	s_waitcnt vmcnt(0) lgkmcnt(0)
	s_barrier
	v_mfma_f32_32x32x16_bf16 v[16:31], v[104:107], v[108:111], v[16:31]
	v_mfma_f32_32x32x16_bf16 v[0:15], v[104:107], v[112:115], v[0:15]
	ds_read_b128 v[104:107], v79 offset:32768
	ds_read_b128 v[108:111], v81 offset:49152
	ds_read_b128 v[112:115], v81 offset:53248
	v_lshl_add_u64 v[140:141], v[64:65], 0, s[4:5]
	global_load_lds_dwordx4 v[140:141], off
	s_mov_b32 m0, s85
	v_lshl_add_u64 v[142:143], v[66:67], 0, s[4:5]
	global_load_lds_dwordx4 v76, s[48:49]
	s_mov_b32 m0, s86
	s_nop 0
	global_load_lds_dwordx4 v[142:143], off
	s_mov_b32 m0, s87
	v_lshl_add_u64 v[140:141], v[68:69], 0, s[4:5]
	global_load_lds_dwordx4 v77, s[48:49]
	s_mov_b32 m0, s88
	s_nop 0
	global_load_lds_dwordx4 v[140:141], off
	s_mov_b32 m0, s89
	v_lshl_add_u64 v[142:143], v[70:71], 0, s[4:5]
	global_load_lds_dwordx4 v78, s[48:49]
	s_mov_b32 m0, s90
	s_mov_b64 s[4:5], 0x380
	global_load_lds_dwordx4 v[142:143], off
	s_mov_b32 m0, s91
	s_nop 0
	global_load_lds_dwordx4 v84, s[48:49]
	s_waitcnt lgkmcnt(0)
	v_mfma_f32_32x32x16_bf16 v[48:63], v[104:107], v[108:111], v[48:63]
	s_mov_b32 m0, s18
	v_mfma_f32_32x32x16_bf16 v[32:47], v[104:107], v[112:115], v[32:47]
	ds_read_b128 v[104:107], v79 offset:36864
	s_waitcnt lgkmcnt(0)
	v_mfma_f32_32x32x16_bf16 v[16:31], v[104:107], v[108:111], v[16:31]
	v_mfma_f32_32x32x16_bf16 v[0:15], v[104:107], v[112:115], v[0:15]
	ds_read_b128 v[104:107], v80 offset:32768
	ds_read_b128 v[108:111], v83 offset:49152
	ds_read_b128 v[112:115], v83 offset:53248
	s_waitcnt lgkmcnt(0)
	v_mfma_f32_32x32x16_bf16 v[48:63], v[104:107], v[108:111], v[48:63]
	v_mfma_f32_32x32x16_bf16 v[32:47], v[104:107], v[112:115], v[32:47]
	ds_read_b128 v[104:107], v80 offset:36864
	s_waitcnt lgkmcnt(0)
	v_mfma_f32_32x32x16_bf16 v[16:31], v[104:107], v[108:111], v[16:31]
	v_mfma_f32_32x32x16_bf16 v[0:15], v[104:107], v[112:115], v[0:15]
	ds_read_b128 v[104:107], v82 offset:32768
	ds_read_b128 v[108:111], v85 offset:49152
	ds_read_b128 v[112:115], v85 offset:53248
	s_waitcnt lgkmcnt(0)
	v_mfma_f32_32x32x16_bf16 v[48:63], v[104:107], v[108:111], v[48:63]
	v_mfma_f32_32x32x16_bf16 v[32:47], v[104:107], v[112:115], v[32:47]
	ds_read_b128 v[104:107], v82 offset:36864
	s_waitcnt lgkmcnt(0)
	v_mfma_f32_32x32x16_bf16 v[16:31], v[104:107], v[108:111], v[16:31]
	v_mfma_f32_32x32x16_bf16 v[0:15], v[104:107], v[112:115], v[0:15]
	ds_read_b128 v[104:107], v86 offset:32768
	ds_read_b128 v[108:111], v87 offset:49152
	ds_read_b128 v[112:115], v87 offset:53248
	s_waitcnt lgkmcnt(0)
	v_mfma_f32_32x32x16_bf16 v[48:63], v[104:107], v[108:111], v[48:63]
	v_mfma_f32_32x32x16_bf16 v[32:47], v[104:107], v[112:115], v[32:47]
	ds_read_b128 v[104:107], v86 offset:36864
	s_waitcnt vmcnt(0)
	s_waitcnt vmcnt(0) lgkmcnt(0)
	s_barrier
; #define WAIT_V0() asm volatile("s_waitcnt vmcnt(0)" ::: "memory")
; DI void gemm_core(char* smem, int nk, const char* Ab, const char* Bb, const unsigned (&aoff)[4], const unsigned (&boff)[4],
;                   f32x16 (&acc)[2][2]) {
;     ...
;   auto stage = [&](int buf, int kt) __attribute__((always_inline)) {
;     const char* ak = Ab + kt * 128;
;     const char* bk = Bb + kt * 128;
;     char* sa = smem + buf * STAGE_B + w * 4096;
; #pragma unroll
;     for (int i = 0; i < 4; ++i) {
;       __builtin_amdgcn_global_load_lds((const unsigned*)(ak + aoff[i]), (unsigned*)(sa + i * 1024), 16, 0, 0);
;       __builtin_amdgcn_global_load_lds((const unsigned*)(bk + boff[i]), (unsigned*)(sa + 16384 + i * 1024), 16, 0, 0);
;     }
;   };
;     ...
;   for (int kt = 0; kt < nk; ++kt) {
;     const int cur = kt & 1;
;     if (kt + 1 < nk) stage(cur ^ 1, kt + 1);
;     const char* sb = smem + cur * STAGE_B;
; #pragma unroll
;     for (int ks = 0; ks < 4; ++ks) {
;       bf16x8 af[2], bfr[2];
; #pragma unroll
;       for (int mb = 0; mb < 2; ++mb) af[mb] = *(const bf16x8*)(sb + a_base + mb * 4096 + xo[ks]);
; #pragma unroll
;       for (int nb = 0; nb < 2; ++nb) bfr[nb] = *(const bf16x8*)(sb + b_base + nb * 4096 + xo[ks]);
; #pragma unroll
;       for (int mb = 0; mb < 2; ++mb)
; #pragma unroll
;         for (int nb = 0; nb < 2; ++nb)
;           acc[mb][nb] = __builtin_amdgcn_mfma_f32_32x32x16_bf16(af[mb], bfr[nb], acc[mb][nb], 0, 0, 0);
;     }
;     WAIT_V0();
;     __syncthreads();
;   }
	v_mfma_f32_32x32x16_bf16 v[16:31], v[104:107], v[108:111], v[16:31]
	v_mfma_f32_32x32x16_bf16 v[0:15], v[104:107], v[112:115], v[0:15]
	ds_read_b128 v[104:107], v79
	ds_read_b128 v[108:111], v81 offset:16384
	ds_read_b128 v[112:115], v81 offset:20480
	v_lshl_add_u64 v[140:141], v[64:65], 0, s[4:5]
	global_load_lds_dwordx4 v[140:141], off
	s_mov_b32 m0, s19
	v_lshl_add_u64 v[142:143], v[66:67], 0, s[4:5]
	global_load_lds_dwordx4 v76, s[50:51]
	s_mov_b32 m0, s22
	s_nop 0
	global_load_lds_dwordx4 v[142:143], off
	s_mov_b32 m0, s23
	v_lshl_add_u64 v[140:141], v[68:69], 0, s[4:5]
	global_load_lds_dwordx4 v77, s[50:51]
	s_mov_b32 m0, s29
	s_nop 0
	global_load_lds_dwordx4 v[140:141], off
	s_mov_b32 m0, s69
	v_lshl_add_u64 v[142:143], v[70:71], 0, s[4:5]
	global_load_lds_dwordx4 v78, s[50:51]
	s_mov_b32 m0, s70
	s_mov_b64 s[4:5], 0x400
	global_load_lds_dwordx4 v[142:143], off
	s_mov_b32 m0, s71
	s_nop 0
	global_load_lds_dwordx4 v84, s[50:51]
	s_waitcnt lgkmcnt(0)
	v_mfma_f32_32x32x16_bf16 v[48:63], v[104:107], v[108:111], v[48:63]
	s_mov_b32 m0, s84
	v_readfirstlane_b32 s84, v89
	v_mfma_f32_32x32x16_bf16 v[32:47], v[104:107], v[112:115], v[32:47]
	ds_read_b128 v[104:107], v79 offset:4096
	s_waitcnt lgkmcnt(0)
	v_mfma_f32_32x32x16_bf16 v[16:31], v[104:107], v[108:111], v[16:31]
	v_mfma_f32_32x32x16_bf16 v[0:15], v[104:107], v[112:115], v[0:15]
	ds_read_b128 v[104:107], v80
	ds_read_b128 v[108:111], v83 offset:16384
	ds_read_b128 v[112:115], v83 offset:20480
	s_waitcnt lgkmcnt(0)
	v_mfma_f32_32x32x16_bf16 v[48:63], v[104:107], v[108:111], v[48:63]
	v_mfma_f32_32x32x16_bf16 v[32:47], v[104:107], v[112:115], v[32:47]
	ds_read_b128 v[104:107], v80 offset:4096
	s_waitcnt lgkmcnt(0)
	v_mfma_f32_32x32x16_bf16 v[16:31], v[104:107], v[108:111], v[16:31]
	v_mfma_f32_32x32x16_bf16 v[0:15], v[104:107], v[112:115], v[0:15]
	ds_read_b128 v[104:107], v82
	ds_read_b128 v[108:111], v85 offset:16384
	ds_read_b128 v[112:115], v85 offset:20480
	s_waitcnt lgkmcnt(0)
	v_mfma_f32_32x32x16_bf16 v[48:63], v[104:107], v[108:111], v[48:63]
	v_mfma_f32_32x32x16_bf16 v[32:47], v[104:107], v[112:115], v[32:47]
	ds_read_b128 v[104:107], v82 offset:4096
	s_waitcnt lgkmcnt(0)
	v_mfma_f32_32x32x16_bf16 v[16:31], v[104:107], v[108:111], v[16:31]
	v_mfma_f32_32x32x16_bf16 v[0:15], v[104:107], v[112:115], v[0:15]
	ds_read_b128 v[104:107], v86
	ds_read_b128 v[108:111], v87 offset:16384
	ds_read_b128 v[112:115], v87 offset:20480
	s_waitcnt lgkmcnt(0)
	v_mfma_f32_32x32x16_bf16 v[48:63], v[104:107], v[108:111], v[48:63]
	v_mfma_f32_32x32x16_bf16 v[32:47], v[104:107], v[112:115], v[32:47]
	ds_read_b128 v[104:107], v86 offset:4096
	s_waitcnt vmcnt(0)
	s_waitcnt vmcnt(0) lgkmcnt(0)
	s_barrier
	v_mfma_f32_32x32x16_bf16 v[16:31], v[104:107], v[108:111], v[16:31]
	v_mfma_f32_32x32x16_bf16 v[0:15], v[104:107], v[112:115], v[0:15]
	ds_read_b128 v[104:107], v79 offset:32768
	ds_read_b128 v[108:111], v81 offset:49152
	ds_read_b128 v[112:115], v81 offset:53248
	v_lshl_add_u64 v[140:141], v[64:65], 0, s[4:5]
	global_load_lds_dwordx4 v[140:141], off
	s_mov_b32 m0, s85
	v_lshl_add_u64 v[142:143], v[66:67], 0, s[4:5]
	global_load_lds_dwordx4 v76, s[52:53]
	s_mov_b32 m0, s86
	v_readfirstlane_b32 s85, v88
	global_load_lds_dwordx4 v[142:143], off
	s_mov_b32 m0, s87
	v_lshl_add_u64 v[140:141], v[68:69], 0, s[4:5]
	global_load_lds_dwordx4 v77, s[52:53]
	s_mov_b32 m0, s88
	v_readfirstlane_b32 s86, v90
	global_load_lds_dwordx4 v[140:141], off
	s_mov_b32 m0, s89
	v_lshl_add_u64 v[142:143], v[70:71], 0, s[4:5]
	global_load_lds_dwordx4 v78, s[52:53]
	s_mov_b32 m0, s90
	s_mov_b64 s[4:5], 0x480
	global_load_lds_dwordx4 v[142:143], off
	s_mov_b32 m0, s91
	v_readfirstlane_b32 s87, v91
	global_load_lds_dwordx4 v84, s[52:53]
	s_waitcnt lgkmcnt(0)
	v_mfma_f32_32x32x16_bf16 v[48:63], v[104:107], v[108:111], v[48:63]
	s_mov_b32 m0, s18
	v_readfirstlane_b32 s18, v97
	v_readfirstlane_b32 s88, v92
	v_readfirstlane_b32 s89, v93
	v_readfirstlane_b32 s90, v94
	v_readfirstlane_b32 s91, v95
	v_mfma_f32_32x32x16_bf16 v[32:47], v[104:107], v[112:115], v[32:47]
	ds_read_b128 v[104:107], v79 offset:36864
	s_waitcnt lgkmcnt(0)
	v_mfma_f32_32x32x16_bf16 v[16:31], v[104:107], v[108:111], v[16:31]
	v_mfma_f32_32x32x16_bf16 v[0:15], v[104:107], v[112:115], v[0:15]
	ds_read_b128 v[104:107], v80 offset:32768
	ds_read_b128 v[108:111], v83 offset:49152
	ds_read_b128 v[112:115], v83 offset:53248
	s_waitcnt lgkmcnt(0)
	v_mfma_f32_32x32x16_bf16 v[48:63], v[104:107], v[108:111], v[48:63]
	v_mfma_f32_32x32x16_bf16 v[32:47], v[104:107], v[112:115], v[32:47]
	ds_read_b128 v[104:107], v80 offset:36864
	s_waitcnt lgkmcnt(0)
	v_mfma_f32_32x32x16_bf16 v[16:31], v[104:107], v[108:111], v[16:31]
	v_mfma_f32_32x32x16_bf16 v[0:15], v[104:107], v[112:115], v[0:15]
	ds_read_b128 v[104:107], v82 offset:32768
	ds_read_b128 v[108:111], v85 offset:49152
	ds_read_b128 v[112:115], v85 offset:53248
	s_waitcnt lgkmcnt(0)
	v_mfma_f32_32x32x16_bf16 v[48:63], v[104:107], v[108:111], v[48:63]
	v_mfma_f32_32x32x16_bf16 v[32:47], v[104:107], v[112:115], v[32:47]
	ds_read_b128 v[104:107], v82 offset:36864
	s_waitcnt lgkmcnt(0)
	v_mfma_f32_32x32x16_bf16 v[16:31], v[104:107], v[108:111], v[16:31]
	v_mfma_f32_32x32x16_bf16 v[0:15], v[104:107], v[112:115], v[0:15]
	ds_read_b128 v[104:107], v86 offset:32768
	ds_read_b128 v[108:111], v87 offset:49152
	ds_read_b128 v[112:115], v87 offset:53248
	s_waitcnt lgkmcnt(0)
	v_mfma_f32_32x32x16_bf16 v[48:63], v[104:107], v[108:111], v[48:63]
	v_mfma_f32_32x32x16_bf16 v[32:47], v[104:107], v[112:115], v[32:47]
	ds_read_b128 v[104:107], v86 offset:36864
	s_waitcnt vmcnt(0)
	s_waitcnt vmcnt(0) lgkmcnt(0)
	s_barrier
; #define WAIT_V0() asm volatile("s_waitcnt vmcnt(0)" ::: "memory")
; DI void gemm_core(char* smem, int nk, const char* Ab, const char* Bb, const unsigned (&aoff)[4], const unsigned (&boff)[4],
;                   f32x16 (&acc)[2][2]) {
;     ...
;   auto stage = [&](int buf, int kt) __attribute__((always_inline)) {
;     const char* ak = Ab + kt * 128;
;     const char* bk = Bb + kt * 128;
;     char* sa = smem + buf * STAGE_B + w * 4096;
; #pragma unroll
;     for (int i = 0; i < 4; ++i) {
;       __builtin_amdgcn_global_load_lds((const unsigned*)(ak + aoff[i]), (unsigned*)(sa + i * 1024), 16, 0, 0);
;       __builtin_amdgcn_global_load_lds((const unsigned*)(bk + boff[i]), (unsigned*)(sa + 16384 + i * 1024), 16, 0, 0);
;     }
;   };
;     ...
;   for (int kt = 0; kt < nk; ++kt) {
;     const int cur = kt & 1;
;     if (kt + 1 < nk) stage(cur ^ 1, kt + 1);
;     const char* sb = smem + cur * STAGE_B;
; #pragma unroll
;     for (int ks = 0; ks < 4; ++ks) {
;       bf16x8 af[2], bfr[2];
; #pragma unroll
;       for (int mb = 0; mb < 2; ++mb) af[mb] = *(const bf16x8*)(sb + a_base + mb * 4096 + xo[ks]);
; #pragma unroll
;       for (int nb = 0; nb < 2; ++nb) bfr[nb] = *(const bf16x8*)(sb + b_base + nb * 4096 + xo[ks]);
; #pragma unroll
;       for (int mb = 0; mb < 2; ++mb)
; #pragma unroll
;         for (int nb = 0; nb < 2; ++nb)
;           acc[mb][nb] = __builtin_amdgcn_mfma_f32_32x32x16_bf16(af[mb], bfr[nb], acc[mb][nb], 0, 0, 0);
;     }
;     WAIT_V0();
;     __syncthreads();
;   }
	v_mfma_f32_32x32x16_bf16 v[16:31], v[104:107], v[108:111], v[16:31]
	v_mfma_f32_32x32x16_bf16 v[0:15], v[104:107], v[112:115], v[0:15]
	v_lshl_add_u64 v[104:105], v[64:65], 0, s[4:5]
	global_load_lds_dwordx4 v[104:105], off
	s_mov_b32 m0, s19
	v_lshl_add_u64 v[104:105], v[66:67], 0, s[4:5]
	global_load_lds_dwordx4 v76, s[54:55]
	s_mov_b32 m0, s22
	v_readfirstlane_b32 s19, v96
	global_load_lds_dwordx4 v[104:105], off
	s_mov_b32 m0, s23
	v_lshl_add_u64 v[104:105], v[68:69], 0, s[4:5]
	global_load_lds_dwordx4 v77, s[54:55]
	s_mov_b32 m0, s29
	v_readfirstlane_b32 s22, v98
	global_load_lds_dwordx4 v[104:105], off
	s_mov_b32 m0, s69
	v_lshl_add_u64 v[104:105], v[70:71], 0, s[4:5]
	global_load_lds_dwordx4 v78, s[54:55]
	s_mov_b32 m0, s70
	s_mov_b64 s[4:5], 0x500
	global_load_lds_dwordx4 v[104:105], off
	s_mov_b32 m0, s71
	v_lshl_add_u64 v[96:97], v[66:67], 0, s[4:5]
	global_load_lds_dwordx4 v84, s[54:55]
	ds_read_b128 v[104:107], v79
	ds_read_b128 v[108:111], v81 offset:16384
	ds_read_b128 v[112:115], v81 offset:20480
	s_waitcnt lgkmcnt(0)
	v_mfma_f32_32x32x16_bf16 v[48:63], v[104:107], v[108:111], v[48:63]
	s_mov_b32 m0, s18
	v_readfirstlane_b32 s23, v99
	v_readfirstlane_b32 s29, v100
	v_readfirstlane_b32 s69, v101
	v_readfirstlane_b32 s70, v102
	v_readfirstlane_b32 s71, v103
	v_mfma_f32_32x32x16_bf16 v[32:47], v[104:107], v[112:115], v[32:47]
	ds_read_b128 v[104:107], v79 offset:4096
	s_waitcnt lgkmcnt(0)
	v_mfma_f32_32x32x16_bf16 v[16:31], v[104:107], v[108:111], v[16:31]
	v_mfma_f32_32x32x16_bf16 v[0:15], v[104:107], v[112:115], v[0:15]
	ds_read_b128 v[104:107], v80
	ds_read_b128 v[108:111], v83 offset:16384
	ds_read_b128 v[112:115], v83 offset:20480
	s_waitcnt lgkmcnt(0)
	v_mfma_f32_32x32x16_bf16 v[48:63], v[104:107], v[108:111], v[48:63]
	v_mfma_f32_32x32x16_bf16 v[32:47], v[104:107], v[112:115], v[32:47]
	ds_read_b128 v[104:107], v80 offset:4096
	s_waitcnt lgkmcnt(0)
	v_mfma_f32_32x32x16_bf16 v[16:31], v[104:107], v[108:111], v[16:31]
	v_mfma_f32_32x32x16_bf16 v[0:15], v[104:107], v[112:115], v[0:15]
	ds_read_b128 v[104:107], v82
	ds_read_b128 v[108:111], v85 offset:16384
	ds_read_b128 v[112:115], v85 offset:20480
	s_waitcnt lgkmcnt(0)
	v_mfma_f32_32x32x16_bf16 v[48:63], v[104:107], v[108:111], v[48:63]
	v_mfma_f32_32x32x16_bf16 v[32:47], v[104:107], v[112:115], v[32:47]
	ds_read_b128 v[104:107], v82 offset:4096
	s_waitcnt lgkmcnt(0)
	v_mfma_f32_32x32x16_bf16 v[16:31], v[104:107], v[108:111], v[16:31]
	v_mfma_f32_32x32x16_bf16 v[0:15], v[104:107], v[112:115], v[0:15]
	ds_read_b128 v[104:107], v86
	ds_read_b128 v[108:111], v87 offset:16384
	ds_read_b128 v[112:115], v87 offset:20480
	s_waitcnt lgkmcnt(0)
	v_mfma_f32_32x32x16_bf16 v[48:63], v[104:107], v[108:111], v[48:63]
	v_mfma_f32_32x32x16_bf16 v[32:47], v[104:107], v[112:115], v[32:47]
	ds_read_b128 v[104:107], v86 offset:4096
	s_waitcnt vmcnt(0)
	s_waitcnt vmcnt(0) lgkmcnt(0)
	s_barrier
	v_mfma_f32_32x32x16_bf16 v[16:31], v[104:107], v[108:111], v[16:31]
	v_mfma_f32_32x32x16_bf16 v[0:15], v[104:107], v[112:115], v[0:15]
	v_lshl_add_u64 v[104:105], v[64:65], 0, s[4:5]
	global_load_lds_dwordx4 v[104:105], off
	s_mov_b32 m0, s19
	s_nop 0
	global_load_lds_dwordx4 v76, s[56:57]
	s_mov_b32 m0, s22
	s_nop 0
	global_load_lds_dwordx4 v[96:97], off
	s_mov_b32 m0, s23
	v_lshl_add_u64 v[96:97], v[68:69], 0, s[4:5]
	global_load_lds_dwordx4 v77, s[56:57]
	s_mov_b32 m0, s29
	s_nop 0
	global_load_lds_dwordx4 v[96:97], off
	s_mov_b32 m0, s69
	v_lshl_add_u64 v[96:97], v[70:71], 0, s[4:5]
	global_load_lds_dwordx4 v78, s[56:57]
	s_mov_b32 m0, s70
	s_mov_b64 s[4:5], 0x580
	global_load_lds_dwordx4 v[96:97], off
	s_mov_b32 m0, s71
	v_lshl_add_u64 v[88:89], v[66:67], 0, s[4:5]
	global_load_lds_dwordx4 v84, s[56:57]
	ds_read_b128 v[96:99], v79 offset:32768
	ds_read_b128 v[100:103], v81 offset:49152
	ds_read_b128 v[104:107], v81 offset:53248
	s_waitcnt lgkmcnt(0)
	v_mfma_f32_32x32x16_bf16 v[48:63], v[96:99], v[100:103], v[48:63]
	s_mov_b32 m0, s84
	v_mfma_f32_32x32x16_bf16 v[32:47], v[96:99], v[104:107], v[32:47]
	ds_read_b128 v[96:99], v79 offset:36864
	s_waitcnt lgkmcnt(0)
	v_mfma_f32_32x32x16_bf16 v[16:31], v[96:99], v[100:103], v[16:31]
	v_mfma_f32_32x32x16_bf16 v[0:15], v[96:99], v[104:107], v[0:15]
	ds_read_b128 v[96:99], v80 offset:32768
	ds_read_b128 v[100:103], v83 offset:49152
	ds_read_b128 v[104:107], v83 offset:53248
	s_waitcnt lgkmcnt(0)
	v_mfma_f32_32x32x16_bf16 v[48:63], v[96:99], v[100:103], v[48:63]
	v_mfma_f32_32x32x16_bf16 v[32:47], v[96:99], v[104:107], v[32:47]
	ds_read_b128 v[96:99], v80 offset:36864
	s_waitcnt lgkmcnt(0)
	v_mfma_f32_32x32x16_bf16 v[16:31], v[96:99], v[100:103], v[16:31]
	v_mfma_f32_32x32x16_bf16 v[0:15], v[96:99], v[104:107], v[0:15]
	ds_read_b128 v[96:99], v82 offset:32768
	ds_read_b128 v[100:103], v85 offset:49152
	ds_read_b128 v[104:107], v85 offset:53248
	s_waitcnt lgkmcnt(0)
	v_mfma_f32_32x32x16_bf16 v[48:63], v[96:99], v[100:103], v[48:63]
	v_mfma_f32_32x32x16_bf16 v[32:47], v[96:99], v[104:107], v[32:47]
	ds_read_b128 v[96:99], v82 offset:36864
	s_waitcnt lgkmcnt(0)
	v_mfma_f32_32x32x16_bf16 v[16:31], v[96:99], v[100:103], v[16:31]
	v_mfma_f32_32x32x16_bf16 v[0:15], v[96:99], v[104:107], v[0:15]
	ds_read_b128 v[96:99], v86 offset:32768
	ds_read_b128 v[100:103], v87 offset:49152
	ds_read_b128 v[104:107], v87 offset:53248
	s_waitcnt lgkmcnt(0)
	v_mfma_f32_32x32x16_bf16 v[48:63], v[96:99], v[100:103], v[48:63]
	v_mfma_f32_32x32x16_bf16 v[32:47], v[96:99], v[104:107], v[32:47]
	ds_read_b128 v[96:99], v86 offset:36864
	s_waitcnt vmcnt(0)
	s_waitcnt vmcnt(0) lgkmcnt(0)
	s_barrier
; #define WAIT_V0() asm volatile("s_waitcnt vmcnt(0)" ::: "memory")
; DI void gemm_core(char* smem, int nk, const char* Ab, const char* Bb, const unsigned (&aoff)[4], const unsigned (&boff)[4],
;                   f32x16 (&acc)[2][2]) {
;     ...
;   auto stage = [&](int buf, int kt) __attribute__((always_inline)) {
;     const char* ak = Ab + kt * 128;
;     const char* bk = Bb + kt * 128;
;     char* sa = smem + buf * STAGE_B + w * 4096;
; #pragma unroll
;     for (int i = 0; i < 4; ++i) {
;       __builtin_amdgcn_global_load_lds((const unsigned*)(ak + aoff[i]), (unsigned*)(sa + i * 1024), 16, 0, 0);
;       __builtin_amdgcn_global_load_lds((const unsigned*)(bk + boff[i]), (unsigned*)(sa + 16384 + i * 1024), 16, 0, 0);
;     }
;   };
;     ...
;   for (int kt = 0; kt < nk; ++kt) {
;     const int cur = kt & 1;
;     if (kt + 1 < nk) stage(cur ^ 1, kt + 1);
;     const char* sb = smem + cur * STAGE_B;
; #pragma unroll
;     for (int ks = 0; ks < 4; ++ks) {
;       bf16x8 af[2], bfr[2];
; #pragma unroll
;       for (int mb = 0; mb < 2; ++mb) af[mb] = *(const bf16x8*)(sb + a_base + mb * 4096 + xo[ks]);
; #pragma unroll
;       for (int nb = 0; nb < 2; ++nb) bfr[nb] = *(const bf16x8*)(sb + b_base + nb * 4096 + xo[ks]);
; #pragma unroll
;       for (int mb = 0; mb < 2; ++mb)
; #pragma unroll
;         for (int nb = 0; nb < 2; ++nb)
;           acc[mb][nb] = __builtin_amdgcn_mfma_f32_32x32x16_bf16(af[mb], bfr[nb], acc[mb][nb], 0, 0, 0);
;     }
;     WAIT_V0();
;     __syncthreads();
;   }
	v_mfma_f32_32x32x16_bf16 v[16:31], v[96:99], v[100:103], v[16:31]
	v_mfma_f32_32x32x16_bf16 v[0:15], v[96:99], v[104:107], v[0:15]
	v_lshl_add_u64 v[96:97], v[64:65], 0, s[4:5]
	global_load_lds_dwordx4 v[96:97], off
	s_mov_b32 m0, s85
	s_nop 0
	global_load_lds_dwordx4 v76, s[58:59]
	s_mov_b32 m0, s86
	s_nop 0
	global_load_lds_dwordx4 v[88:89], off
	s_mov_b32 m0, s87
	v_lshl_add_u64 v[88:89], v[68:69], 0, s[4:5]
	global_load_lds_dwordx4 v77, s[58:59]
	s_mov_b32 m0, s88
	s_nop 0
	global_load_lds_dwordx4 v[88:89], off
	s_mov_b32 m0, s89
	v_lshl_add_u64 v[88:89], v[70:71], 0, s[4:5]
	global_load_lds_dwordx4 v78, s[58:59]
	s_mov_b32 m0, s90
	s_mov_b64 s[4:5], 0x600
	global_load_lds_dwordx4 v[88:89], off
	s_mov_b32 m0, s91
	s_nop 0
	global_load_lds_dwordx4 v84, s[58:59]
	ds_read_b128 v[88:91], v79
	ds_read_b128 v[92:95], v81 offset:16384
	ds_read_b128 v[96:99], v81 offset:20480
	s_waitcnt lgkmcnt(0)
	v_mfma_f32_32x32x16_bf16 v[48:63], v[88:91], v[92:95], v[48:63]
	s_mov_b32 m0, s18
	v_mfma_f32_32x32x16_bf16 v[32:47], v[88:91], v[96:99], v[32:47]
	ds_read_b128 v[88:91], v79 offset:4096
	s_waitcnt lgkmcnt(0)
	v_mfma_f32_32x32x16_bf16 v[16:31], v[88:91], v[92:95], v[16:31]
	v_mfma_f32_32x32x16_bf16 v[0:15], v[88:91], v[96:99], v[0:15]
	ds_read_b128 v[88:91], v80
	ds_read_b128 v[92:95], v83 offset:16384
	ds_read_b128 v[96:99], v83 offset:20480
	s_waitcnt lgkmcnt(0)
	v_mfma_f32_32x32x16_bf16 v[48:63], v[88:91], v[92:95], v[48:63]
	v_mfma_f32_32x32x16_bf16 v[32:47], v[88:91], v[96:99], v[32:47]
	ds_read_b128 v[88:91], v80 offset:4096
	s_waitcnt lgkmcnt(0)
	v_mfma_f32_32x32x16_bf16 v[16:31], v[88:91], v[92:95], v[16:31]
	v_mfma_f32_32x32x16_bf16 v[0:15], v[88:91], v[96:99], v[0:15]
	ds_read_b128 v[88:91], v82
	ds_read_b128 v[92:95], v85 offset:16384
	ds_read_b128 v[96:99], v85 offset:20480
	s_waitcnt lgkmcnt(0)
	v_mfma_f32_32x32x16_bf16 v[48:63], v[88:91], v[92:95], v[48:63]
	v_mfma_f32_32x32x16_bf16 v[32:47], v[88:91], v[96:99], v[32:47]
	ds_read_b128 v[88:91], v82 offset:4096
	s_waitcnt lgkmcnt(0)
	v_mfma_f32_32x32x16_bf16 v[16:31], v[88:91], v[92:95], v[16:31]
	v_mfma_f32_32x32x16_bf16 v[0:15], v[88:91], v[96:99], v[0:15]
	ds_read_b128 v[88:91], v86
	ds_read_b128 v[92:95], v87 offset:16384
	ds_read_b128 v[96:99], v87 offset:20480
	s_waitcnt lgkmcnt(0)
	v_mfma_f32_32x32x16_bf16 v[48:63], v[88:91], v[92:95], v[48:63]
	v_mfma_f32_32x32x16_bf16 v[32:47], v[88:91], v[96:99], v[32:47]
	ds_read_b128 v[88:91], v86 offset:4096
	s_waitcnt vmcnt(0)
	s_waitcnt vmcnt(0) lgkmcnt(0)
	s_barrier
	v_mfma_f32_32x32x16_bf16 v[16:31], v[88:91], v[92:95], v[16:31]
	v_mfma_f32_32x32x16_bf16 v[0:15], v[88:91], v[96:99], v[0:15]
	ds_read_b128 v[88:91], v79 offset:32768
	ds_read_b128 v[92:95], v81 offset:49152
	ds_read_b128 v[96:99], v81 offset:53248
	v_lshl_add_u64 v[140:141], v[64:65], 0, s[4:5]
	global_load_lds_dwordx4 v[140:141], off
	s_mov_b32 m0, s19
	v_lshl_add_u64 v[142:143], v[66:67], 0, s[4:5]
	global_load_lds_dwordx4 v76, s[60:61]
	s_mov_b32 m0, s22
	s_nop 0
	global_load_lds_dwordx4 v[142:143], off
	s_mov_b32 m0, s23
	v_lshl_add_u64 v[140:141], v[68:69], 0, s[4:5]
	global_load_lds_dwordx4 v77, s[60:61]
	s_mov_b32 m0, s29
	s_nop 0
	global_load_lds_dwordx4 v[140:141], off
	s_mov_b32 m0, s69
	v_lshl_add_u64 v[142:143], v[70:71], 0, s[4:5]
	global_load_lds_dwordx4 v78, s[60:61]
	s_mov_b32 m0, s70
	s_mov_b64 s[4:5], 0x680
	global_load_lds_dwordx4 v[142:143], off
	s_mov_b32 m0, s71
	s_nop 0
	global_load_lds_dwordx4 v84, s[60:61]
	s_waitcnt lgkmcnt(0)
	v_mfma_f32_32x32x16_bf16 v[48:63], v[88:91], v[92:95], v[48:63]
	s_mov_b32 m0, s84
	v_mfma_f32_32x32x16_bf16 v[32:47], v[88:91], v[96:99], v[32:47]
	ds_read_b128 v[88:91], v79 offset:36864
	s_waitcnt lgkmcnt(0)
	v_mfma_f32_32x32x16_bf16 v[16:31], v[88:91], v[92:95], v[16:31]
	v_mfma_f32_32x32x16_bf16 v[0:15], v[88:91], v[96:99], v[0:15]
	ds_read_b128 v[88:91], v80 offset:32768
	ds_read_b128 v[92:95], v83 offset:49152
	ds_read_b128 v[96:99], v83 offset:53248
	s_waitcnt lgkmcnt(0)
	v_mfma_f32_32x32x16_bf16 v[48:63], v[88:91], v[92:95], v[48:63]
	v_mfma_f32_32x32x16_bf16 v[32:47], v[88:91], v[96:99], v[32:47]
	ds_read_b128 v[88:91], v80 offset:36864
	s_waitcnt lgkmcnt(0)
	v_mfma_f32_32x32x16_bf16 v[16:31], v[88:91], v[92:95], v[16:31]
	v_mfma_f32_32x32x16_bf16 v[0:15], v[88:91], v[96:99], v[0:15]
	ds_read_b128 v[88:91], v82 offset:32768
	ds_read_b128 v[92:95], v85 offset:49152
	ds_read_b128 v[96:99], v85 offset:53248
	s_waitcnt lgkmcnt(0)
	v_mfma_f32_32x32x16_bf16 v[48:63], v[88:91], v[92:95], v[48:63]
	v_mfma_f32_32x32x16_bf16 v[32:47], v[88:91], v[96:99], v[32:47]
	ds_read_b128 v[88:91], v82 offset:36864
	s_waitcnt lgkmcnt(0)
	v_mfma_f32_32x32x16_bf16 v[16:31], v[88:91], v[92:95], v[16:31]
	v_mfma_f32_32x32x16_bf16 v[0:15], v[88:91], v[96:99], v[0:15]
	ds_read_b128 v[88:91], v86 offset:32768
	ds_read_b128 v[92:95], v87 offset:49152
	ds_read_b128 v[96:99], v87 offset:53248
	s_waitcnt lgkmcnt(0)
	v_mfma_f32_32x32x16_bf16 v[48:63], v[88:91], v[92:95], v[48:63]
	v_mfma_f32_32x32x16_bf16 v[32:47], v[88:91], v[96:99], v[32:47]
	ds_read_b128 v[88:91], v86 offset:36864
	s_waitcnt vmcnt(0)
	s_waitcnt vmcnt(0) lgkmcnt(0)
	s_barrier
; #define WAIT_V0() asm volatile("s_waitcnt vmcnt(0)" ::: "memory")
; DI void gemm_core(char* smem, int nk, const char* Ab, const char* Bb, const unsigned (&aoff)[4], const unsigned (&boff)[4],
;                   f32x16 (&acc)[2][2]) {
;     ...
;   auto stage = [&](int buf, int kt) __attribute__((always_inline)) {
;     const char* ak = Ab + kt * 128;
;     const char* bk = Bb + kt * 128;
;     char* sa = smem + buf * STAGE_B + w * 4096;
; #pragma unroll
;     for (int i = 0; i < 4; ++i) {
;       __builtin_amdgcn_global_load_lds((const unsigned*)(ak + aoff[i]), (unsigned*)(sa + i * 1024), 16, 0, 0);
;       __builtin_amdgcn_global_load_lds((const unsigned*)(bk + boff[i]), (unsigned*)(sa + 16384 + i * 1024), 16, 0, 0);
;     }
;   };
;     ...
;   for (int kt = 0; kt < nk; ++kt) {
;     const int cur = kt & 1;
;     if (kt + 1 < nk) stage(cur ^ 1, kt + 1);
;     const char* sb = smem + cur * STAGE_B;
; #pragma unroll
;     for (int ks = 0; ks < 4; ++ks) {
;       bf16x8 af[2], bfr[2];
; #pragma unroll
;       for (int mb = 0; mb < 2; ++mb) af[mb] = *(const bf16x8*)(sb + a_base + mb * 4096 + xo[ks]);
; #pragma unroll
;       for (int nb = 0; nb < 2; ++nb) bfr[nb] = *(const bf16x8*)(sb + b_base + nb * 4096 + xo[ks]);
; #pragma unroll
;       for (int mb = 0; mb < 2; ++mb)
; #pragma unroll
;         for (int nb = 0; nb < 2; ++nb)
;           acc[mb][nb] = __builtin_amdgcn_mfma_f32_32x32x16_bf16(af[mb], bfr[nb], acc[mb][nb], 0, 0, 0);
;     }
;     WAIT_V0();
;     __syncthreads();
;   }
	v_mfma_f32_32x32x16_bf16 v[16:31], v[88:91], v[92:95], v[16:31]
	v_mfma_f32_32x32x16_bf16 v[0:15], v[88:91], v[96:99], v[0:15]
	ds_read_b128 v[88:91], v79
	ds_read_b128 v[92:95], v81 offset:16384
	ds_read_b128 v[96:99], v81 offset:20480
	v_lshl_add_u64 v[140:141], v[64:65], 0, s[4:5]
	global_load_lds_dwordx4 v[140:141], off
	s_mov_b32 m0, s85
	v_lshl_add_u64 v[142:143], v[66:67], 0, s[4:5]
	global_load_lds_dwordx4 v76, s[62:63]
	s_mov_b32 m0, s86
	s_nop 0
	global_load_lds_dwordx4 v[142:143], off
	s_mov_b32 m0, s87
	v_lshl_add_u64 v[140:141], v[68:69], 0, s[4:5]
	global_load_lds_dwordx4 v77, s[62:63]
	s_mov_b32 m0, s88
	s_nop 0
	global_load_lds_dwordx4 v[140:141], off
	s_mov_b32 m0, s89
	v_lshl_add_u64 v[142:143], v[70:71], 0, s[4:5]
	global_load_lds_dwordx4 v78, s[62:63]
	s_mov_b32 m0, s90
	s_mov_b64 s[4:5], 0x700
	global_load_lds_dwordx4 v[142:143], off
	s_mov_b32 m0, s91
	s_nop 0
	global_load_lds_dwordx4 v84, s[62:63]
	s_waitcnt lgkmcnt(0)
	v_mfma_f32_32x32x16_bf16 v[48:63], v[88:91], v[92:95], v[48:63]
	s_mov_b32 m0, s18
	v_mfma_f32_32x32x16_bf16 v[32:47], v[88:91], v[96:99], v[32:47]
	ds_read_b128 v[88:91], v79 offset:4096
	s_waitcnt lgkmcnt(0)
	v_mfma_f32_32x32x16_bf16 v[16:31], v[88:91], v[92:95], v[16:31]
	v_mfma_f32_32x32x16_bf16 v[0:15], v[88:91], v[96:99], v[0:15]
	ds_read_b128 v[88:91], v80
	ds_read_b128 v[92:95], v83 offset:16384
	ds_read_b128 v[96:99], v83 offset:20480
	s_waitcnt lgkmcnt(0)
	v_mfma_f32_32x32x16_bf16 v[48:63], v[88:91], v[92:95], v[48:63]
	v_mfma_f32_32x32x16_bf16 v[32:47], v[88:91], v[96:99], v[32:47]
	ds_read_b128 v[88:91], v80 offset:4096
	s_waitcnt lgkmcnt(0)
	v_mfma_f32_32x32x16_bf16 v[16:31], v[88:91], v[92:95], v[16:31]
	v_mfma_f32_32x32x16_bf16 v[0:15], v[88:91], v[96:99], v[0:15]
	ds_read_b128 v[88:91], v82
	ds_read_b128 v[92:95], v85 offset:16384
	ds_read_b128 v[96:99], v85 offset:20480
	s_waitcnt lgkmcnt(0)
	v_mfma_f32_32x32x16_bf16 v[48:63], v[88:91], v[92:95], v[48:63]
	v_mfma_f32_32x32x16_bf16 v[32:47], v[88:91], v[96:99], v[32:47]
	ds_read_b128 v[88:91], v82 offset:4096
	s_waitcnt lgkmcnt(0)
	v_mfma_f32_32x32x16_bf16 v[16:31], v[88:91], v[92:95], v[16:31]
	v_mfma_f32_32x32x16_bf16 v[0:15], v[88:91], v[96:99], v[0:15]
	ds_read_b128 v[88:91], v86
	ds_read_b128 v[92:95], v87 offset:16384
	ds_read_b128 v[96:99], v87 offset:20480
	s_waitcnt lgkmcnt(0)
	v_mfma_f32_32x32x16_bf16 v[48:63], v[88:91], v[92:95], v[48:63]
	v_mfma_f32_32x32x16_bf16 v[32:47], v[88:91], v[96:99], v[32:47]
	ds_read_b128 v[88:91], v86 offset:4096
	s_waitcnt vmcnt(0)
	s_waitcnt vmcnt(0) lgkmcnt(0)
	s_barrier
	v_mfma_f32_32x32x16_bf16 v[16:31], v[88:91], v[92:95], v[16:31]
	v_mfma_f32_32x32x16_bf16 v[0:15], v[88:91], v[96:99], v[0:15]
	v_lshl_add_u64 v[88:89], v[64:65], 0, s[4:5]
	global_load_lds_dwordx4 v[88:89], off
	s_mov_b32 m0, s19
	v_lshl_add_u64 v[88:89], v[66:67], 0, s[4:5]
	global_load_lds_dwordx4 v76, s[64:65]
	s_mov_b32 m0, s22
	s_nop 0
	global_load_lds_dwordx4 v[88:89], off
	s_mov_b32 m0, s23
	v_lshl_add_u64 v[88:89], v[68:69], 0, s[4:5]
	global_load_lds_dwordx4 v77, s[64:65]
	s_mov_b32 m0, s29
	s_nop 0
	global_load_lds_dwordx4 v[88:89], off
	s_mov_b32 m0, s69
	v_lshl_add_u64 v[88:89], v[70:71], 0, s[4:5]
	global_load_lds_dwordx4 v78, s[64:65]
	s_mov_b32 m0, s70
	s_mov_b64 s[4:5], 0x780
	global_load_lds_dwordx4 v[88:89], off
	s_mov_b32 m0, s71
	v_lshl_add_u64 v[64:65], v[64:65], 0, s[4:5]
	global_load_lds_dwordx4 v84, s[64:65]
	ds_read_b128 v[88:91], v79 offset:32768
	ds_read_b128 v[92:95], v81 offset:49152
	ds_read_b128 v[96:99], v81 offset:53248
	s_waitcnt lgkmcnt(0)
	v_mfma_f32_32x32x16_bf16 v[48:63], v[88:91], v[92:95], v[48:63]
	s_mov_b32 m0, s84
	s_movk_i32 s4, 0x4000
	v_mfma_f32_32x32x16_bf16 v[32:47], v[88:91], v[96:99], v[32:47]
	ds_read_b128 v[88:91], v79 offset:36864
	s_waitcnt lgkmcnt(0)
	v_mfma_f32_32x32x16_bf16 v[16:31], v[88:91], v[92:95], v[16:31]
	v_mfma_f32_32x32x16_bf16 v[0:15], v[88:91], v[96:99], v[0:15]
	ds_read_b128 v[88:91], v80 offset:32768
	ds_read_b128 v[92:95], v83 offset:49152
	ds_read_b128 v[96:99], v83 offset:53248
	s_waitcnt lgkmcnt(0)
	v_mfma_f32_32x32x16_bf16 v[48:63], v[88:91], v[92:95], v[48:63]
	v_mfma_f32_32x32x16_bf16 v[32:47], v[88:91], v[96:99], v[32:47]
	ds_read_b128 v[88:91], v80 offset:36864
	s_waitcnt lgkmcnt(0)
	v_mfma_f32_32x32x16_bf16 v[16:31], v[88:91], v[92:95], v[16:31]
	v_mfma_f32_32x32x16_bf16 v[0:15], v[88:91], v[96:99], v[0:15]
	ds_read_b128 v[88:91], v82 offset:32768
	ds_read_b128 v[92:95], v85 offset:49152
	ds_read_b128 v[96:99], v85 offset:53248
	s_waitcnt lgkmcnt(0)
	v_mfma_f32_32x32x16_bf16 v[48:63], v[88:91], v[92:95], v[48:63]
	v_mfma_f32_32x32x16_bf16 v[32:47], v[88:91], v[96:99], v[32:47]
	ds_read_b128 v[88:91], v82 offset:36864
	s_waitcnt lgkmcnt(0)
	v_mfma_f32_32x32x16_bf16 v[16:31], v[88:91], v[92:95], v[16:31]
	v_mfma_f32_32x32x16_bf16 v[0:15], v[88:91], v[96:99], v[0:15]
	ds_read_b128 v[88:91], v86 offset:32768
	ds_read_b128 v[92:95], v87 offset:49152
	ds_read_b128 v[96:99], v87 offset:53248
	s_waitcnt lgkmcnt(0)
	v_mfma_f32_32x32x16_bf16 v[48:63], v[88:91], v[92:95], v[48:63]
	v_mfma_f32_32x32x16_bf16 v[32:47], v[88:91], v[96:99], v[32:47]
	ds_read_b128 v[88:91], v86 offset:36864
	s_waitcnt vmcnt(0)
	s_waitcnt vmcnt(0) lgkmcnt(0)
	s_barrier
; #define WAIT_V0() asm volatile("s_waitcnt vmcnt(0)" ::: "memory")
; DI void gemm_core(char* smem, int nk, const char* Ab, const char* Bb, const unsigned (&aoff)[4], const unsigned (&boff)[4],
;                   f32x16 (&acc)[2][2]) {
;     ...
;   for (int kt = 0; kt < nk; ++kt) {
;     const int cur = kt & 1;
;     if (kt + 1 < nk) stage(cur ^ 1, kt + 1);
;     const char* sb = smem + cur * STAGE_B;
; #pragma unroll
;     for (int ks = 0; ks < 4; ++ks) {
;       bf16x8 af[2], bfr[2];
; #pragma unroll
;       for (int mb = 0; mb < 2; ++mb) af[mb] = *(const bf16x8*)(sb + a_base + mb * 4096 + xo[ks]);
; #pragma unroll
;       for (int nb = 0; nb < 2; ++nb) bfr[nb] = *(const bf16x8*)(sb + b_base + nb * 4096 + xo[ks]);
; #pragma unroll
;       for (int mb = 0; mb < 2; ++mb)
; #pragma unroll
;         for (int nb = 0; nb < 2; ++nb)
;           acc[mb][nb] = __builtin_amdgcn_mfma_f32_32x32x16_bf16(af[mb], bfr[nb], acc[mb][nb], 0, 0, 0);
;     }
;     WAIT_V0();
;     __syncthreads();
;   }
	global_load_lds_dwordx4 v[64:65], off
	s_mov_b32 m0, s85
	v_lshl_add_u64 v[64:65], v[66:67], 0, s[6:7]
	global_load_lds_dwordx4 v76, s[66:67]
	s_mov_b32 m0, s86
	v_mfma_f32_32x32x16_bf16 v[16:31], v[88:91], v[92:95], v[16:31]
	global_load_lds_dwordx4 v[64:65], off
	s_mov_b32 m0, s87
	v_lshl_add_u64 v[64:65], v[68:69], 0, s[6:7]
	global_load_lds_dwordx4 v77, s[66:67]
	s_mov_b32 m0, s88
	v_mfma_f32_32x32x16_bf16 v[0:15], v[88:91], v[96:99], v[0:15]
	global_load_lds_dwordx4 v[64:65], off
	s_mov_b32 m0, s89
	v_lshl_add_u64 v[64:65], v[70:71], 0, s[6:7]
	global_load_lds_dwordx4 v78, s[66:67]
	s_mov_b32 m0, s90
	v_readlane_b32 s86, v254, 58
	global_load_lds_dwordx4 v[64:65], off
	s_mov_b32 m0, s91
	v_readlane_b32 s87, v254, 59
	global_load_lds_dwordx4 v84, s[66:67]
	ds_read_b128 v[64:67], v79
	ds_read_b128 v[68:71], v81 offset:16384
	ds_read_b128 v[88:91], v81 offset:20480
	s_waitcnt lgkmcnt(0)
	v_mfma_f32_32x32x16_bf16 v[48:63], v[64:67], v[68:71], v[48:63]
	v_mfma_f32_32x32x16_bf16 v[32:47], v[64:67], v[88:91], v[32:47]
	ds_read_b128 v[64:67], v79 offset:4096
	s_waitcnt lgkmcnt(0)
	v_mfma_f32_32x32x16_bf16 v[16:31], v[64:67], v[68:71], v[16:31]
	v_mfma_f32_32x32x16_bf16 v[0:15], v[64:67], v[88:91], v[0:15]
	ds_read_b128 v[64:67], v80
	ds_read_b128 v[68:71], v83 offset:16384
	ds_read_b128 v[88:91], v83 offset:20480
	s_waitcnt lgkmcnt(0)
	v_mfma_f32_32x32x16_bf16 v[48:63], v[64:67], v[68:71], v[48:63]
	v_mfma_f32_32x32x16_bf16 v[32:47], v[64:67], v[88:91], v[32:47]
	ds_read_b128 v[64:67], v80 offset:4096
	s_waitcnt lgkmcnt(0)
	v_mfma_f32_32x32x16_bf16 v[16:31], v[64:67], v[68:71], v[16:31]
	v_mfma_f32_32x32x16_bf16 v[0:15], v[64:67], v[88:91], v[0:15]
	ds_read_b128 v[64:67], v82
	ds_read_b128 v[68:71], v85 offset:16384
	ds_read_b128 v[88:91], v85 offset:20480
	s_waitcnt lgkmcnt(0)
	v_mfma_f32_32x32x16_bf16 v[48:63], v[64:67], v[68:71], v[48:63]
	v_mfma_f32_32x32x16_bf16 v[32:47], v[64:67], v[88:91], v[32:47]
	ds_read_b128 v[64:67], v82 offset:4096
	s_waitcnt lgkmcnt(0)
	v_mfma_f32_32x32x16_bf16 v[16:31], v[64:67], v[68:71], v[16:31]
	v_mfma_f32_32x32x16_bf16 v[0:15], v[64:67], v[88:91], v[0:15]
	ds_read_b128 v[64:67], v86
	ds_read_b128 v[68:71], v87 offset:16384
	ds_read_b128 v[88:91], v87 offset:20480
	s_waitcnt lgkmcnt(0)
	v_mfma_f32_32x32x16_bf16 v[48:63], v[64:67], v[68:71], v[48:63]
	v_mfma_f32_32x32x16_bf16 v[32:47], v[64:67], v[88:91], v[32:47]
	ds_read_b128 v[64:67], v86 offset:4096
	s_waitcnt vmcnt(0)
	s_waitcnt vmcnt(0) lgkmcnt(0)
	s_barrier
	v_mfma_f32_32x32x16_bf16 v[16:31], v[64:67], v[68:71], v[16:31]
	v_mfma_f32_32x32x16_bf16 v[0:15], v[64:67], v[88:91], v[0:15]
	ds_read_b128 v[64:67], v79 offset:32768
	ds_read_b128 v[68:71], v81 offset:49152
	ds_read_b128 v[88:91], v81 offset:53248
	s_waitcnt lgkmcnt(1)
	v_mfma_f32_32x32x16_bf16 v[48:63], v[64:67], v[68:71], v[48:63]
	s_waitcnt lgkmcnt(0)
	v_mfma_f32_32x32x16_bf16 v[32:47], v[64:67], v[88:91], v[32:47]
	ds_read_b128 v[64:67], v79 offset:36864
	s_waitcnt lgkmcnt(0)
	v_mfma_f32_32x32x16_bf16 v[16:31], v[64:67], v[68:71], v[16:31]
	v_mfma_f32_32x32x16_bf16 v[0:15], v[64:67], v[88:91], v[0:15]
	ds_read_b128 v[64:67], v80 offset:32768
	ds_read_b128 v[68:71], v83 offset:49152
	ds_read_b128 v[76:79], v83 offset:53248
	s_waitcnt lgkmcnt(1)
	v_mfma_f32_32x32x16_bf16 v[48:63], v[64:67], v[68:71], v[48:63]
	s_waitcnt lgkmcnt(0)
	v_mfma_f32_32x32x16_bf16 v[32:47], v[64:67], v[76:79], v[32:47]
	ds_read_b128 v[64:67], v80 offset:36864
	s_waitcnt lgkmcnt(0)
	v_mfma_f32_32x32x16_bf16 v[16:31], v[64:67], v[68:71], v[16:31]
	v_mfma_f32_32x32x16_bf16 v[0:15], v[64:67], v[76:79], v[0:15]
	ds_read_b128 v[64:67], v82 offset:32768
	ds_read_b128 v[68:71], v85 offset:49152
	ds_read_b128 v[76:79], v85 offset:53248
	s_waitcnt lgkmcnt(1)
	v_mfma_f32_32x32x16_bf16 v[48:63], v[64:67], v[68:71], v[48:63]
	s_waitcnt lgkmcnt(0)
	v_mfma_f32_32x32x16_bf16 v[32:47], v[64:67], v[76:79], v[32:47]
	ds_read_b128 v[64:67], v82 offset:36864
	s_waitcnt lgkmcnt(0)
	v_mfma_f32_32x32x16_bf16 v[16:31], v[64:67], v[68:71], v[16:31]
	ds_read_b128 v[68:71], v87 offset:53248
	ds_read_b128 v[80:83], v87 offset:49152
	ds_read_b128 v[88:91], v86 offset:36864
	ds_read_b128 v[84:87], v86 offset:32768
	s_waitcnt vmcnt(0)
	s_waitcnt lgkmcnt(0)
	s_barrier
; DI int ltid() { int t = threadIdx.x; asm volatile("" : "+v"(t)); return t; }
; template <class F>
; DI void epi_foreach(const f32x16 (&acc)[2][2], F f) {
;   const int lane = ltid() & 63, w = ltid() >> 6;
;   const int wm = w >> 1, wn = w & 1;
; #pragma unroll
;   for (int mb = 0; mb < 2; ++mb)
; #pragma unroll
;     for (int nb = 0; nb < 2; ++nb)
; #pragma unroll
;       for (int r = 0; r < 16; ++r) {
;         const int row = wm * 64 + mb * 32 + (r & 3) + 8 * (r >> 2) + 4 * (lane >> 5);
;         const int col = wn * 64 + nb * 32 + (lane & 31);
;         f(row, col, acc[mb][nb][r]);
;         if ((r & 7) == 7) __builtin_amdgcn_sched_barrier(0);
;       }
; DI void phase_up(const Params& P, int layer, char* smem) {
;     ...
;     epi_foreach(acc, [&](int row, int col, float v) __attribute__((always_inline)) { Cs[row * 136 + col] = f2bf(v); });
;     __syncthreads();
;     {
;       const int col = tid & 63, rb = tid >> 6;
;       const int cv = nt * 64 + col, cg_ = DFF + nt * 64 + col;
;       const float w0v = cw[cv], w1v = cw[5632 + cv], w2v = cw[2 * 5632 + cv], bv = cb[cv];
;       const float w0g = cw[cg_], w1g = cw[5632 + cg_], w2g = cw[2 * 5632 + cg_], bgt = cb[cg_];
	v_mfma_f32_32x32x16_bf16 v[48:63], v[84:87], v[80:83], v[48:63]
	v_mfma_f32_32x32x16_bf16 v[0:15], v[64:67], v[76:79], v[0:15]
	v_mov_b32_e32 v64, v161
	v_mov_b32_e32 v65, v161
	v_lshrrev_b32_e32 v67, 3, v64
	v_and_b32_e32 v67, 4, v67
	v_lshrrev_b32_e32 v66, 1, v65
	v_and_b32_e32 v64, 31, v64
	v_and_or_b32 v64, v65, 64, v64
	v_and_or_b32 v65, v66, s3, v67
	v_mul_lo_u32 v65, v65, s97
	s_nop 1
	v_cvt_pk_bf16_f32 v48, v48, s0
	v_lshl_add_u32 v64, v64, 1, v65
	ds_write_b16 v64, v48
	v_cvt_pk_bf16_f32 v48, v49, s0
	ds_write_b16 v64, v48 offset:272
	v_cvt_pk_bf16_f32 v48, v50, s0
	ds_write_b16 v64, v48 offset:544
	v_cvt_pk_bf16_f32 v48, v51, s0
	ds_write_b16 v64, v48 offset:816
	v_cvt_pk_bf16_f32 v48, v52, s0
	ds_write_b16 v64, v48 offset:2176
	v_cvt_pk_bf16_f32 v48, v53, s0
	ds_write_b16 v64, v48 offset:2448
	v_cvt_pk_bf16_f32 v48, v54, s0
	ds_write_b16 v64, v48 offset:2720
	v_cvt_pk_bf16_f32 v48, v55, s0
	v_mfma_f32_32x32x16_bf16 v[32:47], v[84:87], v[68:71], v[32:47]
	ds_write_b16 v64, v48 offset:2992
	v_mfma_f32_32x32x16_bf16 v[16:31], v[88:91], v[80:83], v[16:31]
	v_mfma_f32_32x32x16_bf16 v[0:15], v[88:91], v[68:71], v[0:15]
	v_cvt_pk_bf16_f32 v48, v56, s0
	ds_write_b16 v64, v48 offset:4352
	v_cvt_pk_bf16_f32 v48, v57, s0
	ds_write_b16 v64, v48 offset:4624
	v_cvt_pk_bf16_f32 v48, v58, s0
	ds_write_b16 v64, v48 offset:4896
	v_cvt_pk_bf16_f32 v48, v59, s0
	ds_write_b16 v64, v48 offset:5168
	v_cvt_pk_bf16_f32 v48, v60, s0
	ds_write_b16 v64, v48 offset:6528
	v_cvt_pk_bf16_f32 v48, v61, s0
	ds_write_b16 v64, v48 offset:6800
	v_cvt_pk_bf16_f32 v48, v62, s0
	ds_write_b16 v64, v48 offset:7072
	v_cvt_pk_bf16_f32 v48, v63, s0
	ds_write_b16 v64, v48 offset:7344
	v_cvt_pk_bf16_f32 v32, v32, s0
	ds_write_b16 v64, v32 offset:64
	v_cvt_pk_bf16_f32 v32, v33, s0
	ds_write_b16 v64, v32 offset:336
	v_cvt_pk_bf16_f32 v32, v34, s0
	ds_write_b16 v64, v32 offset:608
	v_cvt_pk_bf16_f32 v32, v35, s0
	ds_write_b16 v64, v32 offset:880
	v_cvt_pk_bf16_f32 v32, v36, s0
	ds_write_b16 v64, v32 offset:2240
	v_cvt_pk_bf16_f32 v32, v37, s0
	ds_write_b16 v64, v32 offset:2512
	v_cvt_pk_bf16_f32 v32, v38, s0
	ds_write_b16 v64, v32 offset:2784
	v_cvt_pk_bf16_f32 v32, v39, s0
	ds_write_b16 v64, v32 offset:3056
	v_cvt_pk_bf16_f32 v32, v40, s0
	ds_write_b16 v64, v32 offset:4416
	v_cvt_pk_bf16_f32 v32, v41, s0
	ds_write_b16 v64, v32 offset:4688
	v_cvt_pk_bf16_f32 v32, v42, s0
	ds_write_b16 v64, v32 offset:4960
	v_cvt_pk_bf16_f32 v32, v43, s0
	ds_write_b16 v64, v32 offset:5232
	v_cvt_pk_bf16_f32 v32, v44, s0
	ds_write_b16 v64, v32 offset:6592
	v_cvt_pk_bf16_f32 v32, v45, s0
	ds_write_b16 v64, v32 offset:6864
	v_cvt_pk_bf16_f32 v32, v46, s0
	ds_write_b16 v64, v32 offset:7136
	v_cvt_pk_bf16_f32 v32, v47, s0
	ds_write_b16 v64, v32 offset:7408
	v_cvt_pk_bf16_f32 v16, v16, s0
	ds_write_b16 v64, v16 offset:8704
	v_cvt_pk_bf16_f32 v16, v17, s0
	ds_write_b16 v64, v16 offset:8976
	v_cvt_pk_bf16_f32 v16, v18, s0
	ds_write_b16 v64, v16 offset:9248
	v_cvt_pk_bf16_f32 v16, v19, s0
	ds_write_b16 v64, v16 offset:9520
	v_cvt_pk_bf16_f32 v16, v20, s0
	ds_write_b16 v64, v16 offset:10880
	v_cvt_pk_bf16_f32 v16, v21, s0
	ds_write_b16 v64, v16 offset:11152
	v_cvt_pk_bf16_f32 v16, v22, s0
	ds_write_b16 v64, v16 offset:11424
	v_cvt_pk_bf16_f32 v16, v23, s0
	ds_write_b16 v64, v16 offset:11696
	v_cvt_pk_bf16_f32 v16, v24, s0
	ds_write_b16 v64, v16 offset:13056
	v_cvt_pk_bf16_f32 v16, v25, s0
	ds_write_b16 v64, v16 offset:13328
	v_cvt_pk_bf16_f32 v16, v26, s0
	ds_write_b16 v64, v16 offset:13600
	v_cvt_pk_bf16_f32 v16, v27, s0
	ds_write_b16 v64, v16 offset:13872
	v_cvt_pk_bf16_f32 v16, v28, s0
	ds_write_b16 v64, v16 offset:15232
	v_cvt_pk_bf16_f32 v16, v29, s0
	ds_write_b16 v64, v16 offset:15504
	v_cvt_pk_bf16_f32 v16, v30, s0
	ds_write_b16 v64, v16 offset:15776
	v_cvt_pk_bf16_f32 v16, v31, s0
	ds_write_b16 v64, v16 offset:16048
	v_cvt_pk_bf16_f32 v0, v0, s0
	ds_write_b16 v64, v0 offset:8768
	v_cvt_pk_bf16_f32 v0, v1, s0
	ds_write_b16 v64, v0 offset:9040
	v_cvt_pk_bf16_f32 v0, v2, s0
	ds_write_b16 v64, v0 offset:9312
	v_cvt_pk_bf16_f32 v0, v3, s0
	ds_write_b16 v64, v0 offset:9584
	v_cvt_pk_bf16_f32 v0, v4, s0
	ds_write_b16 v64, v0 offset:10944
	v_cvt_pk_bf16_f32 v0, v5, s0
	ds_write_b16 v64, v0 offset:11216
	v_cvt_pk_bf16_f32 v0, v6, s0
	ds_write_b16 v64, v0 offset:11488
	v_cvt_pk_bf16_f32 v0, v7, s0
	ds_write_b16 v64, v0 offset:11760
	v_cvt_pk_bf16_f32 v0, v8, s0
	ds_write_b16 v64, v0 offset:13120
	v_cvt_pk_bf16_f32 v0, v9, s0
	ds_write_b16 v64, v0 offset:13392
	v_cvt_pk_bf16_f32 v0, v10, s0
	ds_write_b16 v64, v0 offset:13664
	v_cvt_pk_bf16_f32 v0, v11, s0
	ds_write_b16 v64, v0 offset:13936
	v_cvt_pk_bf16_f32 v0, v12, s0
	ds_write_b16 v64, v0 offset:15296
	v_cvt_pk_bf16_f32 v0, v13, s0
	ds_write_b16 v64, v0 offset:15568
	v_cvt_pk_bf16_f32 v0, v14, s0
	ds_write_b16 v64, v0 offset:15840
	v_cvt_pk_bf16_f32 v0, v15, s0
	ds_write_b16 v64, v0 offset:16112
	s_waitcnt lgkmcnt(0)
	s_barrier
	s_and_saveexec_b64 s[18:19], s[40:41]
	s_mov_b32 s3, 0xb000
	s_cbranch_execz .LBB0_24
	v_add_u32_e32 v136, s21, v74
	v_lshlrev_b64 v[4:5], 2, v[136:137]
	v_lshl_add_u64 v[8:9], s[10:11], 0, v[4:5]
	v_or_b32_e32 v10, s21, v72
	v_lshlrev_b32_e32 v126, 1, v10
	v_lshl_add_u64 v[2:3], s[12:13], 0, v[4:5]
	v_add_co_u32_e32 v4, vcc, 0xb000, v8
	v_ashrrev_i32_e32 v11, 31, v10
	s_nop 0
	v_addc_co_u32_e32 v5, vcc, 0, v9, vcc
	v_lshl_add_u64 v[0:1], v[10:11], 1, s[86:87]
	v_add_co_u32_e32 v6, vcc, 0x5000, v8
	v_lshlrev_b64 v[10:11], 2, v[10:11]
	s_nop 0
	v_addc_co_u32_e32 v7, vcc, 0, v9, vcc
	v_lshl_add_u64 v[12:13], s[12:13], 0, v[10:11]
	v_lshl_add_u64 v[10:11], s[10:11], 0, v[10:11]
	global_load_dword v3, v[2:3], off
	s_mulk_i32 s20, 0x7e
	global_load_dword v5, v[4:5], off
	s_nop 0
	global_load_dword v7, v[6:7], off offset:2048
	s_nop 0
	global_load_dword v9, v[8:9], off
	s_mul_i32 s21, s68, 0x7a
	global_load_dword v2, v[12:13], off
	v_add_co_u32_e32 v12, vcc, s3, v10
	s_sub_i32 s29, s20, s21
	s_nop 0
	v_addc_co_u32_e32 v13, vcc, 0, v11, vcc
	global_load_dword v4, v[12:13], off
	v_add_co_u32_e32 v12, vcc, 0x5000, v10
	s_mov_b64 s[20:21], 0
	s_nop 0
	v_addc_co_u32_e32 v13, vcc, 0, v11, vcc
	global_load_dword v6, v[12:13], off offset:2048
	global_load_dword v8, v[10:11], off
	v_mov_b32_e32 v11, v73
	v_mul_u32_u24_e32 v10, 0x110, v73
	v_mov_b32_e32 v128, 0
	v_mov_b32_e32 v129, 0
	v_mov_b32_e32 v130, 0
	v_mov_b32_e32 v131, 0
	v_mov_b32_e32 v132, 0
	v_mov_b32_e32 v133, 0
	v_mov_b32_e32 v134, 0
	v_mov_b32_e32 v135, 0
	s_waitcnt vmcnt(0)
	v_readfirstlane_b32 s22, v73
	v_add_u32_e32 v10, v75, v10
	v_add_u32_e32 v127, 0x1600, v126
	s_lshl_b32 s22, s22, 1
	s_add_i32 s23, s29, s22
	s_mul_hi_i32 s21, s23, 0x1600
	s_mul_i32 s20, s23, 0x1600
	s_add_u32 s20, s20, s86
	s_addc_u32 s21, s21, s87
	s_branch .LBB0_28

; template <class T> DI T* uoff(T* base, unsigned byteoff) { return (T*)((char*)base + byteoff); }
; template <class T> DI const T* uoff(const T* base, unsigned byteoff) { return (const T*)((const char*)base + byteoff); }
; DI void phase_out(const Params& P, int layer, const float* xin, char* smem) {
;     ...
;   for (int t0 = blockIdx.x; t0 < 256 * 8; t0 += gridDim.x) {
;     const int t = xcd_tile(t0, 256 * 8);
;     const int m0 = (t >> 3) * 128, n0 = (t & 7) * 128;
;     f32x16 acc[2][2];
;     float xr[2][2][16];
;     const unsigned obase_b = 4u * (unsigned)((m0 + wm * 64 + 4 * (lane >> 5)) * 1024 + n0 + wn * 64 + (lane & 31));
; #pragma unroll
;     for (int mb = 0; mb < 2; ++mb)
; #pragma unroll
;       for (int nb = 0; nb < 2; ++nb)
; #pragma unroll
;         for (int r = 0; r < 16; ++r) xr[mb][nb][r] = (*uoff(xin + ((mb * 32 + (r & 3) + 8 * (r >> 2)) * 1024 + nb * 32), obase_b));
.LBB0_43:
	s_ashr_i32 s0, s14, 3
	s_and_b32 s1, s0, 0xffffffc0
	s_lshl_b32 s10, s0, 1
	s_bfe_u32 s11, s0, 0x10005
	s_and_b32 s10, s10, 62
	s_or_b32 s1, s11, s1
	s_or_b32 s1, s1, s10
	s_and_b32 s10, s13, 0x700
	s_or_b32 s11, s0, 63
	s_cmpk_lt_i32 s11, 0x100
	s_cselect_b32 s1, s1, s0
	s_add_i32 s0, s1, s10
	s_lshl_b32 s0, s0, 4
	s_and_b32 s0, s0, 0xffffff80
	s_lshl_b32 s1, s1, 7
	s_and_b32 s15, s1, 0x380
	v_add_lshl_u32 v0, v80, s0, 10
	v_or3_b32 v0, v0, v81, s15
	v_lshlrev_b32_e32 v136, 2, v0
	v_lshl_add_u64 v[0:1], s[18:19], 0, v[136:137]
	v_add_co_u32_e32 v2, vcc, s17, v0
	s_mov_b32 s2, 0x13000
	s_nop 0
	v_addc_co_u32_e32 v3, vcc, 0, v1, vcc
	v_add_co_u32_e32 v4, vcc, s16, v0
	s_mov_b32 s68, 0x18000
	s_nop 0
	v_addc_co_u32_e32 v5, vcc, 0, v1, vcc
	v_add_co_u32_e32 v6, vcc, s20, v0
	s_mov_b32 s3, 0x1b000
	s_nop 0
	v_addc_co_u32_e32 v7, vcc, 0, v1, vcc
	v_add_co_u32_e32 v8, vcc, s9, v0
	global_load_dword v147, v136, s[18:19]
	s_nop 0
	v_addc_co_u32_e32 v9, vcc, 0, v1, vcc
	v_add_co_u32_e32 v10, vcc, s21, v0
	global_load_dword v148, v[4:5], off offset:-4096
	global_load_dword v145, v[4:5], off
	v_addc_co_u32_e32 v11, vcc, 0, v1, vcc
	v_add_co_u32_e32 v12, vcc, s22, v0
	global_load_dword v146, v[6:7], off
	s_nop 0
	v_addc_co_u32_e32 v13, vcc, 0, v1, vcc
	v_add_co_u32_e32 v14, vcc, s23, v0
	global_load_dword v144, v[10:11], off offset:-4096
	global_load_dword v142, v[10:11], off
	v_addc_co_u32_e32 v15, vcc, 0, v1, vcc
	v_add_co_u32_e32 v16, vcc, s28, v0
	global_load_dword v143, v[14:15], off offset:-4096
	global_load_dword v140, v[14:15], off
	v_addc_co_u32_e32 v17, vcc, 0, v1, vcc
	v_add_co_u32_e32 v18, vcc, s29, v0
	s_mov_b32 s6, 0x21000
	s_nop 0
	v_addc_co_u32_e32 v19, vcc, 0, v1, vcc
	v_add_co_u32_e32 v20, vcc, s42, v0
	global_load_dword v141, v[18:19], off offset:-4096
	global_load_dword v135, v[18:19], off
	v_addc_co_u32_e32 v21, vcc, 0, v1, vcc
	v_add_co_u32_e32 v22, vcc, s2, v0
	s_mov_b32 s2, 0x19000
	s_nop 0
	v_addc_co_u32_e32 v23, vcc, 0, v1, vcc
	v_add_co_u32_e32 v24, vcc, s68, v0
	s_mov_b32 s68, 0x1a000
	s_nop 0
	v_addc_co_u32_e32 v25, vcc, 0, v1, vcc
	v_add_co_u32_e32 v26, vcc, s2, v0
	global_load_dword v139, v[22:23], off offset:-4096
	global_load_dword v133, v[22:23], off
	v_addc_co_u32_e32 v27, vcc, 0, v1, vcc
	v_add_co_u32_e32 v28, vcc, s68, v0
	global_load_dword v134, v[26:27], off offset:-4096
	global_load_dword v131, v[26:27], off
	v_addc_co_u32_e32 v29, vcc, 0, v1, vcc
	v_add_co_u32_e32 v30, vcc, s3, v0
	s_mov_b32 s3, 0x20000
	s_nop 0
	v_addc_co_u32_e32 v31, vcc, 0, v1, vcc
	global_load_dword v132, v[30:31], off offset:-4096
	global_load_dword v130, v[30:31], off
	global_load_dword v129, v136, s[18:19] offset:128
	global_load_dword v128, v[2:3], off offset:128
	global_load_dword v127, v[4:5], off offset:128
	global_load_dword v126, v[6:7], off offset:128
	global_load_dword v125, v[8:9], off offset:128
	global_load_dword v124, v[10:11], off offset:128
	global_load_dword v123, v[12:13], off offset:128
	global_load_dword v122, v[14:15], off offset:128
	global_load_dword v121, v[16:17], off offset:128
	global_load_dword v120, v[18:19], off offset:128
	global_load_dword v119, v[20:21], off offset:128
	global_load_dword v117, v[22:23], off offset:128
	global_load_dword v116, v[24:25], off offset:128
	global_load_dword v115, v[26:27], off offset:128
	global_load_dword v114, v[28:29], off offset:128
	global_load_dword v113, v[30:31], off offset:128
	v_add_co_u32_e32 v2, vcc, s3, v0
	s_mov_b32 s12, 0x23000
	s_nop 0
	v_addc_co_u32_e32 v3, vcc, 0, v1, vcc
	v_add_co_u32_e32 v4, vcc, s6, v0
	s_mov_b32 s6, 0x22000
	s_nop 0
	v_addc_co_u32_e32 v5, vcc, 0, v1, vcc
	v_add_co_u32_e32 v6, vcc, s6, v0
	s_mov_b32 s8, 0x28000
	s_nop 0
	v_addc_co_u32_e32 v7, vcc, 0, v1, vcc
	v_add_co_u32_e32 v8, vcc, s12, v0
	s_mov_b32 s64, 0x2a000
	s_nop 0
	v_addc_co_u32_e32 v9, vcc, 0, v1, vcc
	v_add_co_u32_e32 v10, vcc, s8, v0
	s_mov_b32 s8, 0x29000
	s_nop 0
	v_addc_co_u32_e32 v11, vcc, 0, v1, vcc
	v_add_co_u32_e32 v12, vcc, s8, v0
	s_mov_b32 s65, 0x30000
	s_nop 0
	v_addc_co_u32_e32 v13, vcc, 0, v1, vcc
	v_add_co_u32_e32 v14, vcc, s64, v0
	s_mov_b32 s64, 0x2b000
	s_nop 0
	v_addc_co_u32_e32 v15, vcc, 0, v1, vcc
	v_add_co_u32_e32 v16, vcc, s64, v0
	s_mov_b32 s66, 0x32000
	s_nop 0
	v_addc_co_u32_e32 v17, vcc, 0, v1, vcc
	v_add_co_u32_e32 v18, vcc, s65, v0
	s_mov_b32 s65, 0x31000
	s_nop 0
	v_addc_co_u32_e32 v19, vcc, 0, v1, vcc
	v_add_co_u32_e32 v20, vcc, s65, v0
	s_mov_b32 s67, 0x38000
	s_nop 0
	v_addc_co_u32_e32 v21, vcc, 0, v1, vcc
	v_add_co_u32_e32 v22, vcc, s66, v0
	s_mov_b32 s66, 0x33000
	s_nop 0
	v_addc_co_u32_e32 v23, vcc, 0, v1, vcc
	v_add_co_u32_e32 v24, vcc, s66, v0
	global_load_dword v118, v[4:5], off offset:-4096
	global_load_dword v111, v[4:5], off
	v_addc_co_u32_e32 v25, vcc, 0, v1, vcc
	v_add_co_u32_e32 v26, vcc, s67, v0
	s_mov_b32 s67, 0x39000
	s_nop 0
	v_addc_co_u32_e32 v27, vcc, 0, v1, vcc
	v_add_co_u32_e32 v28, vcc, s67, v0
	global_load_dword v112, v[8:9], off offset:-4096
	global_load_dword v109, v[8:9], off
	v_addc_co_u32_e32 v29, vcc, 0, v1, vcc
	v_add_co_u32_e32 v30, vcc, s69, v0
	global_load_dword v110, v[12:13], off offset:-4096
	global_load_dword v107, v[12:13], off
	v_addc_co_u32_e32 v31, vcc, 0, v1, vcc
	v_add_co_u32_e32 v0, vcc, s71, v0
	global_load_dword v108, v[16:17], off offset:-4096
	global_load_dword v105, v[16:17], off
	v_addc_co_u32_e32 v1, vcc, 0, v1, vcc
	global_load_dword v106, v[20:21], off offset:-4096
	global_load_dword v103, v[20:21], off
	global_load_dword v104, v[24:25], off offset:-4096
	global_load_dword v101, v[24:25], off
	global_load_dword v102, v[28:29], off offset:-4096
	global_load_dword v99, v[28:29], off
; #define WAIT_V0() asm volatile("s_waitcnt vmcnt(0)" ::: "memory")
; DI int glds_row(int i) { const int tid = ltid(); return ((tid >> 6) * 4 + i) * 8 + ((tid & 63) >> 3); }
; DI int glds_chunk(int row) { return (ltid() & 7) ^ ((row >> 1) & 7); }
; DI void gemm_core(char* smem, int nk, const char* Ab, const char* Bb, const unsigned (&aoff)[4], const unsigned (&boff)[4],
;                   f32x16 (&acc)[2][2]) {
;     ...
;   auto stage = [&](int buf, int kt) __attribute__((always_inline)) {
;     const char* ak = Ab + kt * 128;
;     const char* bk = Bb + kt * 128;
;     char* sa = smem + buf * STAGE_B + w * 4096;
; #pragma unroll
;     for (int i = 0; i < 4; ++i) {
;       __builtin_amdgcn_global_load_lds((const unsigned*)(ak + aoff[i]), (unsigned*)(sa + i * 1024), 16, 0, 0);
;       __builtin_amdgcn_global_load_lds((const unsigned*)(bk + boff[i]), (unsigned*)(sa + 16384 + i * 1024), 16, 0, 0);
;     }
;   };
;   stage(0, 0);
;   WAIT_V0();
;   __syncthreads();
; DI void gemm_tile(char* smem, int nk, const bf16* A, int lda, int m0, const bf16* Bt, int ldb, int n0, f32x16 (&acc)[2][2]) {
;   unsigned aoff[4], boff[4];
; #pragma unroll
;   for (int i = 0; i < 4; ++i) {
;     const int row = glds_row(i), ch = glds_chunk(row);
;     aoff[i] = (unsigned)((row * lda + ch * 8) * 2);
;     boff[i] = (unsigned)((row * ldb + ch * 8) * 2);
;   }
;   gemm_core(smem, nk, (const char*)(A + (size_t)m0 * lda), (const char*)(Bt + (size_t)n0 * ldb), aoff, boff, acc);
; }
	global_load_dword v100, v[0:1], off offset:-4096
	global_load_dword v98, v[0:1], off
	global_load_dword v97, v[2:3], off offset:128
	global_load_dword v96, v[4:5], off offset:128
	global_load_dword v95, v[6:7], off offset:128
	global_load_dword v94, v[8:9], off offset:128
	global_load_dword v93, v[10:11], off offset:128
	global_load_dword v92, v[12:13], off offset:128
	global_load_dword v91, v[14:15], off offset:128
	global_load_dword v90, v[16:17], off offset:128
	global_load_dword v89, v[18:19], off offset:128
	global_load_dword v88, v[20:21], off offset:128
	global_load_dword v87, v[22:23], off offset:128
	global_load_dword v86, v[24:25], off offset:128
	global_load_dword v85, v[26:27], off offset:128
	global_load_dword v84, v[28:29], off offset:128
	global_load_dword v83, v[30:31], off offset:128
	global_load_dword v82, v[0:1], off offset:128
	v_mov_b32_e32 v0, v161
	s_ashr_i32 s1, s0, 31
	v_lshrrev_b32_e32 v1, 1, v0
	v_lshrrev_b32_e32 v2, 3, v0
	v_bfe_u32 v0, v0, 3, 3
	v_and_or_b32 v0, v1, s43, v0
	v_mov_b32_e32 v1, v161
	v_bfe_u32 v2, v2, 1, 2
	v_xor_b32_e32 v1, v2, v1
	v_lshlrev_b32_e32 v0, 11, v0
	v_lshlrev_b32_e32 v1, 4, v1
	v_and_or_b32 v2, v1, s92, v0
	v_mov_b32_e32 v0, v161
	s_lshl_b64 s[0:1], s[0:1], 11
	v_ashrrev_i32_e32 v1, 1, v0
	v_and_b32_e32 v1, 0xffffffe0, v1
	v_bfe_u32 v0, v0, 3, 3
	v_or3_b32 v0, v0, v1, 8
	v_mov_b32_e32 v1, v161
	v_lshrrev_b32_e32 v3, 1, v0
	v_xor_b32_e32 v1, v3, v1
	v_lshlrev_b32_e32 v0, 11, v0
	v_lshlrev_b32_e32 v1, 4, v1
	v_and_or_b32 v4, v1, s92, v0
	v_mov_b32_e32 v0, v161
	s_add_u32 s10, s4, s0
	v_lshrrev_b32_e32 v1, 1, v0
	v_lshrrev_b32_e32 v3, 3, v0
	v_bfe_u32 v0, v0, 3, 3
	v_and_or_b32 v0, v1, s43, v0
	v_mov_b32_e32 v1, v161
	v_bfe_u32 v3, v3, 1, 2
	v_xor_b32_e32 v1, v3, v1
	v_lshlrev_b32_e32 v1, 4, v1
	v_lshlrev_b32_e32 v0, 11, v0
	v_and_b32_e32 v1, 0x70, v1
	v_or3_b32 v6, v0, v1, s9
	v_mov_b32_e32 v0, v161
	s_addc_u32 s11, s5, s1
	v_ashrrev_i32_e32 v1, 1, v0
	v_and_b32_e32 v1, 0xffffffe0, v1
	v_bfe_u32 v0, v0, 3, 3
	v_or3_b32 v0, v0, v1, 24
	v_mov_b32_e32 v1, v161
	v_lshrrev_b32_e32 v3, 1, v0
	v_xor_b32_e32 v1, v3, v1
	v_lshlrev_b32_e32 v0, 11, v0
	v_lshlrev_b32_e32 v1, 4, v1
	v_and_or_b32 v0, v1, s92, v0
	v_mov_b32_e32 v1, v161
	s_lshl_b32 s0, s15, 11
	v_and_b32_e32 v3, 31, v1
	v_lshrrev_b32_e32 v5, 5, v1
	v_bfe_u32 v7, v1, 5, 1
	v_lshrrev_b32_e32 v8, 1, v1
	v_bfe_u32 v9, v1, 1, 3
	v_lshlrev_b32_e32 v10, 7, v1
	v_lshlrev_b32_e32 v1, 6, v1
	v_and_b32_e32 v154, 0xfffff000, v1
	v_readlane_b32 s1, v255, 6
	v_add_u32_e32 v151, 0x4000, v154
	v_readfirstlane_b32 s17, v154
	s_add_u32 s0, s1, s0
	v_readlane_b32 s1, v255, 5
	s_mov_b32 m0, s17
	v_readfirstlane_b32 s16, v151
	v_or_b32_e32 v160, 0x400, v154
	s_addc_u32 s1, s1, 0
	global_load_lds_dwordx4 v2, s[10:11]
	s_mov_b32 m0, s16
	v_readfirstlane_b32 s18, v160
	v_add_u32_e32 v159, 0x4400, v154
	global_load_lds_dwordx4 v2, s[0:1]
	s_mov_b32 m0, s18
	v_readfirstlane_b32 s19, v159
	v_or_b32_e32 v164, 0x800, v154
	global_load_lds_dwordx4 v4, s[10:11]
	s_mov_b32 m0, s19
	v_readfirstlane_b32 s21, v164
	v_add_u32_e32 v162, 0x4800, v154
	s_mov_b32 s12, 0x1ffffc0
	v_bitop3_b32 v5, v5, v9, 1 bitop3:0x6c
	global_load_lds_dwordx4 v4, s[0:1]
	s_mov_b32 m0, s21
	v_readfirstlane_b32 s20, v162
	v_or_b32_e32 v166, 0xc00, v154
	v_and_or_b32 v3, v8, s12, v3
	v_lshlrev_b32_e32 v8, 4, v5
	v_bitop3_b32 v5, v7, v9, 2 bitop3:0x36
	global_load_lds_dwordx4 v6, s[10:11]
	s_mov_b32 m0, s20
	v_readfirstlane_b32 s23, v166
	v_add_u32_e32 v168, 0x4c00, v154
	v_lshlrev_b32_e32 v153, 4, v5
	v_bitop3_b32 v5, v7, v9, 4 bitop3:0x36
	v_lshlrev_b32_e32 v157, 7, v3
	v_mov_b32_e32 v3, v137
	global_load_lds_dwordx4 v6, s[0:1]
	s_mov_b32 m0, s23
	v_readfirstlane_b32 s22, v168
	v_add_u32_e32 v172, 0x8000, v154
	v_lshlrev_b32_e32 v156, 4, v5
	v_bitop3_b32 v5, v7, v9, 6 bitop3:0x36
	v_lshl_add_u64 v[66:67], s[10:11], 0, v[2:3]
	v_mov_b32_e32 v1, v137
	global_load_lds_dwordx4 v0, s[10:11]
	s_mov_b32 m0, s22
	v_add_u32_e32 v170, 0xc000, v154
	v_readfirstlane_b32 s29, v172
	v_lshlrev_b32_e32 v158, 4, v5
	v_lshl_add_u64 v[64:65], s[0:1], 0, v[2:3]
	v_mov_b32_e32 v5, v137
	v_lshl_add_u64 v[76:77], s[10:11], 0, v[0:1]
	v_lshl_add_u64 v[78:79], s[0:1], 0, v[0:1]
	global_load_lds_dwordx4 v0, s[0:1]
	v_lshl_add_u64 v[0:1], v[66:67], 0, s[94:95]
	s_mov_b32 m0, s29
	v_readfirstlane_b32 s28, v170
	v_add_u32_e32 v174, 0x8400, v154
	v_lshl_add_u64 v[68:69], s[10:11], 0, v[4:5]
	v_mov_b32_e32 v7, v137
	global_load_lds_dwordx4 v[0:1], off
	v_lshl_add_u64 v[0:1], v[64:65], 0, s[94:95]
	s_mov_b32 m0, s28
	v_readfirstlane_b32 s42, v174
	v_add_u32_e32 v2, 0xc400, v154
	v_lshl_add_u64 v[70:71], s[0:1], 0, v[4:5]
	v_lshl_add_u64 v[72:73], s[0:1], 0, v[6:7]
	global_load_lds_dwordx4 v[0:1], off
	v_lshl_add_u64 v[0:1], v[68:69], 0, s[94:95]
	s_mov_b32 m0, s42
	v_readfirstlane_b32 s0, v2
	v_add_u32_e32 v2, 0x8800, v154
	v_lshl_add_u64 v[74:75], s[10:11], 0, v[6:7]
	global_load_lds_dwordx4 v[0:1], off
	v_lshl_add_u64 v[0:1], v[70:71], 0, s[94:95]
	s_mov_b32 m0, s0
	v_readfirstlane_b32 s1, v2
	v_add_u32_e32 v2, 0xc800, v154
	global_load_lds_dwordx4 v[0:1], off
	v_lshl_add_u64 v[0:1], v[74:75], 0, s[94:95]
	s_mov_b32 m0, s1
	v_readfirstlane_b32 s10, v2
	v_add_u32_e32 v2, 0x8c00, v154
	global_load_lds_dwordx4 v[0:1], off
	v_lshl_add_u64 v[0:1], v[72:73], 0, s[94:95]
	s_mov_b32 m0, s10
	v_readfirstlane_b32 s11, v2
	v_add_u32_e32 v2, 0xcc00, v154
	global_load_lds_dwordx4 v[0:1], off
	v_lshl_add_u64 v[0:1], v[76:77], 0, s[94:95]
	s_mov_b32 m0, s11
	v_readfirstlane_b32 s15, v2
	v_and_b32_e32 v176, 0x2f80, v10
	global_load_lds_dwordx4 v[0:1], off
	v_lshl_add_u64 v[0:1], v[78:79], 0, s[94:95]
	s_mov_b32 m0, s15
	v_or_b32_e32 v149, v157, v8
	global_load_lds_dwordx4 v[0:1], off
	s_waitcnt vmcnt(8)
	s_waitcnt vmcnt(8) lgkmcnt(0)
	s_barrier
; #define WAIT_V0() asm volatile("s_waitcnt vmcnt(0)" ::: "memory")
; DI void gemm_core(char* smem, int nk, const char* Ab, const char* Bb, const unsigned (&aoff)[4], const unsigned (&boff)[4],
;                   f32x16 (&acc)[2][2]) {
;     ...
;   auto stage = [&](int buf, int kt) __attribute__((always_inline)) {
;     const char* ak = Ab + kt * 128;
;     const char* bk = Bb + kt * 128;
;     char* sa = smem + buf * STAGE_B + w * 4096;
; #pragma unroll
;     for (int i = 0; i < 4; ++i) {
;       __builtin_amdgcn_global_load_lds((const unsigned*)(ak + aoff[i]), (unsigned*)(sa + i * 1024), 16, 0, 0);
;       __builtin_amdgcn_global_load_lds((const unsigned*)(bk + boff[i]), (unsigned*)(sa + 16384 + i * 1024), 16, 0, 0);
;     }
;   };
;     ...
;   for (int kt = 0; kt < nk; ++kt) {
;     const int cur = kt & 1;
;     if (kt + 1 < nk) stage(cur ^ 1, kt + 1);
;     const char* sb = smem + cur * STAGE_B;
; #pragma unroll
;     for (int ks = 0; ks < 4; ++ks) {
;       bf16x8 af[2], bfr[2];
; #pragma unroll
;       for (int mb = 0; mb < 2; ++mb) af[mb] = *(const bf16x8*)(sb + a_base + mb * 4096 + xo[ks]);
; #pragma unroll
;       for (int nb = 0; nb < 2; ++nb) bfr[nb] = *(const bf16x8*)(sb + b_base + nb * 4096 + xo[ks]);
; #pragma unroll
;       for (int mb = 0; mb < 2; ++mb)
; #pragma unroll
;         for (int nb = 0; nb < 2; ++nb)
;           acc[mb][nb] = __builtin_amdgcn_mfma_f32_32x32x16_bf16(af[mb], bfr[nb], acc[mb][nb], 0, 0, 0);
;     }
;     WAIT_V0();
;     __syncthreads();
;   }
	v_or_b32_e32 v150, v176, v8
	ds_read_b128 v[0:3], v149
	ds_read_b128 v[4:7], v149 offset:4096
	ds_read_b128 v[8:11], v150 offset:16384
	ds_read_b128 v[12:15], v150 offset:20480
	s_waitcnt lgkmcnt(0)
	v_mfma_f32_32x32x16_bf16 v[48:63], v[0:3], v[8:11], 0
	v_or_b32_e32 v152, v157, v153
	v_or_b32_e32 v153, v176, v153
	ds_read_b128 v[208:211], v152
	ds_read_b128 v[212:215], v152 offset:4096
	ds_read_b128 v[216:219], v153 offset:16384
	ds_read_b128 v[220:223], v153 offset:20480
	v_or_b32_e32 v155, v157, v156
	v_or_b32_e32 v156, v176, v156
	v_or_b32_e32 v157, v157, v158
	v_mfma_f32_32x32x16_bf16 v[32:47], v[0:3], v[12:15], 0
	v_or_b32_e32 v158, v176, v158
	s_mov_b32 m0, s17
	s_add_i32 s14, s14, s70
	s_add_i32 s13, s13, s7
	s_cmpk_gt_i32 s14, 0x7ff
	v_mfma_f32_32x32x16_bf16 v[16:31], v[4:7], v[8:11], 0
	v_mfma_f32_32x32x16_bf16 v[0:15], v[4:7], v[12:15], 0
	s_waitcnt lgkmcnt(0)
	v_mfma_f32_32x32x16_bf16 v[48:63], v[208:211], v[216:219], v[48:63]
	v_mfma_f32_32x32x16_bf16 v[32:47], v[208:211], v[220:223], v[32:47]
	v_mfma_f32_32x32x16_bf16 v[16:31], v[212:215], v[216:219], v[16:31]
	v_mfma_f32_32x32x16_bf16 v[0:15], v[212:215], v[220:223], v[0:15]
	ds_read_b128 v[208:211], v155
	ds_read_b128 v[212:215], v155 offset:4096
	ds_read_b128 v[216:219], v156 offset:16384
	ds_read_b128 v[220:223], v156 offset:20480
	s_waitcnt lgkmcnt(0)
	v_mfma_f32_32x32x16_bf16 v[48:63], v[208:211], v[216:219], v[48:63]
	v_mfma_f32_32x32x16_bf16 v[32:47], v[208:211], v[220:223], v[32:47]
	v_mfma_f32_32x32x16_bf16 v[16:31], v[212:215], v[216:219], v[16:31]
	v_mfma_f32_32x32x16_bf16 v[0:15], v[212:215], v[220:223], v[0:15]
	ds_read_b128 v[208:211], v157
	ds_read_b128 v[212:215], v157 offset:4096
	ds_read_b128 v[216:219], v158 offset:16384
	ds_read_b128 v[220:223], v158 offset:20480
	s_waitcnt vmcnt(0)
	s_waitcnt vmcnt(0) lgkmcnt(0)
	s_barrier
	v_mfma_f32_32x32x16_bf16 v[48:63], v[208:211], v[216:219], v[48:63]
	v_mfma_f32_32x32x16_bf16 v[32:47], v[208:211], v[220:223], v[32:47]
	v_mfma_f32_32x32x16_bf16 v[16:31], v[212:215], v[216:219], v[16:31]
	v_mfma_f32_32x32x16_bf16 v[0:15], v[212:215], v[220:223], v[0:15]
	ds_read_b128 v[208:211], v149 offset:32768
	ds_read_b128 v[212:215], v149 offset:36864
	ds_read_b128 v[216:219], v150 offset:49152
	ds_read_b128 v[220:223], v150 offset:53248
	v_lshl_add_u64 v[224:225], v[66:67], 0, s[90:91]
	global_load_lds_dwordx4 v[224:225], off
	v_lshl_add_u64 v[226:227], v[64:65], 0, s[90:91]
	s_mov_b32 m0, s16
	s_nop 0
	global_load_lds_dwordx4 v[226:227], off
	v_lshl_add_u64 v[224:225], v[68:69], 0, s[90:91]
	s_mov_b32 m0, s18
	s_nop 0
	global_load_lds_dwordx4 v[224:225], off
	v_lshl_add_u64 v[226:227], v[70:71], 0, s[90:91]
	s_mov_b32 m0, s19
	s_nop 0
	global_load_lds_dwordx4 v[226:227], off
	v_lshl_add_u64 v[224:225], v[74:75], 0, s[90:91]
	s_mov_b32 m0, s21
	s_nop 0
	global_load_lds_dwordx4 v[224:225], off
	v_lshl_add_u64 v[226:227], v[72:73], 0, s[90:91]
	s_mov_b32 m0, s20
	s_nop 0
	global_load_lds_dwordx4 v[226:227], off
	v_lshl_add_u64 v[224:225], v[76:77], 0, s[90:91]
	s_mov_b32 m0, s23
	s_nop 0
	global_load_lds_dwordx4 v[224:225], off
	v_lshl_add_u64 v[226:227], v[78:79], 0, s[90:91]
	s_mov_b32 m0, s22
	s_nop 0
	global_load_lds_dwordx4 v[226:227], off
	s_waitcnt lgkmcnt(0)
	v_mfma_f32_32x32x16_bf16 v[48:63], v[208:211], v[216:219], v[48:63]
	s_mov_b32 m0, s29
	v_mfma_f32_32x32x16_bf16 v[32:47], v[208:211], v[220:223], v[32:47]
	v_mfma_f32_32x32x16_bf16 v[16:31], v[212:215], v[216:219], v[16:31]
	v_mfma_f32_32x32x16_bf16 v[0:15], v[212:215], v[220:223], v[0:15]
	ds_read_b128 v[208:211], v152 offset:32768
	ds_read_b128 v[212:215], v152 offset:36864
	ds_read_b128 v[216:219], v153 offset:49152
	ds_read_b128 v[220:223], v153 offset:53248
	s_waitcnt lgkmcnt(0)
	v_mfma_f32_32x32x16_bf16 v[48:63], v[208:211], v[216:219], v[48:63]
	v_mfma_f32_32x32x16_bf16 v[32:47], v[208:211], v[220:223], v[32:47]
	v_mfma_f32_32x32x16_bf16 v[16:31], v[212:215], v[216:219], v[16:31]
	v_mfma_f32_32x32x16_bf16 v[0:15], v[212:215], v[220:223], v[0:15]
	ds_read_b128 v[208:211], v155 offset:32768
	ds_read_b128 v[212:215], v155 offset:36864
	ds_read_b128 v[216:219], v156 offset:49152
	ds_read_b128 v[220:223], v156 offset:53248
	s_waitcnt lgkmcnt(0)
	v_mfma_f32_32x32x16_bf16 v[48:63], v[208:211], v[216:219], v[48:63]
	v_mfma_f32_32x32x16_bf16 v[32:47], v[208:211], v[220:223], v[32:47]
	v_mfma_f32_32x32x16_bf16 v[16:31], v[212:215], v[216:219], v[16:31]
	v_mfma_f32_32x32x16_bf16 v[0:15], v[212:215], v[220:223], v[0:15]
	ds_read_b128 v[208:211], v157 offset:32768
	ds_read_b128 v[212:215], v157 offset:36864
	ds_read_b128 v[216:219], v158 offset:49152
	ds_read_b128 v[220:223], v158 offset:53248
	s_waitcnt vmcnt(0)
	s_waitcnt vmcnt(0) lgkmcnt(0)
	s_barrier
; #define WAIT_V0() asm volatile("s_waitcnt vmcnt(0)" ::: "memory")
; DI void gemm_core(char* smem, int nk, const char* Ab, const char* Bb, const unsigned (&aoff)[4], const unsigned (&boff)[4],
;                   f32x16 (&acc)[2][2]) {
;     ...
;   auto stage = [&](int buf, int kt) __attribute__((always_inline)) {
;     const char* ak = Ab + kt * 128;
;     const char* bk = Bb + kt * 128;
;     char* sa = smem + buf * STAGE_B + w * 4096;
; #pragma unroll
;     for (int i = 0; i < 4; ++i) {
;       __builtin_amdgcn_global_load_lds((const unsigned*)(ak + aoff[i]), (unsigned*)(sa + i * 1024), 16, 0, 0);
;       __builtin_amdgcn_global_load_lds((const unsigned*)(bk + boff[i]), (unsigned*)(sa + 16384 + i * 1024), 16, 0, 0);
;     }
;   };
;     ...
;   for (int kt = 0; kt < nk; ++kt) {
;     const int cur = kt & 1;
;     if (kt + 1 < nk) stage(cur ^ 1, kt + 1);
;     const char* sb = smem + cur * STAGE_B;
; #pragma unroll
;     for (int ks = 0; ks < 4; ++ks) {
;       bf16x8 af[2], bfr[2];
; #pragma unroll
;       for (int mb = 0; mb < 2; ++mb) af[mb] = *(const bf16x8*)(sb + a_base + mb * 4096 + xo[ks]);
; #pragma unroll
;       for (int nb = 0; nb < 2; ++nb) bfr[nb] = *(const bf16x8*)(sb + b_base + nb * 4096 + xo[ks]);
; #pragma unroll
;       for (int mb = 0; mb < 2; ++mb)
; #pragma unroll
;         for (int nb = 0; nb < 2; ++nb)
;           acc[mb][nb] = __builtin_amdgcn_mfma_f32_32x32x16_bf16(af[mb], bfr[nb], acc[mb][nb], 0, 0, 0);
;     }
;     WAIT_V0();
;     __syncthreads();
;   }
	v_mfma_f32_32x32x16_bf16 v[48:63], v[208:211], v[216:219], v[48:63]
	v_mfma_f32_32x32x16_bf16 v[32:47], v[208:211], v[220:223], v[32:47]
	v_mfma_f32_32x32x16_bf16 v[16:31], v[212:215], v[216:219], v[16:31]
	v_mfma_f32_32x32x16_bf16 v[0:15], v[212:215], v[220:223], v[0:15]
	ds_read_b128 v[208:211], v149
	ds_read_b128 v[212:215], v149 offset:4096
	ds_read_b128 v[216:219], v150 offset:16384
	ds_read_b128 v[220:223], v150 offset:20480
	v_lshl_add_u64 v[224:225], v[66:67], 0, s[40:41]
	global_load_lds_dwordx4 v[224:225], off
	v_lshl_add_u64 v[226:227], v[64:65], 0, s[40:41]
	s_mov_b32 m0, s28
	s_nop 0
	global_load_lds_dwordx4 v[226:227], off
	v_lshl_add_u64 v[224:225], v[68:69], 0, s[40:41]
	s_mov_b32 m0, s42
	s_nop 0
	global_load_lds_dwordx4 v[224:225], off
	v_lshl_add_u64 v[226:227], v[70:71], 0, s[40:41]
	s_mov_b32 m0, s0
	s_nop 0
	global_load_lds_dwordx4 v[226:227], off
	v_lshl_add_u64 v[224:225], v[74:75], 0, s[40:41]
	s_mov_b32 m0, s1
	s_nop 0
	global_load_lds_dwordx4 v[224:225], off
	v_lshl_add_u64 v[226:227], v[72:73], 0, s[40:41]
	s_mov_b32 m0, s10
	s_nop 0
	global_load_lds_dwordx4 v[226:227], off
	v_lshl_add_u64 v[224:225], v[76:77], 0, s[40:41]
	s_mov_b32 m0, s11
	s_nop 0
	global_load_lds_dwordx4 v[224:225], off
	v_lshl_add_u64 v[226:227], v[78:79], 0, s[40:41]
	s_mov_b32 m0, s15
	s_nop 0
	global_load_lds_dwordx4 v[226:227], off
	s_waitcnt lgkmcnt(0)
	v_mfma_f32_32x32x16_bf16 v[48:63], v[208:211], v[216:219], v[48:63]
	s_mov_b32 m0, s17
	v_mfma_f32_32x32x16_bf16 v[32:47], v[208:211], v[220:223], v[32:47]
	v_mfma_f32_32x32x16_bf16 v[16:31], v[212:215], v[216:219], v[16:31]
	v_mfma_f32_32x32x16_bf16 v[0:15], v[212:215], v[220:223], v[0:15]
	ds_read_b128 v[208:211], v152
	ds_read_b128 v[212:215], v152 offset:4096
	ds_read_b128 v[216:219], v153 offset:16384
	ds_read_b128 v[220:223], v153 offset:20480
	s_waitcnt lgkmcnt(0)
	v_mfma_f32_32x32x16_bf16 v[48:63], v[208:211], v[216:219], v[48:63]
	v_mfma_f32_32x32x16_bf16 v[32:47], v[208:211], v[220:223], v[32:47]
	v_mfma_f32_32x32x16_bf16 v[16:31], v[212:215], v[216:219], v[16:31]
	v_mfma_f32_32x32x16_bf16 v[0:15], v[212:215], v[220:223], v[0:15]
	ds_read_b128 v[208:211], v155
	ds_read_b128 v[212:215], v155 offset:4096
	ds_read_b128 v[216:219], v156 offset:16384
	ds_read_b128 v[220:223], v156 offset:20480
	s_waitcnt lgkmcnt(0)
	v_mfma_f32_32x32x16_bf16 v[48:63], v[208:211], v[216:219], v[48:63]
	v_mfma_f32_32x32x16_bf16 v[32:47], v[208:211], v[220:223], v[32:47]
	v_mfma_f32_32x32x16_bf16 v[16:31], v[212:215], v[216:219], v[16:31]
	v_mfma_f32_32x32x16_bf16 v[0:15], v[212:215], v[220:223], v[0:15]
	ds_read_b128 v[208:211], v157
	ds_read_b128 v[212:215], v157 offset:4096
	ds_read_b128 v[216:219], v158 offset:16384
	ds_read_b128 v[220:223], v158 offset:20480
	s_waitcnt vmcnt(0)
	s_waitcnt vmcnt(0) lgkmcnt(0)
	s_barrier
	v_mfma_f32_32x32x16_bf16 v[48:63], v[208:211], v[216:219], v[48:63]
	v_mfma_f32_32x32x16_bf16 v[32:47], v[208:211], v[220:223], v[32:47]
	v_mfma_f32_32x32x16_bf16 v[16:31], v[212:215], v[216:219], v[16:31]
	v_mfma_f32_32x32x16_bf16 v[0:15], v[212:215], v[220:223], v[0:15]
	ds_read_b128 v[208:211], v149 offset:32768
	ds_read_b128 v[212:215], v149 offset:36864
	ds_read_b128 v[216:219], v150 offset:49152
	ds_read_b128 v[220:223], v150 offset:53248
	v_lshl_add_u64 v[224:225], v[66:67], 0, s[30:31]
	global_load_lds_dwordx4 v[224:225], off
	v_lshl_add_u64 v[226:227], v[64:65], 0, s[30:31]
	s_mov_b32 m0, s16
	s_nop 0
	global_load_lds_dwordx4 v[226:227], off
	v_lshl_add_u64 v[224:225], v[68:69], 0, s[30:31]
	s_mov_b32 m0, s18
	s_nop 0
	global_load_lds_dwordx4 v[224:225], off
	v_lshl_add_u64 v[226:227], v[70:71], 0, s[30:31]
	s_mov_b32 m0, s19
	s_nop 0
	global_load_lds_dwordx4 v[226:227], off
	v_lshl_add_u64 v[224:225], v[74:75], 0, s[30:31]
	s_mov_b32 m0, s21
	s_nop 0
	global_load_lds_dwordx4 v[224:225], off
	v_lshl_add_u64 v[226:227], v[72:73], 0, s[30:31]
	s_mov_b32 m0, s20
	s_nop 0
	global_load_lds_dwordx4 v[226:227], off
	v_lshl_add_u64 v[224:225], v[76:77], 0, s[30:31]
	s_mov_b32 m0, s23
	s_nop 0
	global_load_lds_dwordx4 v[224:225], off
	v_lshl_add_u64 v[226:227], v[78:79], 0, s[30:31]
	s_mov_b32 m0, s22
	s_nop 0
	global_load_lds_dwordx4 v[226:227], off
	s_waitcnt lgkmcnt(0)
	v_mfma_f32_32x32x16_bf16 v[48:63], v[208:211], v[216:219], v[48:63]
	s_mov_b32 m0, s29
	v_mfma_f32_32x32x16_bf16 v[32:47], v[208:211], v[220:223], v[32:47]
	v_mfma_f32_32x32x16_bf16 v[16:31], v[212:215], v[216:219], v[16:31]
	v_mfma_f32_32x32x16_bf16 v[0:15], v[212:215], v[220:223], v[0:15]
	ds_read_b128 v[208:211], v152 offset:32768
	ds_read_b128 v[212:215], v152 offset:36864
	ds_read_b128 v[216:219], v153 offset:49152
	ds_read_b128 v[220:223], v153 offset:53248
	s_waitcnt lgkmcnt(0)
	v_mfma_f32_32x32x16_bf16 v[48:63], v[208:211], v[216:219], v[48:63]
	v_mfma_f32_32x32x16_bf16 v[32:47], v[208:211], v[220:223], v[32:47]
	v_mfma_f32_32x32x16_bf16 v[16:31], v[212:215], v[216:219], v[16:31]
	v_mfma_f32_32x32x16_bf16 v[0:15], v[212:215], v[220:223], v[0:15]
	ds_read_b128 v[208:211], v155 offset:32768
	ds_read_b128 v[212:215], v155 offset:36864
	ds_read_b128 v[216:219], v156 offset:49152
	ds_read_b128 v[220:223], v156 offset:53248
	s_waitcnt lgkmcnt(0)
	v_mfma_f32_32x32x16_bf16 v[48:63], v[208:211], v[216:219], v[48:63]
	v_mfma_f32_32x32x16_bf16 v[32:47], v[208:211], v[220:223], v[32:47]
	v_mfma_f32_32x32x16_bf16 v[16:31], v[212:215], v[216:219], v[16:31]
	v_mfma_f32_32x32x16_bf16 v[0:15], v[212:215], v[220:223], v[0:15]
	ds_read_b128 v[208:211], v157 offset:32768
	ds_read_b128 v[212:215], v157 offset:36864
	ds_read_b128 v[216:219], v158 offset:49152
	ds_read_b128 v[220:223], v158 offset:53248
	s_waitcnt vmcnt(0)
	s_waitcnt vmcnt(0) lgkmcnt(0)
	s_barrier
; #define WAIT_V0() asm volatile("s_waitcnt vmcnt(0)" ::: "memory")
; DI void gemm_core(char* smem, int nk, const char* Ab, const char* Bb, const unsigned (&aoff)[4], const unsigned (&boff)[4],
;                   f32x16 (&acc)[2][2]) {
;     ...
;   auto stage = [&](int buf, int kt) __attribute__((always_inline)) {
;     const char* ak = Ab + kt * 128;
;     const char* bk = Bb + kt * 128;
;     char* sa = smem + buf * STAGE_B + w * 4096;
; #pragma unroll
;     for (int i = 0; i < 4; ++i) {
;       __builtin_amdgcn_global_load_lds((const unsigned*)(ak + aoff[i]), (unsigned*)(sa + i * 1024), 16, 0, 0);
;       __builtin_amdgcn_global_load_lds((const unsigned*)(bk + boff[i]), (unsigned*)(sa + 16384 + i * 1024), 16, 0, 0);
;     }
;   };
;   stage(0, 0);
;   WAIT_V0();
;   __syncthreads();
;   for (int kt = 0; kt < nk; ++kt) {
;     const int cur = kt & 1;
;     if (kt + 1 < nk) stage(cur ^ 1, kt + 1);
;     const char* sb = smem + cur * STAGE_B;
; #pragma unroll
;     for (int ks = 0; ks < 4; ++ks) {
;       bf16x8 af[2], bfr[2];
; #pragma unroll
;       for (int mb = 0; mb < 2; ++mb) af[mb] = *(const bf16x8*)(sb + a_base + mb * 4096 + xo[ks]);
; #pragma unroll
;       for (int nb = 0; nb < 2; ++nb) bfr[nb] = *(const bf16x8*)(sb + b_base + nb * 4096 + xo[ks]);
; #pragma unroll
;       for (int mb = 0; mb < 2; ++mb)
; #pragma unroll
;         for (int nb = 0; nb < 2; ++nb)
;           acc[mb][nb] = __builtin_amdgcn_mfma_f32_32x32x16_bf16(af[mb], bfr[nb], acc[mb][nb], 0, 0, 0);
;     }
;     WAIT_V0();
;     __syncthreads();
;   }
	v_mfma_f32_32x32x16_bf16 v[48:63], v[208:211], v[216:219], v[48:63]
	v_mfma_f32_32x32x16_bf16 v[32:47], v[208:211], v[220:223], v[32:47]
	v_mfma_f32_32x32x16_bf16 v[16:31], v[212:215], v[216:219], v[16:31]
	v_mfma_f32_32x32x16_bf16 v[0:15], v[212:215], v[220:223], v[0:15]
	ds_read_b128 v[208:211], v149
	ds_read_b128 v[212:215], v149 offset:4096
	ds_read_b128 v[216:219], v150 offset:16384
	ds_read_b128 v[220:223], v150 offset:20480
	v_lshl_add_u64 v[224:225], v[66:67], 0, s[88:89]
	global_load_lds_dwordx4 v[224:225], off
	v_lshl_add_u64 v[226:227], v[64:65], 0, s[88:89]
	s_mov_b32 m0, s28
	s_nop 0
	global_load_lds_dwordx4 v[226:227], off
	v_lshl_add_u64 v[224:225], v[68:69], 0, s[88:89]
	s_mov_b32 m0, s42
	s_nop 0
	global_load_lds_dwordx4 v[224:225], off
	v_lshl_add_u64 v[226:227], v[70:71], 0, s[88:89]
	s_mov_b32 m0, s0
	s_nop 0
	global_load_lds_dwordx4 v[226:227], off
	v_lshl_add_u64 v[224:225], v[74:75], 0, s[88:89]
	s_mov_b32 m0, s1
	s_nop 0
	global_load_lds_dwordx4 v[224:225], off
	v_lshl_add_u64 v[226:227], v[72:73], 0, s[88:89]
	s_mov_b32 m0, s10
	s_nop 0
	global_load_lds_dwordx4 v[226:227], off
	v_lshl_add_u64 v[224:225], v[76:77], 0, s[88:89]
	s_mov_b32 m0, s11
	s_nop 0
	global_load_lds_dwordx4 v[224:225], off
	v_lshl_add_u64 v[226:227], v[78:79], 0, s[88:89]
	s_mov_b32 m0, s15
	s_nop 0
	global_load_lds_dwordx4 v[226:227], off
	s_waitcnt lgkmcnt(0)
	v_mfma_f32_32x32x16_bf16 v[48:63], v[208:211], v[216:219], v[48:63]
	s_mov_b32 m0, s17
	v_mfma_f32_32x32x16_bf16 v[32:47], v[208:211], v[220:223], v[32:47]
	v_mfma_f32_32x32x16_bf16 v[16:31], v[212:215], v[216:219], v[16:31]
	v_mfma_f32_32x32x16_bf16 v[0:15], v[212:215], v[220:223], v[0:15]
	ds_read_b128 v[208:211], v152
	ds_read_b128 v[212:215], v152 offset:4096
	ds_read_b128 v[216:219], v153 offset:16384
	ds_read_b128 v[220:223], v153 offset:20480
	s_waitcnt lgkmcnt(0)
	v_mfma_f32_32x32x16_bf16 v[48:63], v[208:211], v[216:219], v[48:63]
	v_mfma_f32_32x32x16_bf16 v[32:47], v[208:211], v[220:223], v[32:47]
	v_mfma_f32_32x32x16_bf16 v[16:31], v[212:215], v[216:219], v[16:31]
	v_mfma_f32_32x32x16_bf16 v[0:15], v[212:215], v[220:223], v[0:15]
	ds_read_b128 v[208:211], v155
	ds_read_b128 v[212:215], v155 offset:4096
	ds_read_b128 v[216:219], v156 offset:16384
	ds_read_b128 v[220:223], v156 offset:20480
	s_waitcnt lgkmcnt(0)
	v_mfma_f32_32x32x16_bf16 v[48:63], v[208:211], v[216:219], v[48:63]
	v_mfma_f32_32x32x16_bf16 v[32:47], v[208:211], v[220:223], v[32:47]
	v_mfma_f32_32x32x16_bf16 v[16:31], v[212:215], v[216:219], v[16:31]
	v_mfma_f32_32x32x16_bf16 v[0:15], v[212:215], v[220:223], v[0:15]
	ds_read_b128 v[208:211], v157
	ds_read_b128 v[212:215], v157 offset:4096
	ds_read_b128 v[216:219], v158 offset:16384
	ds_read_b128 v[220:223], v158 offset:20480
	s_waitcnt vmcnt(0)
	s_waitcnt vmcnt(0) lgkmcnt(0)
	s_barrier
	v_mfma_f32_32x32x16_bf16 v[48:63], v[208:211], v[216:219], v[48:63]
	v_mfma_f32_32x32x16_bf16 v[32:47], v[208:211], v[220:223], v[32:47]
	v_mfma_f32_32x32x16_bf16 v[16:31], v[212:215], v[216:219], v[16:31]
	v_mfma_f32_32x32x16_bf16 v[0:15], v[212:215], v[220:223], v[0:15]
	ds_read_b128 v[208:211], v149 offset:32768
	ds_read_b128 v[212:215], v149 offset:36864
	ds_read_b128 v[216:219], v150 offset:49152
	ds_read_b128 v[220:223], v150 offset:53248
	v_lshl_add_u64 v[224:225], v[66:67], 0, s[44:45]
	global_load_lds_dwordx4 v[224:225], off
	v_lshl_add_u64 v[226:227], v[64:65], 0, s[44:45]
	s_mov_b32 m0, s16
	s_nop 0
	global_load_lds_dwordx4 v[226:227], off
	v_lshl_add_u64 v[224:225], v[68:69], 0, s[44:45]
	s_mov_b32 m0, s18
	s_nop 0
	global_load_lds_dwordx4 v[224:225], off
	v_lshl_add_u64 v[226:227], v[70:71], 0, s[44:45]
	s_mov_b32 m0, s19
	s_nop 0
	global_load_lds_dwordx4 v[226:227], off
	v_lshl_add_u64 v[224:225], v[74:75], 0, s[44:45]
	s_mov_b32 m0, s21
	s_nop 0
	global_load_lds_dwordx4 v[224:225], off
	v_lshl_add_u64 v[226:227], v[72:73], 0, s[44:45]
	s_mov_b32 m0, s20
	s_nop 0
	global_load_lds_dwordx4 v[226:227], off
	v_lshl_add_u64 v[224:225], v[76:77], 0, s[44:45]
	s_mov_b32 m0, s23
	s_nop 0
	global_load_lds_dwordx4 v[224:225], off
	v_lshl_add_u64 v[226:227], v[78:79], 0, s[44:45]
	s_mov_b32 m0, s22
	s_nop 0
	global_load_lds_dwordx4 v[226:227], off
	s_waitcnt lgkmcnt(0)
	v_mfma_f32_32x32x16_bf16 v[48:63], v[208:211], v[216:219], v[48:63]
	s_mov_b32 m0, s29
	v_readfirstlane_b32 s29, v168
	v_mfma_f32_32x32x16_bf16 v[32:47], v[208:211], v[220:223], v[32:47]
	v_mfma_f32_32x32x16_bf16 v[16:31], v[212:215], v[216:219], v[16:31]
	v_mfma_f32_32x32x16_bf16 v[0:15], v[212:215], v[220:223], v[0:15]
	ds_read_b128 v[208:211], v152 offset:32768
	ds_read_b128 v[212:215], v152 offset:36864
	ds_read_b128 v[216:219], v153 offset:49152
	ds_read_b128 v[220:223], v153 offset:53248
	s_waitcnt lgkmcnt(0)
	v_mfma_f32_32x32x16_bf16 v[48:63], v[208:211], v[216:219], v[48:63]
	v_mfma_f32_32x32x16_bf16 v[32:47], v[208:211], v[220:223], v[32:47]
	v_mfma_f32_32x32x16_bf16 v[16:31], v[212:215], v[216:219], v[16:31]
	v_mfma_f32_32x32x16_bf16 v[0:15], v[212:215], v[220:223], v[0:15]
	ds_read_b128 v[208:211], v155 offset:32768
	ds_read_b128 v[212:215], v155 offset:36864
	ds_read_b128 v[216:219], v156 offset:49152
	ds_read_b128 v[220:223], v156 offset:53248
	s_waitcnt lgkmcnt(0)
	v_mfma_f32_32x32x16_bf16 v[48:63], v[208:211], v[216:219], v[48:63]
	v_mfma_f32_32x32x16_bf16 v[32:47], v[208:211], v[220:223], v[32:47]
	v_mfma_f32_32x32x16_bf16 v[16:31], v[212:215], v[216:219], v[16:31]
	v_mfma_f32_32x32x16_bf16 v[0:15], v[212:215], v[220:223], v[0:15]
	ds_read_b128 v[208:211], v157 offset:32768
	ds_read_b128 v[212:215], v157 offset:36864
	ds_read_b128 v[216:219], v158 offset:49152
	ds_read_b128 v[220:223], v158 offset:53248
	s_waitcnt vmcnt(0)
	s_waitcnt vmcnt(0) lgkmcnt(0)
	s_barrier
; #define WAIT_V0() asm volatile("s_waitcnt vmcnt(0)" ::: "memory")
; DI void gemm_core(char* smem, int nk, const char* Ab, const char* Bb, const unsigned (&aoff)[4], const unsigned (&boff)[4],
;                   f32x16 (&acc)[2][2]) {
;     ...
;   auto stage = [&](int buf, int kt) __attribute__((always_inline)) {
;     const char* ak = Ab + kt * 128;
;     const char* bk = Bb + kt * 128;
;     char* sa = smem + buf * STAGE_B + w * 4096;
; #pragma unroll
;     for (int i = 0; i < 4; ++i) {
;       __builtin_amdgcn_global_load_lds((const unsigned*)(ak + aoff[i]), (unsigned*)(sa + i * 1024), 16, 0, 0);
;       __builtin_amdgcn_global_load_lds((const unsigned*)(bk + boff[i]), (unsigned*)(sa + 16384 + i * 1024), 16, 0, 0);
;     }
;   };
;   stage(0, 0);
;   WAIT_V0();
;   __syncthreads();
;   for (int kt = 0; kt < nk; ++kt) {
;     const int cur = kt & 1;
;     if (kt + 1 < nk) stage(cur ^ 1, kt + 1);
;     const char* sb = smem + cur * STAGE_B;
; #pragma unroll
;     for (int ks = 0; ks < 4; ++ks) {
;       bf16x8 af[2], bfr[2];
; #pragma unroll
;       for (int mb = 0; mb < 2; ++mb) af[mb] = *(const bf16x8*)(sb + a_base + mb * 4096 + xo[ks]);
; #pragma unroll
;       for (int nb = 0; nb < 2; ++nb) bfr[nb] = *(const bf16x8*)(sb + b_base + nb * 4096 + xo[ks]);
; #pragma unroll
;       for (int mb = 0; mb < 2; ++mb)
; #pragma unroll
;         for (int nb = 0; nb < 2; ++nb)
;           acc[mb][nb] = __builtin_amdgcn_mfma_f32_32x32x16_bf16(af[mb], bfr[nb], acc[mb][nb], 0, 0, 0);
;     }
;     WAIT_V0();
;     __syncthreads();
;   }
	v_mfma_f32_32x32x16_bf16 v[48:63], v[208:211], v[216:219], v[48:63]
	v_mfma_f32_32x32x16_bf16 v[32:47], v[208:211], v[220:223], v[32:47]
	v_mfma_f32_32x32x16_bf16 v[16:31], v[212:215], v[216:219], v[16:31]
	v_mfma_f32_32x32x16_bf16 v[0:15], v[212:215], v[220:223], v[0:15]
	ds_read_b128 v[208:211], v149
	ds_read_b128 v[212:215], v149 offset:4096
	ds_read_b128 v[216:219], v150 offset:16384
	ds_read_b128 v[220:223], v150 offset:20480
	v_lshl_add_u64 v[224:225], v[66:67], 0, s[46:47]
	global_load_lds_dwordx4 v[224:225], off
	v_lshl_add_u64 v[226:227], v[64:65], 0, s[46:47]
	s_mov_b32 m0, s28
	v_readfirstlane_b32 s28, v162
	global_load_lds_dwordx4 v[226:227], off
	v_lshl_add_u64 v[224:225], v[68:69], 0, s[46:47]
	s_mov_b32 m0, s42
	s_nop 0
	global_load_lds_dwordx4 v[224:225], off
	v_lshl_add_u64 v[226:227], v[70:71], 0, s[46:47]
	s_mov_b32 m0, s0
	v_readfirstlane_b32 s42, v166
	global_load_lds_dwordx4 v[226:227], off
	v_lshl_add_u64 v[224:225], v[74:75], 0, s[46:47]
	s_mov_b32 m0, s1
	s_nop 0
	global_load_lds_dwordx4 v[224:225], off
	v_lshl_add_u64 v[226:227], v[72:73], 0, s[46:47]
	s_mov_b32 m0, s10
	s_nop 0
	global_load_lds_dwordx4 v[226:227], off
	v_lshl_add_u64 v[224:225], v[76:77], 0, s[46:47]
	s_mov_b32 m0, s11
	s_nop 0
	global_load_lds_dwordx4 v[224:225], off
	v_lshl_add_u64 v[226:227], v[78:79], 0, s[46:47]
	s_mov_b32 m0, s15
	s_nop 0
	global_load_lds_dwordx4 v[226:227], off
	s_waitcnt lgkmcnt(0)
	v_mfma_f32_32x32x16_bf16 v[48:63], v[208:211], v[216:219], v[48:63]
	s_mov_b32 m0, s17
	v_readfirstlane_b32 s17, v170
	v_mfma_f32_32x32x16_bf16 v[32:47], v[208:211], v[220:223], v[32:47]
	v_mfma_f32_32x32x16_bf16 v[16:31], v[212:215], v[216:219], v[16:31]
	v_mfma_f32_32x32x16_bf16 v[0:15], v[212:215], v[220:223], v[0:15]
	ds_read_b128 v[208:211], v152
	ds_read_b128 v[212:215], v152 offset:4096
	ds_read_b128 v[216:219], v153 offset:16384
	ds_read_b128 v[220:223], v153 offset:20480
	s_waitcnt lgkmcnt(0)
	v_mfma_f32_32x32x16_bf16 v[48:63], v[208:211], v[216:219], v[48:63]
	v_mfma_f32_32x32x16_bf16 v[32:47], v[208:211], v[220:223], v[32:47]
	v_mfma_f32_32x32x16_bf16 v[16:31], v[212:215], v[216:219], v[16:31]
	v_mfma_f32_32x32x16_bf16 v[0:15], v[212:215], v[220:223], v[0:15]
	ds_read_b128 v[208:211], v155
	ds_read_b128 v[212:215], v155 offset:4096
	ds_read_b128 v[216:219], v156 offset:16384
	ds_read_b128 v[220:223], v156 offset:20480
	s_waitcnt lgkmcnt(0)
	v_mfma_f32_32x32x16_bf16 v[48:63], v[208:211], v[216:219], v[48:63]
	v_mfma_f32_32x32x16_bf16 v[32:47], v[208:211], v[220:223], v[32:47]
	v_mfma_f32_32x32x16_bf16 v[16:31], v[212:215], v[216:219], v[16:31]
	v_mfma_f32_32x32x16_bf16 v[0:15], v[212:215], v[220:223], v[0:15]
	ds_read_b128 v[208:211], v157
	ds_read_b128 v[212:215], v157 offset:4096
	ds_read_b128 v[216:219], v158 offset:16384
	ds_read_b128 v[220:223], v158 offset:20480
	s_waitcnt vmcnt(0)
	s_waitcnt vmcnt(0) lgkmcnt(0)
	s_barrier
	v_mfma_f32_32x32x16_bf16 v[48:63], v[208:211], v[216:219], v[48:63]
	v_mfma_f32_32x32x16_bf16 v[32:47], v[208:211], v[220:223], v[32:47]
	v_mfma_f32_32x32x16_bf16 v[16:31], v[212:215], v[216:219], v[16:31]
	v_mfma_f32_32x32x16_bf16 v[0:15], v[212:215], v[220:223], v[0:15]
	ds_read_b128 v[208:211], v149 offset:32768
	ds_read_b128 v[212:215], v149 offset:36864
	ds_read_b128 v[216:219], v150 offset:49152
	ds_read_b128 v[220:223], v150 offset:53248
	v_lshl_add_u64 v[224:225], v[66:67], 0, s[48:49]
	global_load_lds_dwordx4 v[224:225], off
	v_lshl_add_u64 v[226:227], v[64:65], 0, s[48:49]
	s_mov_b32 m0, s16
	v_readfirstlane_b32 s16, v172
	global_load_lds_dwordx4 v[226:227], off
	v_lshl_add_u64 v[224:225], v[68:69], 0, s[48:49]
	s_mov_b32 m0, s18
	s_nop 0
	global_load_lds_dwordx4 v[224:225], off
	v_lshl_add_u64 v[226:227], v[70:71], 0, s[48:49]
	s_mov_b32 m0, s19
	v_readfirstlane_b32 s18, v174
	global_load_lds_dwordx4 v[226:227], off
	v_lshl_add_u64 v[224:225], v[74:75], 0, s[48:49]
	s_mov_b32 m0, s21
	s_nop 0
	global_load_lds_dwordx4 v[224:225], off
	v_lshl_add_u64 v[226:227], v[72:73], 0, s[48:49]
	s_mov_b32 m0, s20
	v_readfirstlane_b32 s19, v154
	global_load_lds_dwordx4 v[226:227], off
	v_lshl_add_u64 v[224:225], v[76:77], 0, s[48:49]
	s_mov_b32 m0, s23
	v_readfirstlane_b32 s20, v151
	global_load_lds_dwordx4 v[224:225], off
	v_lshl_add_u64 v[226:227], v[78:79], 0, s[48:49]
	s_mov_b32 m0, s22
	v_readfirstlane_b32 s21, v160
	global_load_lds_dwordx4 v[226:227], off
	s_waitcnt lgkmcnt(0)
	v_mfma_f32_32x32x16_bf16 v[48:63], v[208:211], v[216:219], v[48:63]
	s_mov_b32 m0, s16
	v_readfirstlane_b32 s22, v159
	v_readfirstlane_b32 s23, v164
	v_mfma_f32_32x32x16_bf16 v[32:47], v[208:211], v[220:223], v[32:47]
	v_mfma_f32_32x32x16_bf16 v[16:31], v[212:215], v[216:219], v[16:31]
	v_mfma_f32_32x32x16_bf16 v[0:15], v[212:215], v[220:223], v[0:15]
	ds_read_b128 v[208:211], v152 offset:32768
	ds_read_b128 v[212:215], v152 offset:36864
	ds_read_b128 v[216:219], v153 offset:49152
	ds_read_b128 v[220:223], v153 offset:53248
	s_waitcnt lgkmcnt(0)
	v_mfma_f32_32x32x16_bf16 v[48:63], v[208:211], v[216:219], v[48:63]
	v_mfma_f32_32x32x16_bf16 v[32:47], v[208:211], v[220:223], v[32:47]
	v_mfma_f32_32x32x16_bf16 v[16:31], v[212:215], v[216:219], v[16:31]
	v_mfma_f32_32x32x16_bf16 v[0:15], v[212:215], v[220:223], v[0:15]
	ds_read_b128 v[208:211], v155 offset:32768
	ds_read_b128 v[212:215], v155 offset:36864
	ds_read_b128 v[216:219], v156 offset:49152
	ds_read_b128 v[220:223], v156 offset:53248
	s_waitcnt lgkmcnt(0)
	v_mfma_f32_32x32x16_bf16 v[48:63], v[208:211], v[216:219], v[48:63]
	v_mfma_f32_32x32x16_bf16 v[32:47], v[208:211], v[220:223], v[32:47]
	v_mfma_f32_32x32x16_bf16 v[16:31], v[212:215], v[216:219], v[16:31]
	v_mfma_f32_32x32x16_bf16 v[0:15], v[212:215], v[220:223], v[0:15]
	ds_read_b128 v[208:211], v157 offset:32768
	ds_read_b128 v[212:215], v157 offset:36864
	ds_read_b128 v[216:219], v158 offset:49152
	ds_read_b128 v[220:223], v158 offset:53248
	s_waitcnt vmcnt(0)
	s_waitcnt vmcnt(0) lgkmcnt(0)
	s_barrier
; #define WAIT_V0() asm volatile("s_waitcnt vmcnt(0)" ::: "memory")
; DI void gemm_core(char* smem, int nk, const char* Ab, const char* Bb, const unsigned (&aoff)[4], const unsigned (&boff)[4],
;                   f32x16 (&acc)[2][2]) {
;     ...
;   auto stage = [&](int buf, int kt) __attribute__((always_inline)) {
;     const char* ak = Ab + kt * 128;
;     const char* bk = Bb + kt * 128;
;     char* sa = smem + buf * STAGE_B + w * 4096;
; #pragma unroll
;     for (int i = 0; i < 4; ++i) {
;       __builtin_amdgcn_global_load_lds((const unsigned*)(ak + aoff[i]), (unsigned*)(sa + i * 1024), 16, 0, 0);
;       __builtin_amdgcn_global_load_lds((const unsigned*)(bk + boff[i]), (unsigned*)(sa + 16384 + i * 1024), 16, 0, 0);
;     }
;   };
;   stage(0, 0);
;   WAIT_V0();
;   __syncthreads();
;   for (int kt = 0; kt < nk; ++kt) {
;     const int cur = kt & 1;
;     if (kt + 1 < nk) stage(cur ^ 1, kt + 1);
;     const char* sb = smem + cur * STAGE_B;
; #pragma unroll
;     for (int ks = 0; ks < 4; ++ks) {
;       bf16x8 af[2], bfr[2];
; #pragma unroll
;       for (int mb = 0; mb < 2; ++mb) af[mb] = *(const bf16x8*)(sb + a_base + mb * 4096 + xo[ks]);
; #pragma unroll
;       for (int nb = 0; nb < 2; ++nb) bfr[nb] = *(const bf16x8*)(sb + b_base + nb * 4096 + xo[ks]);
; #pragma unroll
;       for (int mb = 0; mb < 2; ++mb)
; #pragma unroll
;         for (int nb = 0; nb < 2; ++nb)
;           acc[mb][nb] = __builtin_amdgcn_mfma_f32_32x32x16_bf16(af[mb], bfr[nb], acc[mb][nb], 0, 0, 0);
;     }
;     WAIT_V0();
;     __syncthreads();
;   }
	v_mfma_f32_32x32x16_bf16 v[48:63], v[208:211], v[216:219], v[48:63]
	v_mfma_f32_32x32x16_bf16 v[32:47], v[208:211], v[220:223], v[32:47]
	v_mfma_f32_32x32x16_bf16 v[16:31], v[212:215], v[216:219], v[16:31]
	v_mfma_f32_32x32x16_bf16 v[0:15], v[212:215], v[220:223], v[0:15]
	ds_read_b128 v[208:211], v149
	ds_read_b128 v[212:215], v149 offset:4096
	ds_read_b128 v[216:219], v150 offset:16384
	ds_read_b128 v[220:223], v150 offset:20480
	v_lshl_add_u64 v[224:225], v[66:67], 0, s[50:51]
	global_load_lds_dwordx4 v[224:225], off
	v_lshl_add_u64 v[226:227], v[64:65], 0, s[50:51]
	s_mov_b32 m0, s17
	s_nop 0
	global_load_lds_dwordx4 v[226:227], off
	v_lshl_add_u64 v[224:225], v[68:69], 0, s[50:51]
	s_mov_b32 m0, s18
	s_nop 0
	global_load_lds_dwordx4 v[224:225], off
	v_lshl_add_u64 v[226:227], v[70:71], 0, s[50:51]
	s_mov_b32 m0, s0
	s_nop 0
	global_load_lds_dwordx4 v[226:227], off
	v_lshl_add_u64 v[224:225], v[74:75], 0, s[50:51]
	s_mov_b32 m0, s1
	s_nop 0
	global_load_lds_dwordx4 v[224:225], off
	v_lshl_add_u64 v[226:227], v[72:73], 0, s[50:51]
	s_mov_b32 m0, s10
	s_nop 0
	global_load_lds_dwordx4 v[226:227], off
	v_lshl_add_u64 v[224:225], v[76:77], 0, s[50:51]
	s_mov_b32 m0, s11
	s_nop 0
	global_load_lds_dwordx4 v[224:225], off
	v_lshl_add_u64 v[226:227], v[78:79], 0, s[50:51]
	s_mov_b32 m0, s15
	s_nop 0
	global_load_lds_dwordx4 v[226:227], off
	s_waitcnt lgkmcnt(0)
	v_mfma_f32_32x32x16_bf16 v[48:63], v[208:211], v[216:219], v[48:63]
	s_mov_b32 m0, s19
	v_mfma_f32_32x32x16_bf16 v[32:47], v[208:211], v[220:223], v[32:47]
	v_mfma_f32_32x32x16_bf16 v[16:31], v[212:215], v[216:219], v[16:31]
	v_mfma_f32_32x32x16_bf16 v[0:15], v[212:215], v[220:223], v[0:15]
	ds_read_b128 v[208:211], v152
	ds_read_b128 v[212:215], v152 offset:4096
	ds_read_b128 v[216:219], v153 offset:16384
	ds_read_b128 v[220:223], v153 offset:20480
	s_waitcnt lgkmcnt(0)
	v_mfma_f32_32x32x16_bf16 v[48:63], v[208:211], v[216:219], v[48:63]
	v_mfma_f32_32x32x16_bf16 v[32:47], v[208:211], v[220:223], v[32:47]
	v_mfma_f32_32x32x16_bf16 v[16:31], v[212:215], v[216:219], v[16:31]
	v_mfma_f32_32x32x16_bf16 v[0:15], v[212:215], v[220:223], v[0:15]
	ds_read_b128 v[208:211], v155
	ds_read_b128 v[212:215], v155 offset:4096
	ds_read_b128 v[216:219], v156 offset:16384
	ds_read_b128 v[220:223], v156 offset:20480
	s_waitcnt lgkmcnt(0)
	v_mfma_f32_32x32x16_bf16 v[48:63], v[208:211], v[216:219], v[48:63]
	v_mfma_f32_32x32x16_bf16 v[32:47], v[208:211], v[220:223], v[32:47]
	v_mfma_f32_32x32x16_bf16 v[16:31], v[212:215], v[216:219], v[16:31]
	v_mfma_f32_32x32x16_bf16 v[0:15], v[212:215], v[220:223], v[0:15]
	ds_read_b128 v[208:211], v157
	ds_read_b128 v[212:215], v157 offset:4096
	ds_read_b128 v[216:219], v158 offset:16384
	ds_read_b128 v[220:223], v158 offset:20480
	s_waitcnt vmcnt(0)
	s_waitcnt vmcnt(0) lgkmcnt(0)
	s_barrier
	v_mfma_f32_32x32x16_bf16 v[48:63], v[208:211], v[216:219], v[48:63]
	v_mfma_f32_32x32x16_bf16 v[32:47], v[208:211], v[220:223], v[32:47]
	v_mfma_f32_32x32x16_bf16 v[16:31], v[212:215], v[216:219], v[16:31]
	v_mfma_f32_32x32x16_bf16 v[0:15], v[212:215], v[220:223], v[0:15]
	ds_read_b128 v[208:211], v149 offset:32768
	ds_read_b128 v[212:215], v149 offset:36864
	ds_read_b128 v[216:219], v150 offset:49152
	ds_read_b128 v[220:223], v150 offset:53248
	v_lshl_add_u64 v[224:225], v[66:67], 0, s[52:53]
	global_load_lds_dwordx4 v[224:225], off
	v_lshl_add_u64 v[226:227], v[64:65], 0, s[52:53]
	s_mov_b32 m0, s20
	s_nop 0
	global_load_lds_dwordx4 v[226:227], off
	v_lshl_add_u64 v[224:225], v[68:69], 0, s[52:53]
	s_mov_b32 m0, s21
	s_nop 0
	global_load_lds_dwordx4 v[224:225], off
	v_lshl_add_u64 v[226:227], v[70:71], 0, s[52:53]
	s_mov_b32 m0, s22
	s_nop 0
	global_load_lds_dwordx4 v[226:227], off
	v_lshl_add_u64 v[224:225], v[74:75], 0, s[52:53]
	s_mov_b32 m0, s23
	s_nop 0
	global_load_lds_dwordx4 v[224:225], off
	v_lshl_add_u64 v[226:227], v[72:73], 0, s[52:53]
	s_mov_b32 m0, s28
	s_nop 0
	global_load_lds_dwordx4 v[226:227], off
	v_lshl_add_u64 v[224:225], v[76:77], 0, s[52:53]
	s_mov_b32 m0, s42
	s_nop 0
	global_load_lds_dwordx4 v[224:225], off
	v_lshl_add_u64 v[226:227], v[78:79], 0, s[52:53]
	s_mov_b32 m0, s29
	s_nop 0
	global_load_lds_dwordx4 v[226:227], off
	s_waitcnt lgkmcnt(0)
	v_mfma_f32_32x32x16_bf16 v[48:63], v[208:211], v[216:219], v[48:63]
	s_mov_b32 m0, s16
	v_mfma_f32_32x32x16_bf16 v[32:47], v[208:211], v[220:223], v[32:47]
	v_mfma_f32_32x32x16_bf16 v[16:31], v[212:215], v[216:219], v[16:31]
	v_mfma_f32_32x32x16_bf16 v[0:15], v[212:215], v[220:223], v[0:15]
	ds_read_b128 v[208:211], v152 offset:32768
	ds_read_b128 v[212:215], v152 offset:36864
	ds_read_b128 v[216:219], v153 offset:49152
	ds_read_b128 v[220:223], v153 offset:53248
	s_waitcnt lgkmcnt(0)
	v_mfma_f32_32x32x16_bf16 v[48:63], v[208:211], v[216:219], v[48:63]
	v_mfma_f32_32x32x16_bf16 v[32:47], v[208:211], v[220:223], v[32:47]
	v_mfma_f32_32x32x16_bf16 v[16:31], v[212:215], v[216:219], v[16:31]
	v_mfma_f32_32x32x16_bf16 v[0:15], v[212:215], v[220:223], v[0:15]
	ds_read_b128 v[208:211], v155 offset:32768
	ds_read_b128 v[212:215], v155 offset:36864
	ds_read_b128 v[216:219], v156 offset:49152
	ds_read_b128 v[220:223], v156 offset:53248
	s_waitcnt lgkmcnt(0)
	v_mfma_f32_32x32x16_bf16 v[48:63], v[208:211], v[216:219], v[48:63]
	v_mfma_f32_32x32x16_bf16 v[32:47], v[208:211], v[220:223], v[32:47]
	v_mfma_f32_32x32x16_bf16 v[16:31], v[212:215], v[216:219], v[16:31]
	v_mfma_f32_32x32x16_bf16 v[0:15], v[212:215], v[220:223], v[0:15]
	ds_read_b128 v[208:211], v157 offset:32768
	ds_read_b128 v[212:215], v157 offset:36864
	ds_read_b128 v[216:219], v158 offset:49152
	ds_read_b128 v[220:223], v158 offset:53248
	s_waitcnt vmcnt(0)
	s_waitcnt vmcnt(0) lgkmcnt(0)
	s_barrier
; #define WAIT_V0() asm volatile("s_waitcnt vmcnt(0)" ::: "memory")
; DI void gemm_core(char* smem, int nk, const char* Ab, const char* Bb, const unsigned (&aoff)[4], const unsigned (&boff)[4],
;                   f32x16 (&acc)[2][2]) {
;     ...
;   auto stage = [&](int buf, int kt) __attribute__((always_inline)) {
;     const char* ak = Ab + kt * 128;
;     const char* bk = Bb + kt * 128;
;     char* sa = smem + buf * STAGE_B + w * 4096;
; #pragma unroll
;     for (int i = 0; i < 4; ++i) {
;       __builtin_amdgcn_global_load_lds((const unsigned*)(ak + aoff[i]), (unsigned*)(sa + i * 1024), 16, 0, 0);
;       __builtin_amdgcn_global_load_lds((const unsigned*)(bk + boff[i]), (unsigned*)(sa + 16384 + i * 1024), 16, 0, 0);
;     }
;   };
;   stage(0, 0);
;   WAIT_V0();
;   __syncthreads();
;   for (int kt = 0; kt < nk; ++kt) {
;     const int cur = kt & 1;
;     if (kt + 1 < nk) stage(cur ^ 1, kt + 1);
;     const char* sb = smem + cur * STAGE_B;
; #pragma unroll
;     for (int ks = 0; ks < 4; ++ks) {
;       bf16x8 af[2], bfr[2];
; #pragma unroll
;       for (int mb = 0; mb < 2; ++mb) af[mb] = *(const bf16x8*)(sb + a_base + mb * 4096 + xo[ks]);
; #pragma unroll
;       for (int nb = 0; nb < 2; ++nb) bfr[nb] = *(const bf16x8*)(sb + b_base + nb * 4096 + xo[ks]);
; #pragma unroll
;       for (int mb = 0; mb < 2; ++mb)
; #pragma unroll
;         for (int nb = 0; nb < 2; ++nb)
;           acc[mb][nb] = __builtin_amdgcn_mfma_f32_32x32x16_bf16(af[mb], bfr[nb], acc[mb][nb], 0, 0, 0);
;     }
;     WAIT_V0();
;     __syncthreads();
;   }
	v_mfma_f32_32x32x16_bf16 v[48:63], v[208:211], v[216:219], v[48:63]
	v_mfma_f32_32x32x16_bf16 v[32:47], v[208:211], v[220:223], v[32:47]
	v_mfma_f32_32x32x16_bf16 v[16:31], v[212:215], v[216:219], v[16:31]
	v_mfma_f32_32x32x16_bf16 v[0:15], v[212:215], v[220:223], v[0:15]
	ds_read_b128 v[208:211], v149
	ds_read_b128 v[212:215], v149 offset:4096
	ds_read_b128 v[216:219], v150 offset:16384
	ds_read_b128 v[220:223], v150 offset:20480
	v_lshl_add_u64 v[224:225], v[66:67], 0, s[54:55]
	global_load_lds_dwordx4 v[224:225], off
	v_lshl_add_u64 v[226:227], v[64:65], 0, s[54:55]
	s_mov_b32 m0, s17
	s_nop 0
	global_load_lds_dwordx4 v[226:227], off
	v_lshl_add_u64 v[224:225], v[68:69], 0, s[54:55]
	s_mov_b32 m0, s18
	s_nop 0
	global_load_lds_dwordx4 v[224:225], off
	v_lshl_add_u64 v[226:227], v[70:71], 0, s[54:55]
	s_mov_b32 m0, s0
	s_nop 0
	global_load_lds_dwordx4 v[226:227], off
	v_lshl_add_u64 v[224:225], v[74:75], 0, s[54:55]
	s_mov_b32 m0, s1
	s_nop 0
	global_load_lds_dwordx4 v[224:225], off
	v_lshl_add_u64 v[226:227], v[72:73], 0, s[54:55]
	s_mov_b32 m0, s10
	s_nop 0
	global_load_lds_dwordx4 v[226:227], off
	v_lshl_add_u64 v[224:225], v[76:77], 0, s[54:55]
	s_mov_b32 m0, s11
	s_nop 0
	global_load_lds_dwordx4 v[224:225], off
	v_lshl_add_u64 v[226:227], v[78:79], 0, s[54:55]
	s_mov_b32 m0, s15
	s_nop 0
	global_load_lds_dwordx4 v[226:227], off
	s_waitcnt lgkmcnt(0)
	v_mfma_f32_32x32x16_bf16 v[48:63], v[208:211], v[216:219], v[48:63]
	s_mov_b32 m0, s19
	v_mfma_f32_32x32x16_bf16 v[32:47], v[208:211], v[220:223], v[32:47]
	v_mfma_f32_32x32x16_bf16 v[16:31], v[212:215], v[216:219], v[16:31]
	v_mfma_f32_32x32x16_bf16 v[0:15], v[212:215], v[220:223], v[0:15]
	ds_read_b128 v[208:211], v152
	ds_read_b128 v[212:215], v152 offset:4096
	ds_read_b128 v[216:219], v153 offset:16384
	ds_read_b128 v[220:223], v153 offset:20480
	s_waitcnt lgkmcnt(0)
	v_mfma_f32_32x32x16_bf16 v[48:63], v[208:211], v[216:219], v[48:63]
	v_mfma_f32_32x32x16_bf16 v[32:47], v[208:211], v[220:223], v[32:47]
	v_mfma_f32_32x32x16_bf16 v[16:31], v[212:215], v[216:219], v[16:31]
	v_mfma_f32_32x32x16_bf16 v[0:15], v[212:215], v[220:223], v[0:15]
	ds_read_b128 v[208:211], v155
	ds_read_b128 v[212:215], v155 offset:4096
	ds_read_b128 v[216:219], v156 offset:16384
	ds_read_b128 v[220:223], v156 offset:20480
	s_waitcnt lgkmcnt(0)
	v_mfma_f32_32x32x16_bf16 v[48:63], v[208:211], v[216:219], v[48:63]
	v_mfma_f32_32x32x16_bf16 v[32:47], v[208:211], v[220:223], v[32:47]
	v_mfma_f32_32x32x16_bf16 v[16:31], v[212:215], v[216:219], v[16:31]
	v_mfma_f32_32x32x16_bf16 v[0:15], v[212:215], v[220:223], v[0:15]
	ds_read_b128 v[208:211], v157
	ds_read_b128 v[212:215], v157 offset:4096
	ds_read_b128 v[216:219], v158 offset:16384
	ds_read_b128 v[220:223], v158 offset:20480
	s_waitcnt vmcnt(0)
	s_waitcnt vmcnt(0) lgkmcnt(0)
	s_barrier
	v_mfma_f32_32x32x16_bf16 v[48:63], v[208:211], v[216:219], v[48:63]
	v_mfma_f32_32x32x16_bf16 v[32:47], v[208:211], v[220:223], v[32:47]
	v_mfma_f32_32x32x16_bf16 v[16:31], v[212:215], v[216:219], v[16:31]
	v_mfma_f32_32x32x16_bf16 v[0:15], v[212:215], v[220:223], v[0:15]
	ds_read_b128 v[208:211], v149 offset:32768
	ds_read_b128 v[212:215], v149 offset:36864
	ds_read_b128 v[216:219], v150 offset:49152
	ds_read_b128 v[220:223], v150 offset:53248
	v_lshl_add_u64 v[224:225], v[66:67], 0, s[56:57]
	global_load_lds_dwordx4 v[224:225], off
	v_lshl_add_u64 v[226:227], v[64:65], 0, s[56:57]
	s_mov_b32 m0, s20
	s_nop 0
	global_load_lds_dwordx4 v[226:227], off
	v_lshl_add_u64 v[224:225], v[68:69], 0, s[56:57]
	s_mov_b32 m0, s21
	s_nop 0
	global_load_lds_dwordx4 v[224:225], off
	v_lshl_add_u64 v[226:227], v[70:71], 0, s[56:57]
	s_mov_b32 m0, s22
	s_nop 0
	global_load_lds_dwordx4 v[226:227], off
	v_lshl_add_u64 v[224:225], v[74:75], 0, s[56:57]
	s_mov_b32 m0, s23
	s_nop 0
	global_load_lds_dwordx4 v[224:225], off
	v_lshl_add_u64 v[226:227], v[72:73], 0, s[56:57]
	s_mov_b32 m0, s28
	s_nop 0
	global_load_lds_dwordx4 v[226:227], off
	v_lshl_add_u64 v[224:225], v[76:77], 0, s[56:57]
	s_mov_b32 m0, s42
	s_nop 0
	global_load_lds_dwordx4 v[224:225], off
	v_lshl_add_u64 v[226:227], v[78:79], 0, s[56:57]
	s_mov_b32 m0, s29
	s_nop 0
	global_load_lds_dwordx4 v[226:227], off
	s_waitcnt lgkmcnt(0)
	v_mfma_f32_32x32x16_bf16 v[48:63], v[208:211], v[216:219], v[48:63]
	s_mov_b32 m0, s16
	v_mfma_f32_32x32x16_bf16 v[32:47], v[208:211], v[220:223], v[32:47]
	v_mfma_f32_32x32x16_bf16 v[16:31], v[212:215], v[216:219], v[16:31]
	v_mfma_f32_32x32x16_bf16 v[0:15], v[212:215], v[220:223], v[0:15]
	ds_read_b128 v[208:211], v152 offset:32768
	ds_read_b128 v[212:215], v152 offset:36864
	ds_read_b128 v[216:219], v153 offset:49152
	ds_read_b128 v[220:223], v153 offset:53248
	s_waitcnt lgkmcnt(0)
	v_mfma_f32_32x32x16_bf16 v[48:63], v[208:211], v[216:219], v[48:63]
	v_mfma_f32_32x32x16_bf16 v[32:47], v[208:211], v[220:223], v[32:47]
	v_mfma_f32_32x32x16_bf16 v[16:31], v[212:215], v[216:219], v[16:31]
	v_mfma_f32_32x32x16_bf16 v[0:15], v[212:215], v[220:223], v[0:15]
	ds_read_b128 v[208:211], v155 offset:32768
	ds_read_b128 v[212:215], v155 offset:36864
	ds_read_b128 v[216:219], v156 offset:49152
	ds_read_b128 v[220:223], v156 offset:53248
	s_waitcnt lgkmcnt(0)
	v_mfma_f32_32x32x16_bf16 v[48:63], v[208:211], v[216:219], v[48:63]
	v_mfma_f32_32x32x16_bf16 v[32:47], v[208:211], v[220:223], v[32:47]
	v_mfma_f32_32x32x16_bf16 v[16:31], v[212:215], v[216:219], v[16:31]
	v_mfma_f32_32x32x16_bf16 v[0:15], v[212:215], v[220:223], v[0:15]
	ds_read_b128 v[208:211], v157 offset:32768
	ds_read_b128 v[212:215], v157 offset:36864
	ds_read_b128 v[216:219], v158 offset:49152
	ds_read_b128 v[220:223], v158 offset:53248
	s_waitcnt vmcnt(0)
	s_waitcnt vmcnt(0) lgkmcnt(0)
	s_barrier
; #define WAIT_V0() asm volatile("s_waitcnt vmcnt(0)" ::: "memory")
; DI void gemm_core(char* smem, int nk, const char* Ab, const char* Bb, const unsigned (&aoff)[4], const unsigned (&boff)[4],
;                   f32x16 (&acc)[2][2]) {
;     ...
;   auto stage = [&](int buf, int kt) __attribute__((always_inline)) {
;     const char* ak = Ab + kt * 128;
;     const char* bk = Bb + kt * 128;
;     char* sa = smem + buf * STAGE_B + w * 4096;
; #pragma unroll
;     for (int i = 0; i < 4; ++i) {
;       __builtin_amdgcn_global_load_lds((const unsigned*)(ak + aoff[i]), (unsigned*)(sa + i * 1024), 16, 0, 0);
;       __builtin_amdgcn_global_load_lds((const unsigned*)(bk + boff[i]), (unsigned*)(sa + 16384 + i * 1024), 16, 0, 0);
;     }
;   };
;   stage(0, 0);
;   WAIT_V0();
;   __syncthreads();
;   for (int kt = 0; kt < nk; ++kt) {
;     const int cur = kt & 1;
;     if (kt + 1 < nk) stage(cur ^ 1, kt + 1);
;     const char* sb = smem + cur * STAGE_B;
; #pragma unroll
;     for (int ks = 0; ks < 4; ++ks) {
;       bf16x8 af[2], bfr[2];
; #pragma unroll
;       for (int mb = 0; mb < 2; ++mb) af[mb] = *(const bf16x8*)(sb + a_base + mb * 4096 + xo[ks]);
; #pragma unroll
;       for (int nb = 0; nb < 2; ++nb) bfr[nb] = *(const bf16x8*)(sb + b_base + nb * 4096 + xo[ks]);
; #pragma unroll
;       for (int mb = 0; mb < 2; ++mb)
; #pragma unroll
;         for (int nb = 0; nb < 2; ++nb)
;           acc[mb][nb] = __builtin_amdgcn_mfma_f32_32x32x16_bf16(af[mb], bfr[nb], acc[mb][nb], 0, 0, 0);
;     }
;     WAIT_V0();
;     __syncthreads();
;   }
	v_mfma_f32_32x32x16_bf16 v[48:63], v[208:211], v[216:219], v[48:63]
	v_mfma_f32_32x32x16_bf16 v[32:47], v[208:211], v[220:223], v[32:47]
	v_mfma_f32_32x32x16_bf16 v[16:31], v[212:215], v[216:219], v[16:31]
	v_mfma_f32_32x32x16_bf16 v[0:15], v[212:215], v[220:223], v[0:15]
	ds_read_b128 v[208:211], v149
	ds_read_b128 v[212:215], v149 offset:4096
	ds_read_b128 v[216:219], v150 offset:16384
	ds_read_b128 v[220:223], v150 offset:20480
	v_lshl_add_u64 v[224:225], v[66:67], 0, s[58:59]
	global_load_lds_dwordx4 v[224:225], off
	v_lshl_add_u64 v[226:227], v[64:65], 0, s[58:59]
	s_mov_b32 m0, s17
	s_nop 0
	global_load_lds_dwordx4 v[226:227], off
	v_lshl_add_u64 v[224:225], v[68:69], 0, s[58:59]
	s_mov_b32 m0, s18
	s_nop 0
	global_load_lds_dwordx4 v[224:225], off
	v_lshl_add_u64 v[226:227], v[70:71], 0, s[58:59]
	s_mov_b32 m0, s0
	s_nop 0
	global_load_lds_dwordx4 v[226:227], off
	v_lshl_add_u64 v[224:225], v[74:75], 0, s[58:59]
	s_mov_b32 m0, s1
	s_nop 0
	global_load_lds_dwordx4 v[224:225], off
	v_lshl_add_u64 v[226:227], v[72:73], 0, s[58:59]
	s_mov_b32 m0, s10
	s_nop 0
	global_load_lds_dwordx4 v[226:227], off
	v_lshl_add_u64 v[224:225], v[76:77], 0, s[58:59]
	s_mov_b32 m0, s11
	s_nop 0
	global_load_lds_dwordx4 v[224:225], off
	v_lshl_add_u64 v[226:227], v[78:79], 0, s[58:59]
	s_mov_b32 m0, s15
	s_nop 0
	global_load_lds_dwordx4 v[226:227], off
	s_waitcnt lgkmcnt(0)
	v_mfma_f32_32x32x16_bf16 v[48:63], v[208:211], v[216:219], v[48:63]
	s_mov_b32 m0, s19
	v_mfma_f32_32x32x16_bf16 v[32:47], v[208:211], v[220:223], v[32:47]
	v_mfma_f32_32x32x16_bf16 v[16:31], v[212:215], v[216:219], v[16:31]
	v_mfma_f32_32x32x16_bf16 v[0:15], v[212:215], v[220:223], v[0:15]
	ds_read_b128 v[208:211], v152
	ds_read_b128 v[212:215], v152 offset:4096
	ds_read_b128 v[216:219], v153 offset:16384
	ds_read_b128 v[220:223], v153 offset:20480
	s_waitcnt lgkmcnt(0)
	v_mfma_f32_32x32x16_bf16 v[48:63], v[208:211], v[216:219], v[48:63]
	v_mfma_f32_32x32x16_bf16 v[32:47], v[208:211], v[220:223], v[32:47]
	v_mfma_f32_32x32x16_bf16 v[16:31], v[212:215], v[216:219], v[16:31]
	v_mfma_f32_32x32x16_bf16 v[0:15], v[212:215], v[220:223], v[0:15]
	ds_read_b128 v[208:211], v155
	ds_read_b128 v[212:215], v155 offset:4096
	ds_read_b128 v[216:219], v156 offset:16384
	ds_read_b128 v[220:223], v156 offset:20480
	s_waitcnt lgkmcnt(0)
	v_mfma_f32_32x32x16_bf16 v[48:63], v[208:211], v[216:219], v[48:63]
	v_mfma_f32_32x32x16_bf16 v[32:47], v[208:211], v[220:223], v[32:47]
	v_mfma_f32_32x32x16_bf16 v[16:31], v[212:215], v[216:219], v[16:31]
	v_mfma_f32_32x32x16_bf16 v[0:15], v[212:215], v[220:223], v[0:15]
	ds_read_b128 v[208:211], v157
	ds_read_b128 v[212:215], v157 offset:4096
	ds_read_b128 v[216:219], v158 offset:16384
	ds_read_b128 v[220:223], v158 offset:20480
	s_waitcnt vmcnt(0)
	s_waitcnt vmcnt(0) lgkmcnt(0)
	s_barrier
	v_mfma_f32_32x32x16_bf16 v[48:63], v[208:211], v[216:219], v[48:63]
	v_mfma_f32_32x32x16_bf16 v[32:47], v[208:211], v[220:223], v[32:47]
	v_lshl_add_u64 v[208:209], v[66:67], 0, s[60:61]
	global_load_lds_dwordx4 v[208:209], off
	v_lshl_add_u64 v[208:209], v[64:65], 0, s[60:61]
	s_mov_b32 m0, s20
	v_lshl_add_u64 v[66:67], v[66:67], 0, s[62:63]
	global_load_lds_dwordx4 v[208:209], off
	v_lshl_add_u64 v[208:209], v[68:69], 0, s[60:61]
	s_mov_b32 m0, s21
	v_mfma_f32_32x32x16_bf16 v[16:31], v[212:215], v[216:219], v[16:31]
	global_load_lds_dwordx4 v[208:209], off
	v_lshl_add_u64 v[208:209], v[70:71], 0, s[60:61]
	s_mov_b32 m0, s22
	v_lshl_add_u64 v[64:65], v[64:65], 0, s[62:63]
	global_load_lds_dwordx4 v[208:209], off
	v_lshl_add_u64 v[208:209], v[74:75], 0, s[60:61]
	s_mov_b32 m0, s23
	v_mfma_f32_32x32x16_bf16 v[0:15], v[212:215], v[220:223], v[0:15]
	global_load_lds_dwordx4 v[208:209], off
	v_lshl_add_u64 v[208:209], v[72:73], 0, s[60:61]
	s_mov_b32 m0, s28
	s_movk_i32 s20, 0x3000
	global_load_lds_dwordx4 v[208:209], off
	v_lshl_add_u64 v[208:209], v[76:77], 0, s[60:61]
	s_mov_b32 m0, s42
	s_mov_b32 s21, 0x9000
	global_load_lds_dwordx4 v[208:209], off
	v_lshl_add_u64 v[208:209], v[78:79], 0, s[60:61]
	s_mov_b32 m0, s29
	s_mov_b32 s22, 0xa000
	global_load_lds_dwordx4 v[208:209], off
	ds_read_b128 v[208:211], v149 offset:32768
	ds_read_b128 v[212:215], v149 offset:36864
	ds_read_b128 v[216:219], v150 offset:49152
	ds_read_b128 v[220:223], v150 offset:53248
	s_waitcnt lgkmcnt(0)
	v_mfma_f32_32x32x16_bf16 v[48:63], v[208:211], v[216:219], v[48:63]
	s_mov_b32 m0, s16
	s_movk_i32 s16, 0x2000
	s_mov_b32 s23, 0xb000
	s_mov_b32 s28, 0x10000
	s_mov_b32 s29, 0x11000
	s_mov_b32 s42, 0x12000
	v_mfma_f32_32x32x16_bf16 v[32:47], v[208:211], v[220:223], v[32:47]
	v_mfma_f32_32x32x16_bf16 v[16:31], v[212:215], v[216:219], v[16:31]
	v_mfma_f32_32x32x16_bf16 v[0:15], v[212:215], v[220:223], v[0:15]
	ds_read_b128 v[208:211], v152 offset:32768
	ds_read_b128 v[212:215], v152 offset:36864
	ds_read_b128 v[216:219], v153 offset:49152
	ds_read_b128 v[220:223], v153 offset:53248
	s_waitcnt lgkmcnt(0)
	v_mfma_f32_32x32x16_bf16 v[48:63], v[208:211], v[216:219], v[48:63]
	v_mfma_f32_32x32x16_bf16 v[32:47], v[208:211], v[220:223], v[32:47]
	v_mfma_f32_32x32x16_bf16 v[16:31], v[212:215], v[216:219], v[16:31]
	v_mfma_f32_32x32x16_bf16 v[0:15], v[212:215], v[220:223], v[0:15]
	ds_read_b128 v[208:211], v155 offset:32768
	ds_read_b128 v[212:215], v155 offset:36864
	ds_read_b128 v[216:219], v156 offset:49152
	ds_read_b128 v[220:223], v156 offset:53248
	s_waitcnt lgkmcnt(0)
	v_mfma_f32_32x32x16_bf16 v[48:63], v[208:211], v[216:219], v[48:63]
	v_mfma_f32_32x32x16_bf16 v[32:47], v[208:211], v[220:223], v[32:47]
	v_mfma_f32_32x32x16_bf16 v[16:31], v[212:215], v[216:219], v[16:31]
	v_mfma_f32_32x32x16_bf16 v[0:15], v[212:215], v[220:223], v[0:15]
	ds_read_b128 v[208:211], v157 offset:32768
	ds_read_b128 v[212:215], v157 offset:36864
	ds_read_b128 v[216:219], v158 offset:49152
	ds_read_b128 v[220:223], v158 offset:53248
	s_waitcnt vmcnt(0)
	s_waitcnt vmcnt(0) lgkmcnt(0)
	s_barrier
; #define WAIT_V0() asm volatile("s_waitcnt vmcnt(0)" ::: "memory")
; DI void gemm_core(char* smem, int nk, const char* Ab, const char* Bb, const unsigned (&aoff)[4], const unsigned (&boff)[4],
;                   f32x16 (&acc)[2][2]) {
;     ...
;   for (int kt = 0; kt < nk; ++kt) {
;     const int cur = kt & 1;
;     if (kt + 1 < nk) stage(cur ^ 1, kt + 1);
;     const char* sb = smem + cur * STAGE_B;
; #pragma unroll
;     for (int ks = 0; ks < 4; ++ks) {
;       bf16x8 af[2], bfr[2];
; #pragma unroll
;       for (int mb = 0; mb < 2; ++mb) af[mb] = *(const bf16x8*)(sb + a_base + mb * 4096 + xo[ks]);
; #pragma unroll
;       for (int nb = 0; nb < 2; ++nb) bfr[nb] = *(const bf16x8*)(sb + b_base + nb * 4096 + xo[ks]);
; #pragma unroll
;       for (int mb = 0; mb < 2; ++mb)
; #pragma unroll
;         for (int nb = 0; nb < 2; ++nb)
;           acc[mb][nb] = __builtin_amdgcn_mfma_f32_32x32x16_bf16(af[mb], bfr[nb], acc[mb][nb], 0, 0, 0);
;     }
;     WAIT_V0();
;     __syncthreads();
;   }
	global_load_lds_dwordx4 v[66:67], off
	s_mov_b32 m0, s17
	v_mfma_f32_32x32x16_bf16 v[48:63], v[208:211], v[216:219], v[48:63]
	global_load_lds_dwordx4 v[64:65], off
	v_lshl_add_u64 v[64:65], v[68:69], 0, s[62:63]
	s_mov_b32 m0, s18
	s_movk_i32 s17, 0x1000
	global_load_lds_dwordx4 v[64:65], off
	v_lshl_add_u64 v[64:65], v[70:71], 0, s[62:63]
	s_mov_b32 m0, s0
	v_mfma_f32_32x32x16_bf16 v[32:47], v[208:211], v[220:223], v[32:47]
	global_load_lds_dwordx4 v[64:65], off
	v_lshl_add_u64 v[64:65], v[74:75], 0, s[62:63]
	s_mov_b32 m0, s1
	s_mov_b32 s0, 0x13000
	global_load_lds_dwordx4 v[64:65], off
	v_lshl_add_u64 v[64:65], v[72:73], 0, s[62:63]
	s_mov_b32 m0, s10
	v_mfma_f32_32x32x16_bf16 v[16:31], v[212:215], v[216:219], v[16:31]
	global_load_lds_dwordx4 v[64:65], off
	v_lshl_add_u64 v[64:65], v[76:77], 0, s[62:63]
	s_mov_b32 m0, s11
	s_mov_b32 s1, 0x18000
	global_load_lds_dwordx4 v[64:65], off
	v_lshl_add_u64 v[64:65], v[78:79], 0, s[62:63]
	s_mov_b32 m0, s15
	v_mfma_f32_32x32x16_bf16 v[0:15], v[212:215], v[220:223], v[0:15]
	global_load_lds_dwordx4 v[64:65], off
	ds_read_b128 v[64:67], v149
	ds_read_b128 v[68:71], v149 offset:4096
	ds_read_b128 v[72:75], v150 offset:16384
	ds_read_b128 v[76:79], v150 offset:20480
	s_mov_b32 s10, 0x1b000
	v_readlane_b32 s18, v255, 3
	v_readlane_b32 s19, v255, 4
	s_waitcnt lgkmcnt(0)
	v_mfma_f32_32x32x16_bf16 v[48:63], v[64:67], v[72:75], v[48:63]
	v_mfma_f32_32x32x16_bf16 v[32:47], v[64:67], v[76:79], v[32:47]
	v_mfma_f32_32x32x16_bf16 v[16:31], v[68:71], v[72:75], v[16:31]
	v_mfma_f32_32x32x16_bf16 v[0:15], v[68:71], v[76:79], v[0:15]
	ds_read_b128 v[64:67], v152
	ds_read_b128 v[68:71], v152 offset:4096
	ds_read_b128 v[72:75], v153 offset:16384
	ds_read_b128 v[76:79], v153 offset:20480
	s_waitcnt lgkmcnt(0)
	v_mfma_f32_32x32x16_bf16 v[48:63], v[64:67], v[72:75], v[48:63]
	v_mfma_f32_32x32x16_bf16 v[32:47], v[64:67], v[76:79], v[32:47]
	v_mfma_f32_32x32x16_bf16 v[16:31], v[68:71], v[72:75], v[16:31]
	v_mfma_f32_32x32x16_bf16 v[0:15], v[68:71], v[76:79], v[0:15]
	ds_read_b128 v[64:67], v155
	ds_read_b128 v[68:71], v155 offset:4096
	ds_read_b128 v[72:75], v156 offset:16384
	ds_read_b128 v[76:79], v156 offset:20480
	s_waitcnt lgkmcnt(0)
	v_mfma_f32_32x32x16_bf16 v[48:63], v[64:67], v[72:75], v[48:63]
	v_mfma_f32_32x32x16_bf16 v[32:47], v[64:67], v[76:79], v[32:47]
	v_mfma_f32_32x32x16_bf16 v[16:31], v[68:71], v[72:75], v[16:31]
	v_mfma_f32_32x32x16_bf16 v[0:15], v[68:71], v[76:79], v[0:15]
	ds_read_b128 v[64:67], v157
	ds_read_b128 v[68:71], v157 offset:4096
	ds_read_b128 v[72:75], v158 offset:16384
	ds_read_b128 v[76:79], v158 offset:20480
	s_waitcnt vmcnt(0)
	s_waitcnt vmcnt(0) lgkmcnt(0)
	s_barrier
	v_mfma_f32_32x32x16_bf16 v[48:63], v[64:67], v[72:75], v[48:63]
	v_mfma_f32_32x32x16_bf16 v[32:47], v[64:67], v[76:79], v[32:47]
	v_mfma_f32_32x32x16_bf16 v[16:31], v[68:71], v[72:75], v[16:31]
	v_mfma_f32_32x32x16_bf16 v[0:15], v[68:71], v[76:79], v[0:15]
	ds_read_b128 v[64:67], v149 offset:32768
	ds_read_b128 v[68:71], v149 offset:36864
	ds_read_b128 v[72:75], v150 offset:49152
	ds_read_b128 v[76:79], v150 offset:53248
	s_waitcnt lgkmcnt(1)
	v_mfma_f32_32x32x16_bf16 v[48:63], v[64:67], v[72:75], v[48:63]
	s_waitcnt lgkmcnt(0)
	v_mfma_f32_32x32x16_bf16 v[32:47], v[64:67], v[76:79], v[32:47]
	v_mfma_f32_32x32x16_bf16 v[16:31], v[68:71], v[72:75], v[16:31]
	v_mfma_f32_32x32x16_bf16 v[0:15], v[68:71], v[76:79], v[0:15]
	ds_read_b128 v[64:67], v152 offset:32768
	ds_read_b128 v[68:71], v152 offset:36864
	ds_read_b128 v[72:75], v153 offset:49152
	ds_read_b128 v[76:79], v153 offset:53248
	s_waitcnt lgkmcnt(1)
	v_mfma_f32_32x32x16_bf16 v[48:63], v[64:67], v[72:75], v[48:63]
	s_waitcnt lgkmcnt(0)
	v_mfma_f32_32x32x16_bf16 v[32:47], v[64:67], v[76:79], v[32:47]
	v_mfma_f32_32x32x16_bf16 v[16:31], v[68:71], v[72:75], v[16:31]
	v_mfma_f32_32x32x16_bf16 v[0:15], v[68:71], v[76:79], v[0:15]
	ds_read_b128 v[64:67], v155 offset:32768
	ds_read_b128 v[68:71], v155 offset:36864
	ds_read_b128 v[72:75], v156 offset:49152
	ds_read_b128 v[76:79], v156 offset:53248
	s_waitcnt lgkmcnt(1)
	v_mfma_f32_32x32x16_bf16 v[48:63], v[64:67], v[72:75], v[48:63]
	s_waitcnt lgkmcnt(0)
	v_mfma_f32_32x32x16_bf16 v[32:47], v[64:67], v[76:79], v[32:47]
	v_mfma_f32_32x32x16_bf16 v[16:31], v[68:71], v[72:75], v[16:31]
	v_mfma_f32_32x32x16_bf16 v[0:15], v[68:71], v[76:79], v[0:15]
	ds_read_b128 v[64:67], v157 offset:32768
	ds_read_b128 v[68:71], v157 offset:36864
	ds_read_b128 v[72:75], v158 offset:49152
	ds_read_b128 v[76:79], v158 offset:53248
	s_waitcnt vmcnt(0)
	s_waitcnt lgkmcnt(0)
	s_barrier
; template <class T> DI T* uoff(T* base, unsigned byteoff) { return (T*)((char*)base + byteoff); }
; template <class T> DI const T* uoff(const T* base, unsigned byteoff) { return (const T*)((const char*)base + byteoff); }
; DI void phase_out(const Params& P, int layer, const float* xin, char* smem) {
;     ...
; #pragma unroll
;     for (int mb = 0; mb < 2; ++mb)
; #pragma unroll
;       for (int nb = 0; nb < 2; ++nb)
; #pragma unroll
;         for (int r = 0; r < 16; ++r)
;           (*uoff(P.out + ((mb * 32 + (r & 3) + 8 * (r >> 2)) * 1024 + nb * 32), obase_b)) = xr[mb][nb][r] + acc[mb][nb][r];
	v_mfma_f32_32x32x16_bf16 v[48:63], v[64:67], v[72:75], v[48:63]
	v_mfma_f32_32x32x16_bf16 v[32:47], v[64:67], v[76:79], v[32:47]
	v_lshl_add_u64 v[64:65], s[82:83], 0, v[136:137]
	s_nop 9
	v_add_f32_e32 v48, v147, v48
	global_store_dword v136, v48, s[82:83]
	v_add_co_u32_e32 v48, vcc, s17, v64
	v_add_f32_e32 v50, v145, v50
	v_add_f32_e32 v52, v144, v52
	v_mfma_f32_32x32x16_bf16 v[16:31], v[68:71], v[72:75], v[16:31]
	v_add_f32_e32 v54, v143, v54
	v_add_f32_e32 v56, v141, v56
	v_add_f32_e32 v32, v129, v32
	global_store_dword v136, v32, s[82:83] offset:128
	v_add_f32_e32 v32, v128, v33
	v_add_f32_e32 v58, v139, v58
	v_add_f32_e32 v60, v134, v60
	v_mfma_f32_32x32x16_bf16 v[0:15], v[68:71], v[76:79], v[0:15]
	v_add_f32_e32 v68, v148, v49
	v_addc_co_u32_e32 v49, vcc, 0, v65, vcc
	v_add_co_u32_e32 v66, vcc, s16, v64
	global_store_dword v[48:49], v32, off offset:128
	s_nop 0
	v_addc_co_u32_e32 v67, vcc, 0, v65, vcc
	global_store_dword v[66:67], v50, off
	v_add_co_u32_e32 v50, vcc, s20, v64
	global_store_dword v[66:67], v68, off offset:-4096
	v_add_f32_e32 v68, v146, v51
	v_addc_co_u32_e32 v51, vcc, 0, v65, vcc
	global_store_dword v[50:51], v68, off
	v_add_co_u32_e32 v68, vcc, s9, v64
	v_add_f32_e32 v32, v127, v34
	s_nop 0
	v_addc_co_u32_e32 v69, vcc, 0, v65, vcc
	v_add_co_u32_e32 v70, vcc, s21, v64
	global_store_dword v[66:67], v32, off offset:128
	s_nop 0
	v_addc_co_u32_e32 v71, vcc, 0, v65, vcc
	global_store_dword v[70:71], v52, off offset:-4096
	v_add_f32_e32 v52, v142, v53
	global_store_dword v[70:71], v52, off
	v_add_co_u32_e32 v52, vcc, s22, v64
	v_add_f32_e32 v32, v126, v35
	s_nop 0
	v_addc_co_u32_e32 v53, vcc, 0, v65, vcc
	v_add_co_u32_e32 v72, vcc, s23, v64
	global_store_dword v[50:51], v32, off offset:128
	s_nop 0
	v_addc_co_u32_e32 v73, vcc, 0, v65, vcc
	global_store_dword v[72:73], v54, off offset:-4096
	v_add_f32_e32 v54, v140, v55
	global_store_dword v[72:73], v54, off
	v_add_co_u32_e32 v54, vcc, s28, v64
	v_add_f32_e32 v32, v125, v36
	s_nop 0
	v_addc_co_u32_e32 v55, vcc, 0, v65, vcc
	v_add_co_u32_e32 v74, vcc, s29, v64
	global_store_dword v[68:69], v32, off offset:128
	s_nop 0
	v_addc_co_u32_e32 v75, vcc, 0, v65, vcc
	global_store_dword v[74:75], v56, off offset:-4096
	v_add_f32_e32 v56, v135, v57
	global_store_dword v[74:75], v56, off
	v_add_co_u32_e32 v56, vcc, s42, v64
	v_add_f32_e32 v32, v124, v37
	s_nop 0
	v_addc_co_u32_e32 v57, vcc, 0, v65, vcc
	v_add_co_u32_e32 v76, vcc, s0, v64
	global_store_dword v[70:71], v32, off offset:128
	s_nop 0
	v_addc_co_u32_e32 v77, vcc, 0, v65, vcc
	global_store_dword v[76:77], v58, off offset:-4096
	v_add_f32_e32 v58, v133, v59
	v_add_f32_e32 v32, v123, v38
	global_store_dword v[76:77], v58, off
	v_add_co_u32_e32 v58, vcc, s1, v64
	global_store_dword v[52:53], v32, off offset:128
	v_add_f32_e32 v32, v122, v39
	v_addc_co_u32_e32 v59, vcc, 0, v65, vcc
	global_store_dword v[72:73], v32, off offset:128
	v_add_f32_e32 v32, v121, v40
	v_add_co_u32_e32 v78, vcc, s2, v64
	global_store_dword v[54:55], v32, off offset:128
	v_add_f32_e32 v32, v120, v41
	v_addc_co_u32_e32 v79, vcc, 0, v65, vcc
	global_store_dword v[74:75], v32, off offset:128
	v_add_f32_e32 v32, v119, v42
	global_store_dword v[78:79], v60, off offset:-4096
	v_add_f32_e32 v60, v131, v61
	global_store_dword v[56:57], v32, off offset:128
	v_add_f32_e32 v32, v117, v43
	global_store_dword v[78:79], v60, off
	v_add_co_u32_e32 v60, vcc, s68, v64
	global_store_dword v[76:77], v32, off offset:128
	v_add_f32_e32 v32, v116, v44
	v_addc_co_u32_e32 v61, vcc, 0, v65, vcc
	global_store_dword v[58:59], v32, off offset:128
	v_add_f32_e32 v32, v115, v45
	v_add_f32_e32 v62, v132, v62
	v_add_co_u32_e32 v132, vcc, s10, v64
	global_store_dword v[78:79], v32, off offset:128
	v_add_f32_e32 v32, v114, v46
	v_addc_co_u32_e32 v133, vcc, 0, v65, vcc
	global_store_dword v[60:61], v32, off offset:128
	v_add_f32_e32 v32, v113, v47
	global_store_dword v[132:133], v32, off offset:128
	v_add_co_u32_e32 v32, vcc, s3, v64
	s_mov_b32 s0, 0x21000
	s_nop 0
; template <class T> DI T* uoff(T* base, unsigned byteoff) { return (T*)((char*)base + byteoff); }
; template <class T> DI const T* uoff(const T* base, unsigned byteoff) { return (const T*)((const char*)base + byteoff); }
; DI void phase_out(const Params& P, int layer, const float* xin, char* smem) {
;     ...
; #pragma unroll
;     for (int mb = 0; mb < 2; ++mb)
; #pragma unroll
;       for (int nb = 0; nb < 2; ++nb)
; #pragma unroll
;         for (int r = 0; r < 16; ++r)
;           (*uoff(P.out + ((mb * 32 + (r & 3) + 8 * (r >> 2)) * 1024 + nb * 32), obase_b)) = xr[mb][nb][r] + acc[mb][nb][r];
;   }
	v_addc_co_u32_e32 v33, vcc, 0, v65, vcc
	v_add_co_u32_e32 v34, vcc, s0, v64
	v_add_f32_e32 v16, v118, v16
	s_nop 0
	v_addc_co_u32_e32 v35, vcc, 0, v65, vcc
	global_store_dword v[34:35], v16, off offset:-4096
	v_add_f32_e32 v16, v111, v17
	global_store_dword v[34:35], v16, off
	v_add_co_u32_e32 v16, vcc, s6, v64
	s_mov_b32 s1, 0x23000
	s_nop 0
	v_addc_co_u32_e32 v17, vcc, 0, v65, vcc
	v_add_co_u32_e32 v36, vcc, s1, v64
	v_add_f32_e32 v18, v112, v18
	s_nop 0
	v_addc_co_u32_e32 v37, vcc, 0, v65, vcc
	s_mov_b32 s2, 0x28000
	global_store_dword v[36:37], v18, off offset:-4096
	v_add_f32_e32 v18, v109, v19
	global_store_dword v[36:37], v18, off
	v_add_co_u32_e32 v18, vcc, s2, v64
	v_add_f32_e32 v20, v110, v20
	s_nop 0
	v_addc_co_u32_e32 v19, vcc, 0, v65, vcc
	v_add_co_u32_e32 v38, vcc, s8, v64
	s_mov_b32 s3, 0x2a000
	s_nop 0
	v_addc_co_u32_e32 v39, vcc, 0, v65, vcc
	global_store_dword v[38:39], v20, off offset:-4096
	v_add_f32_e32 v20, v107, v21
	global_store_dword v[38:39], v20, off
	v_add_co_u32_e32 v20, vcc, s3, v64
	v_add_f32_e32 v22, v108, v22
	s_nop 0
	v_addc_co_u32_e32 v21, vcc, 0, v65, vcc
	v_add_co_u32_e32 v40, vcc, s64, v64
	s_mov_b32 s0, 0x30000
	s_nop 0
	v_addc_co_u32_e32 v41, vcc, 0, v65, vcc
	global_store_dword v[40:41], v22, off offset:-4096
	v_add_f32_e32 v22, v105, v23
	global_store_dword v[40:41], v22, off
	v_add_co_u32_e32 v22, vcc, s0, v64
	v_add_f32_e32 v24, v106, v24
	s_nop 0
	v_addc_co_u32_e32 v23, vcc, 0, v65, vcc
	v_add_co_u32_e32 v42, vcc, s65, v64
	s_mov_b32 s1, 0x32000
	s_nop 0
	v_addc_co_u32_e32 v43, vcc, 0, v65, vcc
	global_store_dword v[42:43], v24, off offset:-4096
	v_add_f32_e32 v24, v103, v25
	v_add_f32_e32 v0, v97, v0
	global_store_dword v[42:43], v24, off
	v_add_co_u32_e32 v24, vcc, s1, v64
	global_store_dword v[32:33], v0, off offset:128
	v_add_f32_e32 v0, v96, v1
	v_addc_co_u32_e32 v25, vcc, 0, v65, vcc
	global_store_dword v[34:35], v0, off offset:128
	v_add_f32_e32 v0, v95, v2
	v_add_co_u32_e32 v44, vcc, s66, v64
	global_store_dword v[16:17], v0, off offset:128
	v_add_f32_e32 v0, v94, v3
	v_add_f32_e32 v26, v104, v26
	v_addc_co_u32_e32 v45, vcc, 0, v65, vcc
	global_store_dword v[36:37], v0, off offset:128
	v_add_f32_e32 v0, v93, v4
	s_mov_b32 s2, 0x38000
	global_store_dword v[44:45], v26, off offset:-4096
	v_add_f32_e32 v26, v101, v27
	global_store_dword v[18:19], v0, off offset:128
	v_add_f32_e32 v0, v92, v5
	global_store_dword v[44:45], v26, off
	v_add_co_u32_e32 v26, vcc, s2, v64
	global_store_dword v[38:39], v0, off offset:128
	v_add_f32_e32 v0, v91, v6
	v_addc_co_u32_e32 v27, vcc, 0, v65, vcc
	global_store_dword v[20:21], v0, off offset:128
	v_add_f32_e32 v0, v90, v7
	v_add_co_u32_e32 v46, vcc, s67, v64
	global_store_dword v[40:41], v0, off offset:128
	v_add_f32_e32 v0, v89, v8
	v_add_f32_e32 v28, v102, v28
	v_addc_co_u32_e32 v47, vcc, 0, v65, vcc
	global_store_dword v[22:23], v0, off offset:128
	v_add_f32_e32 v0, v88, v9
	global_store_dword v[46:47], v28, off offset:-4096
	v_add_f32_e32 v28, v99, v29
	global_store_dword v[42:43], v0, off offset:128
	v_add_f32_e32 v0, v87, v10
	global_store_dword v[46:47], v28, off
	v_add_co_u32_e32 v28, vcc, s69, v64
	global_store_dword v[24:25], v0, off offset:128
	v_add_f32_e32 v0, v86, v11
	v_addc_co_u32_e32 v29, vcc, 0, v65, vcc
	global_store_dword v[44:45], v0, off offset:128
	v_add_f32_e32 v0, v85, v12
	v_add_co_u32_e32 v48, vcc, s71, v64
	global_store_dword v[26:27], v0, off offset:128
	v_add_f32_e32 v0, v84, v13
	v_add_f32_e32 v30, v100, v30
	v_addc_co_u32_e32 v49, vcc, 0, v65, vcc
	global_store_dword v[46:47], v0, off offset:128
	v_add_f32_e32 v0, v83, v14
	global_store_dword v[132:133], v62, off offset:-4096
	v_add_f32_e32 v62, v130, v63
	global_store_dword v[48:49], v30, off offset:-4096
	v_add_f32_e32 v30, v98, v31
	global_store_dword v[28:29], v0, off offset:128
	v_add_f32_e32 v0, v82, v15
	global_store_dword v[132:133], v62, off
	global_store_dword v[48:49], v30, off
	global_store_dword v[48:49], v0, off offset:128
	s_cbranch_scc0 .LBB0_43

; #define WAIT_V0() asm volatile("s_waitcnt vmcnt(0)" ::: "memory")
; DI int glds_row(int i) { const int tid = ltid(); return ((tid >> 6) * 4 + i) * 8 + ((tid & 63) >> 3); }
; DI int glds_chunk(int row) { return (ltid() & 7) ^ ((row >> 1) & 7); }
; DI void gemm_core(char* smem, int nk, const char* Ab, const char* Bb, const unsigned (&aoff)[4], const unsigned (&boff)[4],
;                   f32x16 (&acc)[2][2]) {
;     ...
;   auto stage = [&](int buf, int kt) __attribute__((always_inline)) {
;     const char* ak = Ab + kt * 128;
;     const char* bk = Bb + kt * 128;
;     char* sa = smem + buf * STAGE_B + w * 4096;
; #pragma unroll
;     for (int i = 0; i < 4; ++i) {
;       __builtin_amdgcn_global_load_lds((const unsigned*)(ak + aoff[i]), (unsigned*)(sa + i * 1024), 16, 0, 0);
;       __builtin_amdgcn_global_load_lds((const unsigned*)(bk + boff[i]), (unsigned*)(sa + 16384 + i * 1024), 16, 0, 0);
;     }
;   };
;   stage(0, 0);
;   WAIT_V0();
;   __syncthreads();
;   for (int kt = 0; kt < nk; ++kt) {
;     const int cur = kt & 1;
;     if (kt + 1 < nk) stage(cur ^ 1, kt + 1);
; DI void gemm_tile(char* smem, int nk, const bf16* A, int lda, int m0, const bf16* Bt, int ldb, int n0, f32x16 (&acc)[2][2]) {
;   unsigned aoff[4], boff[4];
; #pragma unroll
;   for (int i = 0; i < 4; ++i) {
;     const int row = glds_row(i), ch = glds_chunk(row);
;     aoff[i] = (unsigned)((row * lda + ch * 8) * 2);
;     boff[i] = (unsigned)((row * ldb + ch * 8) * 2);
;   }
;   gemm_core(smem, nk, (const char*)(A + (size_t)m0 * lda), (const char*)(Bt + (size_t)n0 * ldb), aoff, boff, acc);
; }
.LBB0_436:
	v_mov_b32_e32 v0, v161
	s_ashr_i32 s0, s14, 3
	v_lshrrev_b32_e32 v1, 1, v0
	v_lshrrev_b32_e32 v2, 3, v0
	v_bfe_u32 v0, v0, 3, 3
	v_and_or_b32 v0, v1, s9, v0
	v_mov_b32_e32 v1, v161
	v_bfe_u32 v2, v2, 1, 2
	v_xor_b32_e32 v1, v2, v1
	v_lshlrev_b32_e32 v0, 11, v0
	v_lshlrev_b32_e32 v1, 4, v1
	v_and_or_b32 v136, v1, s92, v0
	v_mov_b32_e32 v0, v161
	s_and_b32 s1, s0, 0xffffffc0
	v_ashrrev_i32_e32 v1, 1, v0
	v_and_b32_e32 v1, 0xffffffe0, v1
	v_bfe_u32 v0, v0, 3, 3
	v_or3_b32 v0, v0, v1, 8
	v_mov_b32_e32 v1, v161
	v_lshrrev_b32_e32 v2, 1, v0
	v_xor_b32_e32 v1, v2, v1
	v_lshlrev_b32_e32 v0, 11, v0
	v_lshlrev_b32_e32 v1, 4, v1
	v_and_or_b32 v0, v1, s92, v0
	v_mov_b32_e32 v1, v161
	s_lshl_b32 s10, s0, 1
	v_lshrrev_b32_e32 v2, 1, v1
	v_lshrrev_b32_e32 v3, 3, v1
	v_bfe_u32 v1, v1, 3, 3
	v_and_or_b32 v1, v2, s9, v1
	v_mov_b32_e32 v2, v161
	s_bfe_u32 s11, s0, 0x10005
	v_bfe_u32 v3, v3, 1, 2
	s_and_b32 s10, s10, 62
	s_or_b32 s1, s11, s1
	v_xor_b32_e32 v2, v3, v2
	s_or_b32 s1, s1, s10
	s_or_b32 s10, s0, 63
	v_lshlrev_b32_e32 v2, 4, v2
	s_cmpk_lt_i32 s10, 0x2c0
	v_lshlrev_b32_e32 v1, 11, v1
	v_and_b32_e32 v2, 0x70, v2
	s_cselect_b32 s1, s1, s0
	v_or3_b32 v2, v1, v2, s8
	v_mov_b32_e32 v1, v161
	s_mul_hi_i32 s10, s1, 0x2e8ba2e9
	s_lshr_b32 s11, s10, 31
	v_ashrrev_i32_e32 v3, 1, v1
	s_ashr_i32 s10, s10, 1
	v_and_b32_e32 v3, 0xffffffe0, v3
	v_bfe_u32 v1, v1, 3, 3
	s_and_b32 s0, s13, 0xc0
	s_add_i32 s10, s10, s11
	v_or3_b32 v1, v1, v3, 24
	v_mov_b32_e32 v3, v161
	s_add_i32 s15, s10, s0
	s_bfe_i32 s11, s14, 0x10002
	s_mul_i32 s10, s10, 11
	v_lshrrev_b32_e32 v4, 1, v1
	s_and_b32 s11, s11, 11
	s_sub_i32 s1, s1, s10
	v_xor_b32_e32 v3, v4, v3
	s_lshl_b32 s0, s15, 7
	s_add_i32 s1, s1, s11
	v_lshlrev_b32_e32 v1, 11, v1
	v_lshlrev_b32_e32 v3, 4, v3
	v_mov_b32_e32 v12, v161
	s_lshl_b32 s10, s1, 7
	v_and_or_b32 v4, v3, s92, v1
	s_ashr_i32 s1, s0, 31
	s_lshl_b64 s[16:17], s[0:1], 11
	v_and_b32_e32 v1, 31, v12
	v_lshrrev_b32_e32 v5, 1, v12
	v_and_or_b32 v1, v5, s6, v1
	s_add_u32 s16, s84, s16
	v_lshlrev_b32_e32 v112, 7, v1
	v_lshlrev_b32_e32 v1, 6, v12
	s_addc_u32 s17, s85, s17
	s_ashr_i32 s11, s10, 31
	v_and_b32_e32 v89, 0xfffff000, v1
	s_lshl_b64 s[18:19], s[10:11], 11
	v_add_u32_e32 v88, 0x4000, v89
	v_readfirstlane_b32 s20, v89
	s_add_u32 s18, s2, s18
	s_mov_b32 m0, s20
	v_readfirstlane_b32 s21, v88
	v_or_b32_e32 v90, 0x400, v89
	s_addc_u32 s19, s12, s19
	global_load_lds_dwordx4 v136, s[16:17]
	s_mov_b32 m0, s21
	v_readfirstlane_b32 s22, v90
	v_add_u32_e32 v91, 0x4400, v89
	global_load_lds_dwordx4 v136, s[18:19]
	s_mov_b32 m0, s22
	v_readfirstlane_b32 s23, v91
	v_or_b32_e32 v92, 0x800, v89
	global_load_lds_dwordx4 v0, s[16:17]
	s_mov_b32 m0, s23
	v_readfirstlane_b32 s28, v92
	v_add_u32_e32 v93, 0x4800, v89
	global_load_lds_dwordx4 v0, s[18:19]
	s_mov_b32 m0, s28
	v_readfirstlane_b32 s29, v93
	v_or_b32_e32 v94, 0xc00, v89
	global_load_lds_dwordx4 v2, s[16:17]
	s_mov_b32 m0, s29
	v_readfirstlane_b32 s40, v94
	v_add_u32_e32 v95, 0x4c00, v89
	v_lshrrev_b32_e32 v3, 5, v12
	v_bfe_u32 v99, v12, 1, 3
	global_load_lds_dwordx4 v2, s[18:19]
	s_mov_b32 m0, s40
	v_readfirstlane_b32 s41, v95
	v_add_u32_e32 v97, 0x8000, v89
	v_bitop3_b32 v3, v3, v99, 1 bitop3:0x6c
	v_lshl_add_u64 v[64:65], s[16:17], 0, v[136:137]
	v_mov_b32_e32 v1, v137
	global_load_lds_dwordx4 v4, s[16:17]
	s_mov_b32 m0, s41
	v_add_u32_e32 v96, 0xc000, v89
	v_readfirstlane_b32 s42, v97
	v_lshlrev_b32_e32 v6, 4, v3
	v_lshl_add_u64 v[66:67], s[18:19], 0, v[136:137]
	v_lshl_add_u64 v[68:69], s[16:17], 0, v[0:1]
	v_lshl_add_u64 v[70:71], s[18:19], 0, v[0:1]
	v_mov_b32_e32 v3, v137
	global_load_lds_dwordx4 v4, s[18:19]
	v_lshl_add_u64 v[0:1], v[64:65], 0, s[94:95]
	s_mov_b32 m0, s42
	v_readfirstlane_b32 s43, v96
	v_add_u32_e32 v98, 0x8400, v89
	v_lshl_add_u64 v[72:73], s[16:17], 0, v[2:3]
	v_lshl_add_u64 v[74:75], s[18:19], 0, v[2:3]
	global_load_lds_dwordx4 v[0:1], off
	v_lshl_add_u64 v[0:1], v[66:67], 0, s[94:95]
	s_mov_b32 m0, s43
	v_readfirstlane_b32 s44, v98
	v_add_u32_e32 v2, 0xc400, v89
	v_mov_b32_e32 v5, v137
	global_load_lds_dwordx4 v[0:1], off
	v_lshl_add_u64 v[0:1], v[68:69], 0, s[94:95]
	s_mov_b32 m0, s44
	v_readfirstlane_b32 s1, v2
	v_add_u32_e32 v2, 0x8800, v89
	v_lshl_add_u64 v[76:77], s[16:17], 0, v[4:5]
	global_load_lds_dwordx4 v[0:1], off
	v_lshl_add_u64 v[0:1], v[70:71], 0, s[94:95]
	s_mov_b32 m0, s1
	v_readfirstlane_b32 s16, v2
	v_add_u32_e32 v2, 0xc800, v89
	global_load_lds_dwordx4 v[0:1], off
	v_lshl_add_u64 v[0:1], v[72:73], 0, s[94:95]
	s_mov_b32 m0, s16
	v_readfirstlane_b32 s17, v2
	v_add_u32_e32 v2, 0x8c00, v89
	v_lshl_add_u64 v[78:79], s[18:19], 0, v[4:5]
	global_load_lds_dwordx4 v[0:1], off
	v_lshl_add_u64 v[0:1], v[74:75], 0, s[94:95]
	s_mov_b32 m0, s17
	v_readfirstlane_b32 s18, v2
	v_add_u32_e32 v2, 0xcc00, v89
	global_load_lds_dwordx4 v[0:1], off
	v_lshl_add_u64 v[0:1], v[76:77], 0, s[94:95]
	s_mov_b32 m0, s18
	v_readfirstlane_b32 s19, v2
	global_load_lds_dwordx4 v[0:1], off
	v_lshl_add_u64 v[0:1], v[78:79], 0, s[94:95]
	s_mov_b32 m0, s19
	v_or_b32_e32 v80, v112, v6
	global_load_lds_dwordx4 v[0:1], off
	s_waitcnt vmcnt(8)
	s_waitcnt vmcnt(8) lgkmcnt(0)
	s_barrier
; #define WAIT_V0() asm volatile("s_waitcnt vmcnt(0)" ::: "memory")
; DI void gemm_core(char* smem, int nk, const char* Ab, const char* Bb, const unsigned (&aoff)[4], const unsigned (&boff)[4],
;                   f32x16 (&acc)[2][2]) {
;     ...
;   for (int kt = 0; kt < nk; ++kt) {
;     const int cur = kt & 1;
;     if (kt + 1 < nk) stage(cur ^ 1, kt + 1);
;     const char* sb = smem + cur * STAGE_B;
; #pragma unroll
;     for (int ks = 0; ks < 4; ++ks) {
;       bf16x8 af[2], bfr[2];
; #pragma unroll
;       for (int mb = 0; mb < 2; ++mb) af[mb] = *(const bf16x8*)(sb + a_base + mb * 4096 + xo[ks]);
; #pragma unroll
;       for (int nb = 0; nb < 2; ++nb) bfr[nb] = *(const bf16x8*)(sb + b_base + nb * 4096 + xo[ks]);
; #pragma unroll
;       for (int mb = 0; mb < 2; ++mb)
; #pragma unroll
;         for (int nb = 0; nb < 2; ++nb)
;           acc[mb][nb] = __builtin_amdgcn_mfma_f32_32x32x16_bf16(af[mb], bfr[nb], acc[mb][nb], 0, 0, 0);
;     }
;     WAIT_V0();
;     __syncthreads();
;   }
	ds_read_b128 v[0:3], v80
	v_lshlrev_b32_e32 v4, 7, v12
	v_and_b32_e32 v113, 0x2f80, v4
	v_or_b32_e32 v82, v113, v6
	ds_read_b128 v[4:7], v82 offset:16384
	ds_read_b128 v[8:11], v82 offset:20480
	s_waitcnt lgkmcnt(0)
	v_mfma_f32_32x32x16_bf16 v[48:63], v[0:3], v[4:7], 0
	v_bfe_u32 v114, v12, 5, 1
	s_mov_b32 m0, s20
	v_mfma_f32_32x32x16_bf16 v[32:47], v[0:3], v[8:11], 0
	ds_read_b128 v[0:3], v80 offset:4096
	s_waitcnt lgkmcnt(0)
	v_mfma_f32_32x32x16_bf16 v[16:31], v[0:3], v[4:7], 0
	v_bitop3_b32 v4, v114, v99, 2 bitop3:0x36
	v_lshlrev_b32_e32 v83, 4, v4
	v_or_b32_e32 v81, v112, v83
	ds_read_b128 v[84:87], v81
	v_or_b32_e32 v83, v113, v83
	ds_read_b128 v[100:103], v83 offset:16384
	ds_read_b128 v[104:107], v83 offset:20480
	s_waitcnt lgkmcnt(0)
	v_mfma_f32_32x32x16_bf16 v[48:63], v[84:87], v[100:103], v[48:63]
	v_mfma_f32_32x32x16_bf16 v[32:47], v[84:87], v[104:107], v[32:47]
	ds_read_b128 v[84:87], v81 offset:4096
	v_mfma_f32_32x32x16_bf16 v[0:15], v[0:3], v[8:11], 0
	s_waitcnt lgkmcnt(0)
	v_mfma_f32_32x32x16_bf16 v[16:31], v[84:87], v[100:103], v[16:31]
	v_bitop3_b32 v100, v114, v99, 4 bitop3:0x36
	v_lshlrev_b32_e32 v108, 4, v100
	v_mfma_f32_32x32x16_bf16 v[0:15], v[84:87], v[104:107], v[0:15]
	v_or_b32_e32 v84, v112, v108
	ds_read_b128 v[100:103], v84
	v_or_b32_e32 v85, v113, v108
	ds_read_b128 v[104:107], v85 offset:16384
	ds_read_b128 v[108:111], v85 offset:20480
	v_bitop3_b32 v86, v114, v99, 6 bitop3:0x36
	v_lshlrev_b32_e32 v87, 4, v86
	s_waitcnt lgkmcnt(0)
	v_mfma_f32_32x32x16_bf16 v[48:63], v[100:103], v[104:107], v[48:63]
	v_or_b32_e32 v86, v112, v87
	v_or_b32_e32 v87, v113, v87
	v_mfma_f32_32x32x16_bf16 v[32:47], v[100:103], v[108:111], v[32:47]
	ds_read_b128 v[100:103], v84 offset:4096
	s_waitcnt lgkmcnt(0)
	v_mfma_f32_32x32x16_bf16 v[16:31], v[100:103], v[104:107], v[16:31]
	ds_read_b128 v[104:107], v87 offset:16384
	v_mfma_f32_32x32x16_bf16 v[0:15], v[100:103], v[108:111], v[0:15]
	ds_read_b128 v[100:103], v86
	ds_read_b128 v[108:111], v87 offset:20480
	s_waitcnt lgkmcnt(0)
	v_mfma_f32_32x32x16_bf16 v[48:63], v[100:103], v[104:107], v[48:63]
	v_mfma_f32_32x32x16_bf16 v[32:47], v[100:103], v[108:111], v[32:47]
	ds_read_b128 v[100:103], v86 offset:4096
	s_waitcnt vmcnt(0)
	s_waitcnt vmcnt(0) lgkmcnt(0)
	s_barrier
	v_mfma_f32_32x32x16_bf16 v[16:31], v[100:103], v[104:107], v[16:31]
	v_mfma_f32_32x32x16_bf16 v[0:15], v[100:103], v[108:111], v[0:15]
	ds_read_b128 v[100:103], v80 offset:32768
	ds_read_b128 v[104:107], v82 offset:49152
	ds_read_b128 v[108:111], v82 offset:53248
	v_lshl_add_u64 v[116:117], v[64:65], 0, s[36:37]
	global_load_lds_dwordx4 v[116:117], off
	v_lshl_add_u64 v[118:119], v[66:67], 0, s[36:37]
	s_mov_b32 m0, s21
	s_nop 0
	global_load_lds_dwordx4 v[118:119], off
	v_lshl_add_u64 v[116:117], v[68:69], 0, s[36:37]
	s_mov_b32 m0, s22
	s_nop 0
	global_load_lds_dwordx4 v[116:117], off
	v_lshl_add_u64 v[118:119], v[70:71], 0, s[36:37]
	s_mov_b32 m0, s23
	s_nop 0
	global_load_lds_dwordx4 v[118:119], off
	v_lshl_add_u64 v[116:117], v[72:73], 0, s[36:37]
	s_mov_b32 m0, s28
	s_nop 0
	global_load_lds_dwordx4 v[116:117], off
	v_lshl_add_u64 v[118:119], v[74:75], 0, s[36:37]
	s_mov_b32 m0, s29
	s_nop 0
	global_load_lds_dwordx4 v[118:119], off
	v_lshl_add_u64 v[116:117], v[76:77], 0, s[36:37]
	s_mov_b32 m0, s40
	s_nop 0
	global_load_lds_dwordx4 v[116:117], off
	v_lshl_add_u64 v[118:119], v[78:79], 0, s[36:37]
	s_mov_b32 m0, s41
	s_nop 0
	global_load_lds_dwordx4 v[118:119], off
	s_waitcnt lgkmcnt(0)
	v_mfma_f32_32x32x16_bf16 v[48:63], v[100:103], v[104:107], v[48:63]
	s_mov_b32 m0, s42
	v_mfma_f32_32x32x16_bf16 v[32:47], v[100:103], v[108:111], v[32:47]
	ds_read_b128 v[100:103], v80 offset:36864
	s_waitcnt lgkmcnt(0)
	v_mfma_f32_32x32x16_bf16 v[16:31], v[100:103], v[104:107], v[16:31]
	v_mfma_f32_32x32x16_bf16 v[0:15], v[100:103], v[108:111], v[0:15]
	ds_read_b128 v[100:103], v81 offset:32768
	ds_read_b128 v[104:107], v83 offset:49152
	ds_read_b128 v[108:111], v83 offset:53248
	s_waitcnt lgkmcnt(0)
	v_mfma_f32_32x32x16_bf16 v[48:63], v[100:103], v[104:107], v[48:63]
	v_mfma_f32_32x32x16_bf16 v[32:47], v[100:103], v[108:111], v[32:47]
	ds_read_b128 v[100:103], v81 offset:36864
	s_waitcnt lgkmcnt(0)
	v_mfma_f32_32x32x16_bf16 v[16:31], v[100:103], v[104:107], v[16:31]
	v_mfma_f32_32x32x16_bf16 v[0:15], v[100:103], v[108:111], v[0:15]
	ds_read_b128 v[100:103], v84 offset:32768
	ds_read_b128 v[104:107], v85 offset:49152
	ds_read_b128 v[108:111], v85 offset:53248
	s_waitcnt lgkmcnt(0)
	v_mfma_f32_32x32x16_bf16 v[48:63], v[100:103], v[104:107], v[48:63]
	v_mfma_f32_32x32x16_bf16 v[32:47], v[100:103], v[108:111], v[32:47]
	ds_read_b128 v[100:103], v84 offset:36864
	s_waitcnt lgkmcnt(0)
	v_mfma_f32_32x32x16_bf16 v[16:31], v[100:103], v[104:107], v[16:31]
	v_mfma_f32_32x32x16_bf16 v[0:15], v[100:103], v[108:111], v[0:15]
	ds_read_b128 v[100:103], v86 offset:32768
	ds_read_b128 v[104:107], v87 offset:49152
	ds_read_b128 v[108:111], v87 offset:53248
	s_waitcnt lgkmcnt(0)
	v_mfma_f32_32x32x16_bf16 v[48:63], v[100:103], v[104:107], v[48:63]
	v_mfma_f32_32x32x16_bf16 v[32:47], v[100:103], v[108:111], v[32:47]
	ds_read_b128 v[100:103], v86 offset:36864
	s_waitcnt vmcnt(0)
	s_waitcnt vmcnt(0) lgkmcnt(0)
	s_barrier
; #define WAIT_V0() asm volatile("s_waitcnt vmcnt(0)" ::: "memory")
; DI void gemm_core(char* smem, int nk, const char* Ab, const char* Bb, const unsigned (&aoff)[4], const unsigned (&boff)[4],
;                   f32x16 (&acc)[2][2]) {
;     ...
;   for (int kt = 0; kt < nk; ++kt) {
;     const int cur = kt & 1;
;     if (kt + 1 < nk) stage(cur ^ 1, kt + 1);
;     const char* sb = smem + cur * STAGE_B;
; #pragma unroll
;     for (int ks = 0; ks < 4; ++ks) {
;       bf16x8 af[2], bfr[2];
; #pragma unroll
;       for (int mb = 0; mb < 2; ++mb) af[mb] = *(const bf16x8*)(sb + a_base + mb * 4096 + xo[ks]);
; #pragma unroll
;       for (int nb = 0; nb < 2; ++nb) bfr[nb] = *(const bf16x8*)(sb + b_base + nb * 4096 + xo[ks]);
; #pragma unroll
;       for (int mb = 0; mb < 2; ++mb)
; #pragma unroll
;         for (int nb = 0; nb < 2; ++nb)
;           acc[mb][nb] = __builtin_amdgcn_mfma_f32_32x32x16_bf16(af[mb], bfr[nb], acc[mb][nb], 0, 0, 0);
;     }
;     WAIT_V0();
;     __syncthreads();
;   }
	v_mfma_f32_32x32x16_bf16 v[16:31], v[100:103], v[104:107], v[16:31]
	v_mfma_f32_32x32x16_bf16 v[0:15], v[100:103], v[108:111], v[0:15]
	ds_read_b128 v[100:103], v80
	ds_read_b128 v[104:107], v82 offset:16384
	ds_read_b128 v[108:111], v82 offset:20480
	v_lshl_add_u64 v[116:117], v[64:65], 0, s[38:39]
	global_load_lds_dwordx4 v[116:117], off
	v_lshl_add_u64 v[118:119], v[66:67], 0, s[38:39]
	s_mov_b32 m0, s43
	s_nop 0
	global_load_lds_dwordx4 v[118:119], off
	v_lshl_add_u64 v[116:117], v[68:69], 0, s[38:39]
	s_mov_b32 m0, s44
	s_nop 0
	global_load_lds_dwordx4 v[116:117], off
	v_lshl_add_u64 v[118:119], v[70:71], 0, s[38:39]
	s_mov_b32 m0, s1
	s_nop 0
	global_load_lds_dwordx4 v[118:119], off
	v_lshl_add_u64 v[116:117], v[72:73], 0, s[38:39]
	s_mov_b32 m0, s16
	s_nop 0
	global_load_lds_dwordx4 v[116:117], off
	v_lshl_add_u64 v[118:119], v[74:75], 0, s[38:39]
	s_mov_b32 m0, s17
	s_nop 0
	global_load_lds_dwordx4 v[118:119], off
	v_lshl_add_u64 v[116:117], v[76:77], 0, s[38:39]
	s_mov_b32 m0, s18
	s_nop 0
	global_load_lds_dwordx4 v[116:117], off
	v_lshl_add_u64 v[118:119], v[78:79], 0, s[38:39]
	s_mov_b32 m0, s19
	s_nop 0
	global_load_lds_dwordx4 v[118:119], off
	s_waitcnt lgkmcnt(0)
	v_mfma_f32_32x32x16_bf16 v[48:63], v[100:103], v[104:107], v[48:63]
	s_mov_b32 m0, s20
	v_mfma_f32_32x32x16_bf16 v[32:47], v[100:103], v[108:111], v[32:47]
	ds_read_b128 v[100:103], v80 offset:4096
	s_waitcnt lgkmcnt(0)
	v_mfma_f32_32x32x16_bf16 v[16:31], v[100:103], v[104:107], v[16:31]
	v_mfma_f32_32x32x16_bf16 v[0:15], v[100:103], v[108:111], v[0:15]
	ds_read_b128 v[100:103], v81
	ds_read_b128 v[104:107], v83 offset:16384
	ds_read_b128 v[108:111], v83 offset:20480
	s_waitcnt lgkmcnt(0)
	v_mfma_f32_32x32x16_bf16 v[48:63], v[100:103], v[104:107], v[48:63]
	v_mfma_f32_32x32x16_bf16 v[32:47], v[100:103], v[108:111], v[32:47]
	ds_read_b128 v[100:103], v81 offset:4096
	s_waitcnt lgkmcnt(0)
	v_mfma_f32_32x32x16_bf16 v[16:31], v[100:103], v[104:107], v[16:31]
	v_mfma_f32_32x32x16_bf16 v[0:15], v[100:103], v[108:111], v[0:15]
	ds_read_b128 v[100:103], v84
	ds_read_b128 v[104:107], v85 offset:16384
	ds_read_b128 v[108:111], v85 offset:20480
	s_waitcnt lgkmcnt(0)
	v_mfma_f32_32x32x16_bf16 v[48:63], v[100:103], v[104:107], v[48:63]
	v_mfma_f32_32x32x16_bf16 v[32:47], v[100:103], v[108:111], v[32:47]
	ds_read_b128 v[100:103], v84 offset:4096
	s_waitcnt lgkmcnt(0)
	v_mfma_f32_32x32x16_bf16 v[16:31], v[100:103], v[104:107], v[16:31]
	v_mfma_f32_32x32x16_bf16 v[0:15], v[100:103], v[108:111], v[0:15]
	ds_read_b128 v[100:103], v86
	ds_read_b128 v[104:107], v87 offset:16384
	ds_read_b128 v[108:111], v87 offset:20480
	s_waitcnt lgkmcnt(0)
	v_mfma_f32_32x32x16_bf16 v[48:63], v[100:103], v[104:107], v[48:63]
	v_mfma_f32_32x32x16_bf16 v[32:47], v[100:103], v[108:111], v[32:47]
	ds_read_b128 v[100:103], v86 offset:4096
	s_waitcnt vmcnt(0)
	s_waitcnt vmcnt(0) lgkmcnt(0)
	s_barrier
	v_mfma_f32_32x32x16_bf16 v[16:31], v[100:103], v[104:107], v[16:31]
	v_mfma_f32_32x32x16_bf16 v[0:15], v[100:103], v[108:111], v[0:15]
	ds_read_b128 v[100:103], v80 offset:32768
	ds_read_b128 v[104:107], v82 offset:49152
	ds_read_b128 v[108:111], v82 offset:53248
	v_lshl_add_u64 v[116:117], v[64:65], 0, s[30:31]
	global_load_lds_dwordx4 v[116:117], off
	v_lshl_add_u64 v[118:119], v[66:67], 0, s[30:31]
	s_mov_b32 m0, s21
	s_nop 0
	global_load_lds_dwordx4 v[118:119], off
	v_lshl_add_u64 v[116:117], v[68:69], 0, s[30:31]
	s_mov_b32 m0, s22
	s_nop 0
	global_load_lds_dwordx4 v[116:117], off
	v_lshl_add_u64 v[118:119], v[70:71], 0, s[30:31]
	s_mov_b32 m0, s23
	s_nop 0
	global_load_lds_dwordx4 v[118:119], off
	v_lshl_add_u64 v[116:117], v[72:73], 0, s[30:31]
	s_mov_b32 m0, s28
	s_nop 0
	global_load_lds_dwordx4 v[116:117], off
	v_lshl_add_u64 v[118:119], v[74:75], 0, s[30:31]
	s_mov_b32 m0, s29
	s_nop 0
	global_load_lds_dwordx4 v[118:119], off
	v_lshl_add_u64 v[116:117], v[76:77], 0, s[30:31]
	s_mov_b32 m0, s40
	s_nop 0
	global_load_lds_dwordx4 v[116:117], off
	v_lshl_add_u64 v[118:119], v[78:79], 0, s[30:31]
	s_mov_b32 m0, s41
	s_nop 0
	global_load_lds_dwordx4 v[118:119], off
	s_waitcnt lgkmcnt(0)
	v_mfma_f32_32x32x16_bf16 v[48:63], v[100:103], v[104:107], v[48:63]
	s_mov_b32 m0, s42
	v_mfma_f32_32x32x16_bf16 v[32:47], v[100:103], v[108:111], v[32:47]
	ds_read_b128 v[100:103], v80 offset:36864
	s_waitcnt lgkmcnt(0)
	v_mfma_f32_32x32x16_bf16 v[16:31], v[100:103], v[104:107], v[16:31]
	v_mfma_f32_32x32x16_bf16 v[0:15], v[100:103], v[108:111], v[0:15]
	ds_read_b128 v[100:103], v81 offset:32768
	ds_read_b128 v[104:107], v83 offset:49152
	ds_read_b128 v[108:111], v83 offset:53248
	s_waitcnt lgkmcnt(0)
	v_mfma_f32_32x32x16_bf16 v[48:63], v[100:103], v[104:107], v[48:63]
	v_mfma_f32_32x32x16_bf16 v[32:47], v[100:103], v[108:111], v[32:47]
	ds_read_b128 v[100:103], v81 offset:36864
	s_waitcnt lgkmcnt(0)
	v_mfma_f32_32x32x16_bf16 v[16:31], v[100:103], v[104:107], v[16:31]
	v_mfma_f32_32x32x16_bf16 v[0:15], v[100:103], v[108:111], v[0:15]
	ds_read_b128 v[100:103], v84 offset:32768
	ds_read_b128 v[104:107], v85 offset:49152
	ds_read_b128 v[108:111], v85 offset:53248
	s_waitcnt lgkmcnt(0)
	v_mfma_f32_32x32x16_bf16 v[48:63], v[100:103], v[104:107], v[48:63]
	v_mfma_f32_32x32x16_bf16 v[32:47], v[100:103], v[108:111], v[32:47]
	ds_read_b128 v[100:103], v84 offset:36864
	s_waitcnt lgkmcnt(0)
	v_mfma_f32_32x32x16_bf16 v[16:31], v[100:103], v[104:107], v[16:31]
	v_mfma_f32_32x32x16_bf16 v[0:15], v[100:103], v[108:111], v[0:15]
	ds_read_b128 v[100:103], v86 offset:32768
	ds_read_b128 v[104:107], v87 offset:49152
	ds_read_b128 v[108:111], v87 offset:53248
	s_waitcnt lgkmcnt(0)
	v_mfma_f32_32x32x16_bf16 v[48:63], v[100:103], v[104:107], v[48:63]
	v_mfma_f32_32x32x16_bf16 v[32:47], v[100:103], v[108:111], v[32:47]
	ds_read_b128 v[100:103], v86 offset:36864
	s_waitcnt vmcnt(0)
	s_waitcnt vmcnt(0) lgkmcnt(0)
	s_barrier
; #define WAIT_V0() asm volatile("s_waitcnt vmcnt(0)" ::: "memory")
; DI void gemm_core(char* smem, int nk, const char* Ab, const char* Bb, const unsigned (&aoff)[4], const unsigned (&boff)[4],
;                   f32x16 (&acc)[2][2]) {
;     ...
;   for (int kt = 0; kt < nk; ++kt) {
;     const int cur = kt & 1;
;     if (kt + 1 < nk) stage(cur ^ 1, kt + 1);
;     const char* sb = smem + cur * STAGE_B;
; #pragma unroll
;     for (int ks = 0; ks < 4; ++ks) {
;       bf16x8 af[2], bfr[2];
; #pragma unroll
;       for (int mb = 0; mb < 2; ++mb) af[mb] = *(const bf16x8*)(sb + a_base + mb * 4096 + xo[ks]);
; #pragma unroll
;       for (int nb = 0; nb < 2; ++nb) bfr[nb] = *(const bf16x8*)(sb + b_base + nb * 4096 + xo[ks]);
; #pragma unroll
;       for (int mb = 0; mb < 2; ++mb)
; #pragma unroll
;         for (int nb = 0; nb < 2; ++nb)
;           acc[mb][nb] = __builtin_amdgcn_mfma_f32_32x32x16_bf16(af[mb], bfr[nb], acc[mb][nb], 0, 0, 0);
;     }
;     WAIT_V0();
;     __syncthreads();
;   }
	v_mfma_f32_32x32x16_bf16 v[16:31], v[100:103], v[104:107], v[16:31]
	v_mfma_f32_32x32x16_bf16 v[0:15], v[100:103], v[108:111], v[0:15]
	ds_read_b128 v[100:103], v80
	ds_read_b128 v[104:107], v82 offset:16384
	ds_read_b128 v[108:111], v82 offset:20480
	v_lshl_add_u64 v[116:117], v[64:65], 0, s[46:47]
	global_load_lds_dwordx4 v[116:117], off
	v_lshl_add_u64 v[118:119], v[66:67], 0, s[46:47]
	s_mov_b32 m0, s43
	s_nop 0
	global_load_lds_dwordx4 v[118:119], off
	v_lshl_add_u64 v[116:117], v[68:69], 0, s[46:47]
	s_mov_b32 m0, s44
	s_nop 0
	global_load_lds_dwordx4 v[116:117], off
	v_lshl_add_u64 v[118:119], v[70:71], 0, s[46:47]
	s_mov_b32 m0, s1
	s_nop 0
	global_load_lds_dwordx4 v[118:119], off
	v_lshl_add_u64 v[116:117], v[72:73], 0, s[46:47]
	s_mov_b32 m0, s16
	s_nop 0
	global_load_lds_dwordx4 v[116:117], off
	v_lshl_add_u64 v[118:119], v[74:75], 0, s[46:47]
	s_mov_b32 m0, s17
	s_nop 0
	global_load_lds_dwordx4 v[118:119], off
	v_lshl_add_u64 v[116:117], v[76:77], 0, s[46:47]
	s_mov_b32 m0, s18
	s_nop 0
	global_load_lds_dwordx4 v[116:117], off
	v_lshl_add_u64 v[118:119], v[78:79], 0, s[46:47]
	s_mov_b32 m0, s19
	s_nop 0
	global_load_lds_dwordx4 v[118:119], off
	s_waitcnt lgkmcnt(0)
	v_mfma_f32_32x32x16_bf16 v[48:63], v[100:103], v[104:107], v[48:63]
	s_mov_b32 m0, s20
	v_mfma_f32_32x32x16_bf16 v[32:47], v[100:103], v[108:111], v[32:47]
	ds_read_b128 v[100:103], v80 offset:4096
	s_waitcnt lgkmcnt(0)
	v_mfma_f32_32x32x16_bf16 v[16:31], v[100:103], v[104:107], v[16:31]
	v_mfma_f32_32x32x16_bf16 v[0:15], v[100:103], v[108:111], v[0:15]
	ds_read_b128 v[100:103], v81
	ds_read_b128 v[104:107], v83 offset:16384
	ds_read_b128 v[108:111], v83 offset:20480
	s_waitcnt lgkmcnt(0)
	v_mfma_f32_32x32x16_bf16 v[48:63], v[100:103], v[104:107], v[48:63]
	v_mfma_f32_32x32x16_bf16 v[32:47], v[100:103], v[108:111], v[32:47]
	ds_read_b128 v[100:103], v81 offset:4096
	s_waitcnt lgkmcnt(0)
	v_mfma_f32_32x32x16_bf16 v[16:31], v[100:103], v[104:107], v[16:31]
	v_mfma_f32_32x32x16_bf16 v[0:15], v[100:103], v[108:111], v[0:15]
	ds_read_b128 v[100:103], v84
	ds_read_b128 v[104:107], v85 offset:16384
	ds_read_b128 v[108:111], v85 offset:20480
	s_waitcnt lgkmcnt(0)
	v_mfma_f32_32x32x16_bf16 v[48:63], v[100:103], v[104:107], v[48:63]
	v_mfma_f32_32x32x16_bf16 v[32:47], v[100:103], v[108:111], v[32:47]
	ds_read_b128 v[100:103], v84 offset:4096
	s_waitcnt lgkmcnt(0)
	v_mfma_f32_32x32x16_bf16 v[16:31], v[100:103], v[104:107], v[16:31]
	v_mfma_f32_32x32x16_bf16 v[0:15], v[100:103], v[108:111], v[0:15]
	ds_read_b128 v[100:103], v86
	ds_read_b128 v[104:107], v87 offset:16384
	ds_read_b128 v[108:111], v87 offset:20480
	s_waitcnt lgkmcnt(0)
	v_mfma_f32_32x32x16_bf16 v[48:63], v[100:103], v[104:107], v[48:63]
	v_mfma_f32_32x32x16_bf16 v[32:47], v[100:103], v[108:111], v[32:47]
	ds_read_b128 v[100:103], v86 offset:4096
	s_waitcnt vmcnt(0)
	s_waitcnt vmcnt(0) lgkmcnt(0)
	s_barrier
	v_mfma_f32_32x32x16_bf16 v[16:31], v[100:103], v[104:107], v[16:31]
	v_mfma_f32_32x32x16_bf16 v[0:15], v[100:103], v[108:111], v[0:15]
	ds_read_b128 v[100:103], v80 offset:32768
	ds_read_b128 v[104:107], v82 offset:49152
	ds_read_b128 v[108:111], v82 offset:53248
	v_lshl_add_u64 v[116:117], v[64:65], 0, s[48:49]
	global_load_lds_dwordx4 v[116:117], off
	v_lshl_add_u64 v[118:119], v[66:67], 0, s[48:49]
	s_mov_b32 m0, s21
	s_nop 0
	global_load_lds_dwordx4 v[118:119], off
	v_lshl_add_u64 v[116:117], v[68:69], 0, s[48:49]
	s_mov_b32 m0, s22
	s_nop 0
	global_load_lds_dwordx4 v[116:117], off
	v_lshl_add_u64 v[118:119], v[70:71], 0, s[48:49]
	s_mov_b32 m0, s23
	s_nop 0
	global_load_lds_dwordx4 v[118:119], off
	v_lshl_add_u64 v[116:117], v[72:73], 0, s[48:49]
	s_mov_b32 m0, s28
	s_nop 0
	global_load_lds_dwordx4 v[116:117], off
	v_lshl_add_u64 v[118:119], v[74:75], 0, s[48:49]
	s_mov_b32 m0, s29
	s_nop 0
	global_load_lds_dwordx4 v[118:119], off
	v_lshl_add_u64 v[116:117], v[76:77], 0, s[48:49]
	s_mov_b32 m0, s40
	s_nop 0
	global_load_lds_dwordx4 v[116:117], off
	v_lshl_add_u64 v[118:119], v[78:79], 0, s[48:49]
	s_mov_b32 m0, s41
	s_nop 0
	global_load_lds_dwordx4 v[118:119], off
	s_waitcnt lgkmcnt(0)
	v_mfma_f32_32x32x16_bf16 v[48:63], v[100:103], v[104:107], v[48:63]
	s_mov_b32 m0, s42
	v_readfirstlane_b32 s42, v93
	v_mfma_f32_32x32x16_bf16 v[32:47], v[100:103], v[108:111], v[32:47]
	ds_read_b128 v[100:103], v80 offset:36864
	s_waitcnt lgkmcnt(0)
	v_mfma_f32_32x32x16_bf16 v[16:31], v[100:103], v[104:107], v[16:31]
	v_mfma_f32_32x32x16_bf16 v[0:15], v[100:103], v[108:111], v[0:15]
	ds_read_b128 v[100:103], v81 offset:32768
	ds_read_b128 v[104:107], v83 offset:49152
	ds_read_b128 v[108:111], v83 offset:53248
	s_waitcnt lgkmcnt(0)
	v_mfma_f32_32x32x16_bf16 v[48:63], v[100:103], v[104:107], v[48:63]
	v_mfma_f32_32x32x16_bf16 v[32:47], v[100:103], v[108:111], v[32:47]
	ds_read_b128 v[100:103], v81 offset:36864
	s_waitcnt lgkmcnt(0)
	v_mfma_f32_32x32x16_bf16 v[16:31], v[100:103], v[104:107], v[16:31]
	v_mfma_f32_32x32x16_bf16 v[0:15], v[100:103], v[108:111], v[0:15]
	ds_read_b128 v[100:103], v84 offset:32768
	ds_read_b128 v[104:107], v85 offset:49152
	ds_read_b128 v[108:111], v85 offset:53248
	s_waitcnt lgkmcnt(0)
	v_mfma_f32_32x32x16_bf16 v[48:63], v[100:103], v[104:107], v[48:63]
	v_mfma_f32_32x32x16_bf16 v[32:47], v[100:103], v[108:111], v[32:47]
	ds_read_b128 v[100:103], v84 offset:36864
	s_waitcnt lgkmcnt(0)
	v_mfma_f32_32x32x16_bf16 v[16:31], v[100:103], v[104:107], v[16:31]
	v_mfma_f32_32x32x16_bf16 v[0:15], v[100:103], v[108:111], v[0:15]
	ds_read_b128 v[100:103], v86 offset:32768
	ds_read_b128 v[104:107], v87 offset:49152
	ds_read_b128 v[108:111], v87 offset:53248
	s_waitcnt lgkmcnt(0)
	v_mfma_f32_32x32x16_bf16 v[48:63], v[100:103], v[104:107], v[48:63]
	v_mfma_f32_32x32x16_bf16 v[32:47], v[100:103], v[108:111], v[32:47]
	ds_read_b128 v[100:103], v86 offset:36864
	s_waitcnt vmcnt(0)
	s_waitcnt vmcnt(0) lgkmcnt(0)
	s_barrier
; #define WAIT_V0() asm volatile("s_waitcnt vmcnt(0)" ::: "memory")
; DI void gemm_core(char* smem, int nk, const char* Ab, const char* Bb, const unsigned (&aoff)[4], const unsigned (&boff)[4],
;                   f32x16 (&acc)[2][2]) {
;     ...
;   for (int kt = 0; kt < nk; ++kt) {
;     const int cur = kt & 1;
;     if (kt + 1 < nk) stage(cur ^ 1, kt + 1);
;     const char* sb = smem + cur * STAGE_B;
; #pragma unroll
;     for (int ks = 0; ks < 4; ++ks) {
;       bf16x8 af[2], bfr[2];
; #pragma unroll
;       for (int mb = 0; mb < 2; ++mb) af[mb] = *(const bf16x8*)(sb + a_base + mb * 4096 + xo[ks]);
; #pragma unroll
;       for (int nb = 0; nb < 2; ++nb) bfr[nb] = *(const bf16x8*)(sb + b_base + nb * 4096 + xo[ks]);
; #pragma unroll
;       for (int mb = 0; mb < 2; ++mb)
; #pragma unroll
;         for (int nb = 0; nb < 2; ++nb)
;           acc[mb][nb] = __builtin_amdgcn_mfma_f32_32x32x16_bf16(af[mb], bfr[nb], acc[mb][nb], 0, 0, 0);
;     }
;     WAIT_V0();
;     __syncthreads();
;   }
	v_mfma_f32_32x32x16_bf16 v[16:31], v[100:103], v[104:107], v[16:31]
	v_mfma_f32_32x32x16_bf16 v[0:15], v[100:103], v[108:111], v[0:15]
	ds_read_b128 v[100:103], v80
	ds_read_b128 v[104:107], v82 offset:16384
	ds_read_b128 v[108:111], v82 offset:20480
	v_lshl_add_u64 v[116:117], v[64:65], 0, s[50:51]
	global_load_lds_dwordx4 v[116:117], off
	v_lshl_add_u64 v[118:119], v[66:67], 0, s[50:51]
	s_mov_b32 m0, s43
	v_readfirstlane_b32 s43, v94
	global_load_lds_dwordx4 v[118:119], off
	v_lshl_add_u64 v[116:117], v[68:69], 0, s[50:51]
	s_mov_b32 m0, s44
	v_readfirstlane_b32 s44, v95
	global_load_lds_dwordx4 v[116:117], off
	v_lshl_add_u64 v[118:119], v[70:71], 0, s[50:51]
	s_mov_b32 m0, s1
	s_nop 0
	global_load_lds_dwordx4 v[118:119], off
	v_lshl_add_u64 v[116:117], v[72:73], 0, s[50:51]
	s_mov_b32 m0, s16
	s_nop 0
	global_load_lds_dwordx4 v[116:117], off
	v_lshl_add_u64 v[118:119], v[74:75], 0, s[50:51]
	s_mov_b32 m0, s17
	s_nop 0
	global_load_lds_dwordx4 v[118:119], off
	v_lshl_add_u64 v[116:117], v[76:77], 0, s[50:51]
	s_mov_b32 m0, s18
	s_nop 0
	global_load_lds_dwordx4 v[116:117], off
	v_lshl_add_u64 v[118:119], v[78:79], 0, s[50:51]
	s_mov_b32 m0, s19
	s_nop 0
	global_load_lds_dwordx4 v[118:119], off
	s_waitcnt lgkmcnt(0)
	v_mfma_f32_32x32x16_bf16 v[48:63], v[100:103], v[104:107], v[48:63]
	s_mov_b32 m0, s20
	v_readfirstlane_b32 s20, v97
	v_mfma_f32_32x32x16_bf16 v[32:47], v[100:103], v[108:111], v[32:47]
	ds_read_b128 v[100:103], v80 offset:4096
	s_waitcnt lgkmcnt(0)
	v_mfma_f32_32x32x16_bf16 v[16:31], v[100:103], v[104:107], v[16:31]
	v_mfma_f32_32x32x16_bf16 v[0:15], v[100:103], v[108:111], v[0:15]
	ds_read_b128 v[100:103], v81
	ds_read_b128 v[104:107], v83 offset:16384
	ds_read_b128 v[108:111], v83 offset:20480
	s_waitcnt lgkmcnt(0)
	v_mfma_f32_32x32x16_bf16 v[48:63], v[100:103], v[104:107], v[48:63]
	v_mfma_f32_32x32x16_bf16 v[32:47], v[100:103], v[108:111], v[32:47]
	ds_read_b128 v[100:103], v81 offset:4096
	s_waitcnt lgkmcnt(0)
	v_mfma_f32_32x32x16_bf16 v[16:31], v[100:103], v[104:107], v[16:31]
	v_mfma_f32_32x32x16_bf16 v[0:15], v[100:103], v[108:111], v[0:15]
	ds_read_b128 v[100:103], v84
	ds_read_b128 v[104:107], v85 offset:16384
	ds_read_b128 v[108:111], v85 offset:20480
	s_waitcnt lgkmcnt(0)
	v_mfma_f32_32x32x16_bf16 v[48:63], v[100:103], v[104:107], v[48:63]
	v_mfma_f32_32x32x16_bf16 v[32:47], v[100:103], v[108:111], v[32:47]
	ds_read_b128 v[100:103], v84 offset:4096
	s_waitcnt lgkmcnt(0)
	v_mfma_f32_32x32x16_bf16 v[16:31], v[100:103], v[104:107], v[16:31]
	v_mfma_f32_32x32x16_bf16 v[0:15], v[100:103], v[108:111], v[0:15]
	ds_read_b128 v[100:103], v86
	ds_read_b128 v[104:107], v87 offset:16384
	ds_read_b128 v[108:111], v87 offset:20480
	s_waitcnt lgkmcnt(0)
	v_mfma_f32_32x32x16_bf16 v[48:63], v[100:103], v[104:107], v[48:63]
	v_mfma_f32_32x32x16_bf16 v[32:47], v[100:103], v[108:111], v[32:47]
	ds_read_b128 v[100:103], v86 offset:4096
	s_waitcnt vmcnt(0)
	s_waitcnt vmcnt(0) lgkmcnt(0)
	s_barrier
	v_mfma_f32_32x32x16_bf16 v[16:31], v[100:103], v[104:107], v[16:31]
	v_mfma_f32_32x32x16_bf16 v[0:15], v[100:103], v[108:111], v[0:15]
	v_lshl_add_u64 v[100:101], v[64:65], 0, s[52:53]
	global_load_lds_dwordx4 v[100:101], off
	v_lshl_add_u64 v[100:101], v[66:67], 0, s[52:53]
	s_mov_b32 m0, s21
	v_readfirstlane_b32 s21, v96
	global_load_lds_dwordx4 v[100:101], off
	v_lshl_add_u64 v[100:101], v[68:69], 0, s[52:53]
	s_mov_b32 m0, s22
	v_readfirstlane_b32 s22, v98
	global_load_lds_dwordx4 v[100:101], off
	v_lshl_add_u64 v[100:101], v[70:71], 0, s[52:53]
	s_mov_b32 m0, s23
	v_lshl_add_u64 v[96:97], v[68:69], 0, s[54:55]
	global_load_lds_dwordx4 v[100:101], off
	v_lshl_add_u64 v[100:101], v[72:73], 0, s[52:53]
	s_mov_b32 m0, s28
	v_readfirstlane_b32 s23, v89
	global_load_lds_dwordx4 v[100:101], off
	v_lshl_add_u64 v[100:101], v[74:75], 0, s[52:53]
	s_mov_b32 m0, s29
	v_readfirstlane_b32 s28, v88
	global_load_lds_dwordx4 v[100:101], off
	v_lshl_add_u64 v[100:101], v[76:77], 0, s[52:53]
	s_mov_b32 m0, s40
	v_readfirstlane_b32 s29, v90
	global_load_lds_dwordx4 v[100:101], off
	v_lshl_add_u64 v[100:101], v[78:79], 0, s[52:53]
	s_mov_b32 m0, s41
	v_lshl_add_u64 v[88:89], v[68:69], 0, s[56:57]
	global_load_lds_dwordx4 v[100:101], off
	ds_read_b128 v[100:103], v80 offset:32768
	ds_read_b128 v[104:107], v82 offset:49152
	ds_read_b128 v[108:111], v82 offset:53248
	s_waitcnt lgkmcnt(0)
	v_mfma_f32_32x32x16_bf16 v[48:63], v[100:103], v[104:107], v[48:63]
	s_mov_b32 m0, s20
	v_readfirstlane_b32 s40, v91
	v_readfirstlane_b32 s41, v92
	v_mfma_f32_32x32x16_bf16 v[32:47], v[100:103], v[108:111], v[32:47]
	ds_read_b128 v[100:103], v80 offset:36864
	s_waitcnt lgkmcnt(0)
	v_mfma_f32_32x32x16_bf16 v[16:31], v[100:103], v[104:107], v[16:31]
	v_mfma_f32_32x32x16_bf16 v[0:15], v[100:103], v[108:111], v[0:15]
	ds_read_b128 v[100:103], v81 offset:32768
	ds_read_b128 v[104:107], v83 offset:49152
	ds_read_b128 v[108:111], v83 offset:53248
	s_waitcnt lgkmcnt(0)
	v_mfma_f32_32x32x16_bf16 v[48:63], v[100:103], v[104:107], v[48:63]
	v_mfma_f32_32x32x16_bf16 v[32:47], v[100:103], v[108:111], v[32:47]
	ds_read_b128 v[100:103], v81 offset:36864
	s_waitcnt lgkmcnt(0)
	v_mfma_f32_32x32x16_bf16 v[16:31], v[100:103], v[104:107], v[16:31]
	v_mfma_f32_32x32x16_bf16 v[0:15], v[100:103], v[108:111], v[0:15]
	ds_read_b128 v[100:103], v84 offset:32768
	ds_read_b128 v[104:107], v85 offset:49152
	ds_read_b128 v[108:111], v85 offset:53248
	s_waitcnt lgkmcnt(0)
	v_mfma_f32_32x32x16_bf16 v[48:63], v[100:103], v[104:107], v[48:63]
	v_mfma_f32_32x32x16_bf16 v[32:47], v[100:103], v[108:111], v[32:47]
	ds_read_b128 v[100:103], v84 offset:36864
	s_waitcnt lgkmcnt(0)
	v_mfma_f32_32x32x16_bf16 v[16:31], v[100:103], v[104:107], v[16:31]
	v_mfma_f32_32x32x16_bf16 v[0:15], v[100:103], v[108:111], v[0:15]
	ds_read_b128 v[100:103], v86 offset:32768
	ds_read_b128 v[104:107], v87 offset:49152
	ds_read_b128 v[108:111], v87 offset:53248
	s_waitcnt lgkmcnt(0)
	v_mfma_f32_32x32x16_bf16 v[48:63], v[100:103], v[104:107], v[48:63]
	v_mfma_f32_32x32x16_bf16 v[32:47], v[100:103], v[108:111], v[32:47]
	ds_read_b128 v[100:103], v86 offset:36864
	s_waitcnt vmcnt(0)
	s_waitcnt vmcnt(0) lgkmcnt(0)
	s_barrier
; #define WAIT_V0() asm volatile("s_waitcnt vmcnt(0)" ::: "memory")
; DI void gemm_core(char* smem, int nk, const char* Ab, const char* Bb, const unsigned (&aoff)[4], const unsigned (&boff)[4],
;                   f32x16 (&acc)[2][2]) {
;     ...
;   for (int kt = 0; kt < nk; ++kt) {
;     const int cur = kt & 1;
;     if (kt + 1 < nk) stage(cur ^ 1, kt + 1);
;     const char* sb = smem + cur * STAGE_B;
; #pragma unroll
;     for (int ks = 0; ks < 4; ++ks) {
;       bf16x8 af[2], bfr[2];
; #pragma unroll
;       for (int mb = 0; mb < 2; ++mb) af[mb] = *(const bf16x8*)(sb + a_base + mb * 4096 + xo[ks]);
; #pragma unroll
;       for (int nb = 0; nb < 2; ++nb) bfr[nb] = *(const bf16x8*)(sb + b_base + nb * 4096 + xo[ks]);
; #pragma unroll
;       for (int mb = 0; mb < 2; ++mb)
; #pragma unroll
;         for (int nb = 0; nb < 2; ++nb)
;           acc[mb][nb] = __builtin_amdgcn_mfma_f32_32x32x16_bf16(af[mb], bfr[nb], acc[mb][nb], 0, 0, 0);
;     }
;     WAIT_V0();
;     __syncthreads();
;   }
	v_mfma_f32_32x32x16_bf16 v[16:31], v[100:103], v[104:107], v[16:31]
	v_mfma_f32_32x32x16_bf16 v[0:15], v[100:103], v[108:111], v[0:15]
	v_lshl_add_u64 v[100:101], v[64:65], 0, s[54:55]
	global_load_lds_dwordx4 v[100:101], off
	v_lshl_add_u64 v[100:101], v[66:67], 0, s[54:55]
	s_mov_b32 m0, s21
	s_nop 0
	global_load_lds_dwordx4 v[100:101], off
	s_mov_b32 m0, s22
	s_nop 0
	global_load_lds_dwordx4 v[96:97], off
	v_lshl_add_u64 v[96:97], v[70:71], 0, s[54:55]
	s_mov_b32 m0, s1
	s_nop 0
	global_load_lds_dwordx4 v[96:97], off
	v_lshl_add_u64 v[96:97], v[72:73], 0, s[54:55]
	s_mov_b32 m0, s16
	s_nop 0
	global_load_lds_dwordx4 v[96:97], off
	v_lshl_add_u64 v[96:97], v[74:75], 0, s[54:55]
	s_mov_b32 m0, s17
	s_nop 0
	global_load_lds_dwordx4 v[96:97], off
	v_lshl_add_u64 v[96:97], v[76:77], 0, s[54:55]
	s_mov_b32 m0, s18
	s_nop 0
	global_load_lds_dwordx4 v[96:97], off
	v_lshl_add_u64 v[96:97], v[78:79], 0, s[54:55]
	s_mov_b32 m0, s19
	s_nop 0
	global_load_lds_dwordx4 v[96:97], off
	ds_read_b128 v[96:99], v80
	ds_read_b128 v[100:103], v82 offset:16384
	ds_read_b128 v[104:107], v82 offset:20480
	s_waitcnt lgkmcnt(0)
	v_mfma_f32_32x32x16_bf16 v[48:63], v[96:99], v[100:103], v[48:63]
	s_mov_b32 m0, s23
	v_mfma_f32_32x32x16_bf16 v[32:47], v[96:99], v[104:107], v[32:47]
	ds_read_b128 v[96:99], v80 offset:4096
	s_waitcnt lgkmcnt(0)
	v_mfma_f32_32x32x16_bf16 v[16:31], v[96:99], v[100:103], v[16:31]
	v_mfma_f32_32x32x16_bf16 v[0:15], v[96:99], v[104:107], v[0:15]
	ds_read_b128 v[96:99], v81
	ds_read_b128 v[100:103], v83 offset:16384
	ds_read_b128 v[104:107], v83 offset:20480
	s_waitcnt lgkmcnt(0)
	v_mfma_f32_32x32x16_bf16 v[48:63], v[96:99], v[100:103], v[48:63]
	v_mfma_f32_32x32x16_bf16 v[32:47], v[96:99], v[104:107], v[32:47]
	ds_read_b128 v[96:99], v81 offset:4096
	s_waitcnt lgkmcnt(0)
	v_mfma_f32_32x32x16_bf16 v[16:31], v[96:99], v[100:103], v[16:31]
	v_mfma_f32_32x32x16_bf16 v[0:15], v[96:99], v[104:107], v[0:15]
	ds_read_b128 v[96:99], v84
	ds_read_b128 v[100:103], v85 offset:16384
	ds_read_b128 v[104:107], v85 offset:20480
	s_waitcnt lgkmcnt(0)
	v_mfma_f32_32x32x16_bf16 v[48:63], v[96:99], v[100:103], v[48:63]
	v_mfma_f32_32x32x16_bf16 v[32:47], v[96:99], v[104:107], v[32:47]
	ds_read_b128 v[96:99], v84 offset:4096
	s_waitcnt lgkmcnt(0)
	v_mfma_f32_32x32x16_bf16 v[16:31], v[96:99], v[100:103], v[16:31]
	v_mfma_f32_32x32x16_bf16 v[0:15], v[96:99], v[104:107], v[0:15]
	ds_read_b128 v[96:99], v86
	ds_read_b128 v[100:103], v87 offset:16384
	ds_read_b128 v[104:107], v87 offset:20480
	s_waitcnt lgkmcnt(0)
	v_mfma_f32_32x32x16_bf16 v[48:63], v[96:99], v[100:103], v[48:63]
	v_mfma_f32_32x32x16_bf16 v[32:47], v[96:99], v[104:107], v[32:47]
	ds_read_b128 v[96:99], v86 offset:4096
	s_waitcnt vmcnt(0)
	s_waitcnt vmcnt(0) lgkmcnt(0)
	s_barrier
	v_mfma_f32_32x32x16_bf16 v[16:31], v[96:99], v[100:103], v[16:31]
	v_mfma_f32_32x32x16_bf16 v[0:15], v[96:99], v[104:107], v[0:15]
	v_lshl_add_u64 v[96:97], v[64:65], 0, s[56:57]
	global_load_lds_dwordx4 v[96:97], off
	v_lshl_add_u64 v[96:97], v[66:67], 0, s[56:57]
	s_mov_b32 m0, s28
	s_nop 0
	global_load_lds_dwordx4 v[96:97], off
	s_mov_b32 m0, s29
	s_nop 0
	global_load_lds_dwordx4 v[88:89], off
	v_lshl_add_u64 v[88:89], v[70:71], 0, s[56:57]
	s_mov_b32 m0, s40
	s_nop 0
	global_load_lds_dwordx4 v[88:89], off
	v_lshl_add_u64 v[88:89], v[72:73], 0, s[56:57]
	s_mov_b32 m0, s41
	s_nop 0
	global_load_lds_dwordx4 v[88:89], off
	v_lshl_add_u64 v[88:89], v[74:75], 0, s[56:57]
	s_mov_b32 m0, s42
	s_nop 0
	global_load_lds_dwordx4 v[88:89], off
	v_lshl_add_u64 v[88:89], v[76:77], 0, s[56:57]
	s_mov_b32 m0, s43
	s_nop 0
	global_load_lds_dwordx4 v[88:89], off
	v_lshl_add_u64 v[88:89], v[78:79], 0, s[56:57]
	s_mov_b32 m0, s44
	s_nop 0
	global_load_lds_dwordx4 v[88:89], off
	ds_read_b128 v[88:91], v80 offset:32768
	ds_read_b128 v[92:95], v82 offset:49152
	ds_read_b128 v[96:99], v82 offset:53248
	s_waitcnt lgkmcnt(0)
	v_mfma_f32_32x32x16_bf16 v[48:63], v[88:91], v[92:95], v[48:63]
	s_mov_b32 m0, s20
	v_mfma_f32_32x32x16_bf16 v[32:47], v[88:91], v[96:99], v[32:47]
	ds_read_b128 v[88:91], v80 offset:36864
	s_waitcnt lgkmcnt(0)
	v_mfma_f32_32x32x16_bf16 v[16:31], v[88:91], v[92:95], v[16:31]
	v_mfma_f32_32x32x16_bf16 v[0:15], v[88:91], v[96:99], v[0:15]
	ds_read_b128 v[88:91], v81 offset:32768
	ds_read_b128 v[92:95], v83 offset:49152
	ds_read_b128 v[96:99], v83 offset:53248
	s_waitcnt lgkmcnt(0)
	v_mfma_f32_32x32x16_bf16 v[48:63], v[88:91], v[92:95], v[48:63]
	v_mfma_f32_32x32x16_bf16 v[32:47], v[88:91], v[96:99], v[32:47]
	ds_read_b128 v[88:91], v81 offset:36864
	s_waitcnt lgkmcnt(0)
	v_mfma_f32_32x32x16_bf16 v[16:31], v[88:91], v[92:95], v[16:31]
	v_mfma_f32_32x32x16_bf16 v[0:15], v[88:91], v[96:99], v[0:15]
	ds_read_b128 v[88:91], v84 offset:32768
	ds_read_b128 v[92:95], v85 offset:49152
	ds_read_b128 v[96:99], v85 offset:53248
	s_waitcnt lgkmcnt(0)
	v_mfma_f32_32x32x16_bf16 v[48:63], v[88:91], v[92:95], v[48:63]
	v_mfma_f32_32x32x16_bf16 v[32:47], v[88:91], v[96:99], v[32:47]
	ds_read_b128 v[88:91], v84 offset:36864
	s_waitcnt lgkmcnt(0)
	v_mfma_f32_32x32x16_bf16 v[16:31], v[88:91], v[92:95], v[16:31]
	v_mfma_f32_32x32x16_bf16 v[0:15], v[88:91], v[96:99], v[0:15]
	ds_read_b128 v[88:91], v86 offset:32768
	ds_read_b128 v[92:95], v87 offset:49152
	ds_read_b128 v[96:99], v87 offset:53248
	s_waitcnt lgkmcnt(0)
	v_mfma_f32_32x32x16_bf16 v[48:63], v[88:91], v[92:95], v[48:63]
	v_mfma_f32_32x32x16_bf16 v[32:47], v[88:91], v[96:99], v[32:47]
	ds_read_b128 v[88:91], v86 offset:36864
	s_waitcnt vmcnt(0)
	s_waitcnt vmcnt(0) lgkmcnt(0)
	s_barrier
; #define WAIT_V0() asm volatile("s_waitcnt vmcnt(0)" ::: "memory")
; DI void gemm_core(char* smem, int nk, const char* Ab, const char* Bb, const unsigned (&aoff)[4], const unsigned (&boff)[4],
;                   f32x16 (&acc)[2][2]) {
;     ...
;   for (int kt = 0; kt < nk; ++kt) {
;     const int cur = kt & 1;
;     if (kt + 1 < nk) stage(cur ^ 1, kt + 1);
;     const char* sb = smem + cur * STAGE_B;
; #pragma unroll
;     for (int ks = 0; ks < 4; ++ks) {
;       bf16x8 af[2], bfr[2];
; #pragma unroll
;       for (int mb = 0; mb < 2; ++mb) af[mb] = *(const bf16x8*)(sb + a_base + mb * 4096 + xo[ks]);
; #pragma unroll
;       for (int nb = 0; nb < 2; ++nb) bfr[nb] = *(const bf16x8*)(sb + b_base + nb * 4096 + xo[ks]);
; #pragma unroll
;       for (int mb = 0; mb < 2; ++mb)
; #pragma unroll
;         for (int nb = 0; nb < 2; ++nb)
;           acc[mb][nb] = __builtin_amdgcn_mfma_f32_32x32x16_bf16(af[mb], bfr[nb], acc[mb][nb], 0, 0, 0);
;     }
;     WAIT_V0();
;     __syncthreads();
;   }
	v_mfma_f32_32x32x16_bf16 v[16:31], v[88:91], v[92:95], v[16:31]
	v_mfma_f32_32x32x16_bf16 v[0:15], v[88:91], v[96:99], v[0:15]
	ds_read_b128 v[88:91], v80
	ds_read_b128 v[92:95], v82 offset:16384
	ds_read_b128 v[96:99], v82 offset:20480
	v_lshl_add_u64 v[116:117], v[64:65], 0, s[58:59]
	global_load_lds_dwordx4 v[116:117], off
	v_lshl_add_u64 v[118:119], v[66:67], 0, s[58:59]
	s_mov_b32 m0, s21
	s_nop 0
	global_load_lds_dwordx4 v[118:119], off
	v_lshl_add_u64 v[116:117], v[68:69], 0, s[58:59]
	s_mov_b32 m0, s22
	s_nop 0
	global_load_lds_dwordx4 v[116:117], off
	v_lshl_add_u64 v[118:119], v[70:71], 0, s[58:59]
	s_mov_b32 m0, s1
	s_nop 0
	global_load_lds_dwordx4 v[118:119], off
	v_lshl_add_u64 v[116:117], v[72:73], 0, s[58:59]
	s_mov_b32 m0, s16
	s_nop 0
	global_load_lds_dwordx4 v[116:117], off
	v_lshl_add_u64 v[118:119], v[74:75], 0, s[58:59]
	s_mov_b32 m0, s17
	s_nop 0
	global_load_lds_dwordx4 v[118:119], off
	v_lshl_add_u64 v[116:117], v[76:77], 0, s[58:59]
	s_mov_b32 m0, s18
	s_nop 0
	global_load_lds_dwordx4 v[116:117], off
	v_lshl_add_u64 v[118:119], v[78:79], 0, s[58:59]
	s_mov_b32 m0, s19
	s_nop 0
	global_load_lds_dwordx4 v[118:119], off
	s_waitcnt lgkmcnt(0)
	v_mfma_f32_32x32x16_bf16 v[48:63], v[88:91], v[92:95], v[48:63]
	s_mov_b32 m0, s23
	v_mfma_f32_32x32x16_bf16 v[32:47], v[88:91], v[96:99], v[32:47]
	ds_read_b128 v[88:91], v80 offset:4096
	s_waitcnt lgkmcnt(0)
	v_mfma_f32_32x32x16_bf16 v[16:31], v[88:91], v[92:95], v[16:31]
	v_mfma_f32_32x32x16_bf16 v[0:15], v[88:91], v[96:99], v[0:15]
	ds_read_b128 v[88:91], v81
	ds_read_b128 v[92:95], v83 offset:16384
	ds_read_b128 v[96:99], v83 offset:20480
	s_waitcnt lgkmcnt(0)
	v_mfma_f32_32x32x16_bf16 v[48:63], v[88:91], v[92:95], v[48:63]
	v_mfma_f32_32x32x16_bf16 v[32:47], v[88:91], v[96:99], v[32:47]
	ds_read_b128 v[88:91], v81 offset:4096
	s_waitcnt lgkmcnt(0)
	v_mfma_f32_32x32x16_bf16 v[16:31], v[88:91], v[92:95], v[16:31]
	v_mfma_f32_32x32x16_bf16 v[0:15], v[88:91], v[96:99], v[0:15]
	ds_read_b128 v[88:91], v84
	ds_read_b128 v[92:95], v85 offset:16384
	ds_read_b128 v[96:99], v85 offset:20480
	s_waitcnt lgkmcnt(0)
	v_mfma_f32_32x32x16_bf16 v[48:63], v[88:91], v[92:95], v[48:63]
	v_mfma_f32_32x32x16_bf16 v[32:47], v[88:91], v[96:99], v[32:47]
	ds_read_b128 v[88:91], v84 offset:4096
	s_waitcnt lgkmcnt(0)
	v_mfma_f32_32x32x16_bf16 v[16:31], v[88:91], v[92:95], v[16:31]
	v_mfma_f32_32x32x16_bf16 v[0:15], v[88:91], v[96:99], v[0:15]
	ds_read_b128 v[88:91], v86
	ds_read_b128 v[92:95], v87 offset:16384
	ds_read_b128 v[96:99], v87 offset:20480
	s_waitcnt lgkmcnt(0)
	v_mfma_f32_32x32x16_bf16 v[48:63], v[88:91], v[92:95], v[48:63]
	v_mfma_f32_32x32x16_bf16 v[32:47], v[88:91], v[96:99], v[32:47]
	ds_read_b128 v[88:91], v86 offset:4096
	s_waitcnt vmcnt(0)
	s_waitcnt vmcnt(0) lgkmcnt(0)
	s_barrier
	v_mfma_f32_32x32x16_bf16 v[16:31], v[88:91], v[92:95], v[16:31]
	v_mfma_f32_32x32x16_bf16 v[0:15], v[88:91], v[96:99], v[0:15]
	ds_read_b128 v[88:91], v80 offset:32768
	ds_read_b128 v[92:95], v82 offset:49152
	ds_read_b128 v[96:99], v82 offset:53248
	v_lshl_add_u64 v[116:117], v[64:65], 0, s[60:61]
	global_load_lds_dwordx4 v[116:117], off
	v_lshl_add_u64 v[118:119], v[66:67], 0, s[60:61]
	s_mov_b32 m0, s28
	s_nop 0
	global_load_lds_dwordx4 v[118:119], off
	v_lshl_add_u64 v[116:117], v[68:69], 0, s[60:61]
	s_mov_b32 m0, s29
	s_nop 0
	global_load_lds_dwordx4 v[116:117], off
	v_lshl_add_u64 v[118:119], v[70:71], 0, s[60:61]
	s_mov_b32 m0, s40
	s_nop 0
	global_load_lds_dwordx4 v[118:119], off
	v_lshl_add_u64 v[116:117], v[72:73], 0, s[60:61]
	s_mov_b32 m0, s41
	s_nop 0
	global_load_lds_dwordx4 v[116:117], off
	v_lshl_add_u64 v[118:119], v[74:75], 0, s[60:61]
	s_mov_b32 m0, s42
	s_nop 0
	global_load_lds_dwordx4 v[118:119], off
	v_lshl_add_u64 v[116:117], v[76:77], 0, s[60:61]
	s_mov_b32 m0, s43
	s_nop 0
	global_load_lds_dwordx4 v[116:117], off
	v_lshl_add_u64 v[118:119], v[78:79], 0, s[60:61]
	s_mov_b32 m0, s44
	s_nop 0
	global_load_lds_dwordx4 v[118:119], off
	s_waitcnt lgkmcnt(0)
	v_mfma_f32_32x32x16_bf16 v[48:63], v[88:91], v[92:95], v[48:63]
	s_mov_b32 m0, s20
	v_mfma_f32_32x32x16_bf16 v[32:47], v[88:91], v[96:99], v[32:47]
	ds_read_b128 v[88:91], v80 offset:36864
	s_waitcnt lgkmcnt(0)
	v_mfma_f32_32x32x16_bf16 v[16:31], v[88:91], v[92:95], v[16:31]
	v_mfma_f32_32x32x16_bf16 v[0:15], v[88:91], v[96:99], v[0:15]
	ds_read_b128 v[88:91], v81 offset:32768
	ds_read_b128 v[92:95], v83 offset:49152
	ds_read_b128 v[96:99], v83 offset:53248
	s_waitcnt lgkmcnt(0)
	v_mfma_f32_32x32x16_bf16 v[48:63], v[88:91], v[92:95], v[48:63]
	v_mfma_f32_32x32x16_bf16 v[32:47], v[88:91], v[96:99], v[32:47]
	ds_read_b128 v[88:91], v81 offset:36864
	s_waitcnt lgkmcnt(0)
	v_mfma_f32_32x32x16_bf16 v[16:31], v[88:91], v[92:95], v[16:31]
	v_mfma_f32_32x32x16_bf16 v[0:15], v[88:91], v[96:99], v[0:15]
	ds_read_b128 v[88:91], v84 offset:32768
	ds_read_b128 v[92:95], v85 offset:49152
	ds_read_b128 v[96:99], v85 offset:53248
	s_waitcnt lgkmcnt(0)
	v_mfma_f32_32x32x16_bf16 v[48:63], v[88:91], v[92:95], v[48:63]
	v_mfma_f32_32x32x16_bf16 v[32:47], v[88:91], v[96:99], v[32:47]
	ds_read_b128 v[88:91], v84 offset:36864
	s_waitcnt lgkmcnt(0)
	v_mfma_f32_32x32x16_bf16 v[16:31], v[88:91], v[92:95], v[16:31]
	v_mfma_f32_32x32x16_bf16 v[0:15], v[88:91], v[96:99], v[0:15]
	ds_read_b128 v[88:91], v86 offset:32768
	ds_read_b128 v[92:95], v87 offset:49152
	ds_read_b128 v[96:99], v87 offset:53248
	s_waitcnt lgkmcnt(0)
	v_mfma_f32_32x32x16_bf16 v[48:63], v[88:91], v[92:95], v[48:63]
	v_mfma_f32_32x32x16_bf16 v[32:47], v[88:91], v[96:99], v[32:47]
	ds_read_b128 v[88:91], v86 offset:36864
	s_waitcnt vmcnt(0)
	s_waitcnt vmcnt(0) lgkmcnt(0)
	s_barrier
; #define WAIT_V0() asm volatile("s_waitcnt vmcnt(0)" ::: "memory")
; DI void gemm_core(char* smem, int nk, const char* Ab, const char* Bb, const unsigned (&aoff)[4], const unsigned (&boff)[4],
;                   f32x16 (&acc)[2][2]) {
;     ...
;   for (int kt = 0; kt < nk; ++kt) {
;     const int cur = kt & 1;
;     if (kt + 1 < nk) stage(cur ^ 1, kt + 1);
;     const char* sb = smem + cur * STAGE_B;
; #pragma unroll
;     for (int ks = 0; ks < 4; ++ks) {
;       bf16x8 af[2], bfr[2];
; #pragma unroll
;       for (int mb = 0; mb < 2; ++mb) af[mb] = *(const bf16x8*)(sb + a_base + mb * 4096 + xo[ks]);
; #pragma unroll
;       for (int nb = 0; nb < 2; ++nb) bfr[nb] = *(const bf16x8*)(sb + b_base + nb * 4096 + xo[ks]);
; #pragma unroll
;       for (int mb = 0; mb < 2; ++mb)
; #pragma unroll
;         for (int nb = 0; nb < 2; ++nb)
;           acc[mb][nb] = __builtin_amdgcn_mfma_f32_32x32x16_bf16(af[mb], bfr[nb], acc[mb][nb], 0, 0, 0);
;     }
;     WAIT_V0();
;     __syncthreads();
;   }
	v_mfma_f32_32x32x16_bf16 v[16:31], v[88:91], v[92:95], v[16:31]
	v_mfma_f32_32x32x16_bf16 v[0:15], v[88:91], v[96:99], v[0:15]
	ds_read_b128 v[88:91], v80
	ds_read_b128 v[92:95], v82 offset:16384
	ds_read_b128 v[96:99], v82 offset:20480
	v_lshl_add_u64 v[116:117], v[64:65], 0, s[62:63]
	global_load_lds_dwordx4 v[116:117], off
	v_lshl_add_u64 v[118:119], v[66:67], 0, s[62:63]
	s_mov_b32 m0, s21
	s_nop 0
	global_load_lds_dwordx4 v[118:119], off
	v_lshl_add_u64 v[116:117], v[68:69], 0, s[62:63]
	s_mov_b32 m0, s22
	s_nop 0
	global_load_lds_dwordx4 v[116:117], off
	v_lshl_add_u64 v[118:119], v[70:71], 0, s[62:63]
	s_mov_b32 m0, s1
	s_nop 0
	global_load_lds_dwordx4 v[118:119], off
	v_lshl_add_u64 v[116:117], v[72:73], 0, s[62:63]
	s_mov_b32 m0, s16
	s_nop 0
	global_load_lds_dwordx4 v[116:117], off
	v_lshl_add_u64 v[118:119], v[74:75], 0, s[62:63]
	s_mov_b32 m0, s17
	s_nop 0
	global_load_lds_dwordx4 v[118:119], off
	v_lshl_add_u64 v[116:117], v[76:77], 0, s[62:63]
	s_mov_b32 m0, s18
	s_nop 0
	global_load_lds_dwordx4 v[116:117], off
	v_lshl_add_u64 v[118:119], v[78:79], 0, s[62:63]
	s_mov_b32 m0, s19
	s_nop 0
	global_load_lds_dwordx4 v[118:119], off
	s_waitcnt lgkmcnt(0)
	v_mfma_f32_32x32x16_bf16 v[48:63], v[88:91], v[92:95], v[48:63]
	s_mov_b32 m0, s23
	v_mfma_f32_32x32x16_bf16 v[32:47], v[88:91], v[96:99], v[32:47]
	ds_read_b128 v[88:91], v80 offset:4096
	s_waitcnt lgkmcnt(0)
	v_mfma_f32_32x32x16_bf16 v[16:31], v[88:91], v[92:95], v[16:31]
	v_mfma_f32_32x32x16_bf16 v[0:15], v[88:91], v[96:99], v[0:15]
	ds_read_b128 v[88:91], v81
	ds_read_b128 v[92:95], v83 offset:16384
	ds_read_b128 v[96:99], v83 offset:20480
	s_waitcnt lgkmcnt(0)
	v_mfma_f32_32x32x16_bf16 v[48:63], v[88:91], v[92:95], v[48:63]
	v_mfma_f32_32x32x16_bf16 v[32:47], v[88:91], v[96:99], v[32:47]
	ds_read_b128 v[88:91], v81 offset:4096
	s_waitcnt lgkmcnt(0)
	v_mfma_f32_32x32x16_bf16 v[16:31], v[88:91], v[92:95], v[16:31]
	v_mfma_f32_32x32x16_bf16 v[0:15], v[88:91], v[96:99], v[0:15]
	ds_read_b128 v[88:91], v84
	ds_read_b128 v[92:95], v85 offset:16384
	ds_read_b128 v[96:99], v85 offset:20480
	s_waitcnt lgkmcnt(0)
	v_mfma_f32_32x32x16_bf16 v[48:63], v[88:91], v[92:95], v[48:63]
	v_mfma_f32_32x32x16_bf16 v[32:47], v[88:91], v[96:99], v[32:47]
	ds_read_b128 v[88:91], v84 offset:4096
	s_waitcnt lgkmcnt(0)
	v_mfma_f32_32x32x16_bf16 v[16:31], v[88:91], v[92:95], v[16:31]
	v_mfma_f32_32x32x16_bf16 v[0:15], v[88:91], v[96:99], v[0:15]
	ds_read_b128 v[88:91], v86
	ds_read_b128 v[92:95], v87 offset:16384
	ds_read_b128 v[96:99], v87 offset:20480
	s_waitcnt lgkmcnt(0)
	v_mfma_f32_32x32x16_bf16 v[48:63], v[88:91], v[92:95], v[48:63]
	v_mfma_f32_32x32x16_bf16 v[32:47], v[88:91], v[96:99], v[32:47]
	ds_read_b128 v[88:91], v86 offset:4096
	s_waitcnt vmcnt(0)
	s_waitcnt vmcnt(0) lgkmcnt(0)
	s_barrier
	v_mfma_f32_32x32x16_bf16 v[16:31], v[88:91], v[92:95], v[16:31]
	v_mfma_f32_32x32x16_bf16 v[0:15], v[88:91], v[96:99], v[0:15]
	v_lshl_add_u64 v[88:89], v[64:65], 0, s[64:65]
	global_load_lds_dwordx4 v[88:89], off
	v_lshl_add_u64 v[88:89], v[66:67], 0, s[64:65]
	s_mov_b32 m0, s28
	v_lshl_add_u64 v[64:65], v[64:65], 0, s[66:67]
	global_load_lds_dwordx4 v[88:89], off
	v_lshl_add_u64 v[88:89], v[68:69], 0, s[64:65]
	s_mov_b32 m0, s29
	s_nop 0
	global_load_lds_dwordx4 v[88:89], off
	v_lshl_add_u64 v[88:89], v[70:71], 0, s[64:65]
	s_mov_b32 m0, s40
	s_nop 0
	global_load_lds_dwordx4 v[88:89], off
	v_lshl_add_u64 v[88:89], v[72:73], 0, s[64:65]
	s_mov_b32 m0, s41
	s_nop 0
	global_load_lds_dwordx4 v[88:89], off
	v_lshl_add_u64 v[88:89], v[74:75], 0, s[64:65]
	s_mov_b32 m0, s42
	s_nop 0
	global_load_lds_dwordx4 v[88:89], off
	v_lshl_add_u64 v[88:89], v[76:77], 0, s[64:65]
	s_mov_b32 m0, s43
	s_nop 0
	global_load_lds_dwordx4 v[88:89], off
	v_lshl_add_u64 v[88:89], v[78:79], 0, s[64:65]
	s_mov_b32 m0, s44
	s_nop 0
	global_load_lds_dwordx4 v[88:89], off
	ds_read_b128 v[88:91], v80 offset:32768
	ds_read_b128 v[92:95], v82 offset:49152
	ds_read_b128 v[96:99], v82 offset:53248
	s_waitcnt lgkmcnt(0)
	v_mfma_f32_32x32x16_bf16 v[48:63], v[88:91], v[92:95], v[48:63]
	s_mov_b32 m0, s20
	v_mfma_f32_32x32x16_bf16 v[32:47], v[88:91], v[96:99], v[32:47]
	ds_read_b128 v[88:91], v80 offset:36864
	s_waitcnt lgkmcnt(0)
	v_mfma_f32_32x32x16_bf16 v[16:31], v[88:91], v[92:95], v[16:31]
	v_mfma_f32_32x32x16_bf16 v[0:15], v[88:91], v[96:99], v[0:15]
	ds_read_b128 v[88:91], v81 offset:32768
	ds_read_b128 v[92:95], v83 offset:49152
	ds_read_b128 v[96:99], v83 offset:53248
	s_waitcnt lgkmcnt(0)
	v_mfma_f32_32x32x16_bf16 v[48:63], v[88:91], v[92:95], v[48:63]
	v_mfma_f32_32x32x16_bf16 v[32:47], v[88:91], v[96:99], v[32:47]
	ds_read_b128 v[88:91], v81 offset:36864
	s_waitcnt lgkmcnt(0)
	v_mfma_f32_32x32x16_bf16 v[16:31], v[88:91], v[92:95], v[16:31]
	v_mfma_f32_32x32x16_bf16 v[0:15], v[88:91], v[96:99], v[0:15]
	ds_read_b128 v[88:91], v84 offset:32768
	ds_read_b128 v[92:95], v85 offset:49152
	ds_read_b128 v[96:99], v85 offset:53248
	s_waitcnt lgkmcnt(0)
	v_mfma_f32_32x32x16_bf16 v[48:63], v[88:91], v[92:95], v[48:63]
	v_mfma_f32_32x32x16_bf16 v[32:47], v[88:91], v[96:99], v[32:47]
	ds_read_b128 v[88:91], v84 offset:36864
	s_waitcnt lgkmcnt(0)
	v_mfma_f32_32x32x16_bf16 v[16:31], v[88:91], v[92:95], v[16:31]
	v_mfma_f32_32x32x16_bf16 v[0:15], v[88:91], v[96:99], v[0:15]
	ds_read_b128 v[88:91], v86 offset:32768
	ds_read_b128 v[92:95], v87 offset:49152
	ds_read_b128 v[96:99], v87 offset:53248
	s_waitcnt lgkmcnt(0)
	v_mfma_f32_32x32x16_bf16 v[48:63], v[88:91], v[92:95], v[48:63]
	v_mfma_f32_32x32x16_bf16 v[32:47], v[88:91], v[96:99], v[32:47]
	ds_read_b128 v[88:91], v86 offset:36864
	s_waitcnt vmcnt(0)
	s_waitcnt vmcnt(0) lgkmcnt(0)
	s_barrier
; #define WAIT_V0() asm volatile("s_waitcnt vmcnt(0)" ::: "memory")
; DI void gemm_core(char* smem, int nk, const char* Ab, const char* Bb, const unsigned (&aoff)[4], const unsigned (&boff)[4],
;                   f32x16 (&acc)[2][2]) {
;     ...
;   for (int kt = 0; kt < nk; ++kt) {
;     const int cur = kt & 1;
;     if (kt + 1 < nk) stage(cur ^ 1, kt + 1);
;     const char* sb = smem + cur * STAGE_B;
; #pragma unroll
;     for (int ks = 0; ks < 4; ++ks) {
;       bf16x8 af[2], bfr[2];
; #pragma unroll
;       for (int mb = 0; mb < 2; ++mb) af[mb] = *(const bf16x8*)(sb + a_base + mb * 4096 + xo[ks]);
; #pragma unroll
;       for (int nb = 0; nb < 2; ++nb) bfr[nb] = *(const bf16x8*)(sb + b_base + nb * 4096 + xo[ks]);
; #pragma unroll
;       for (int mb = 0; mb < 2; ++mb)
; #pragma unroll
;         for (int nb = 0; nb < 2; ++nb)
;           acc[mb][nb] = __builtin_amdgcn_mfma_f32_32x32x16_bf16(af[mb], bfr[nb], acc[mb][nb], 0, 0, 0);
;     }
;     WAIT_V0();
;     __syncthreads();
;   }
; DI void phase_gemm_in(const Params& P, int layer, char* smem) {
;     ...
;     epi_foreach(acc, [&](int row, int col, float v) __attribute__((always_inline)) {
;       const int c = n0 + col;
;       Cs[row * 136 + col] = (c >= C_QI && c < C_CQ) ? f2h(v) : f2bf(v);
;     });
	global_load_lds_dwordx4 v[64:65], off
	v_lshl_add_u64 v[64:65], v[66:67], 0, s[66:67]
	s_mov_b32 m0, s21
	v_mfma_f32_32x32x16_bf16 v[16:31], v[88:91], v[92:95], v[16:31]
	global_load_lds_dwordx4 v[64:65], off
	v_lshl_add_u64 v[64:65], v[68:69], 0, s[66:67]
	s_mov_b32 m0, s22
	s_nop 0
	global_load_lds_dwordx4 v[64:65], off
	v_lshl_add_u64 v[64:65], v[70:71], 0, s[66:67]
	s_mov_b32 m0, s1
	v_mfma_f32_32x32x16_bf16 v[0:15], v[88:91], v[96:99], v[0:15]
	global_load_lds_dwordx4 v[64:65], off
	v_lshl_add_u64 v[64:65], v[72:73], 0, s[66:67]
	s_mov_b32 m0, s16
	v_mov_b32_e32 v96, v161
	global_load_lds_dwordx4 v[64:65], off
	v_lshl_add_u64 v[64:65], v[74:75], 0, s[66:67]
	s_mov_b32 m0, s17
	v_mov_b32_e32 v97, v161
	global_load_lds_dwordx4 v[64:65], off
	v_lshl_add_u64 v[64:65], v[76:77], 0, s[66:67]
	s_mov_b32 m0, s18
	s_add_i32 s1, s10, 0xfffffa00
	global_load_lds_dwordx4 v[64:65], off
	v_lshl_add_u64 v[64:65], v[78:79], 0, s[66:67]
	s_mov_b32 m0, s19
	s_nop 0
	global_load_lds_dwordx4 v[64:65], off
	ds_read_b128 v[64:67], v80
	ds_read_b128 v[68:71], v82 offset:16384
	ds_read_b128 v[72:75], v82 offset:20480
	s_waitcnt lgkmcnt(0)
	v_mfma_f32_32x32x16_bf16 v[48:63], v[64:67], v[68:71], v[48:63]
	v_mfma_f32_32x32x16_bf16 v[32:47], v[64:67], v[72:75], v[32:47]
	ds_read_b128 v[64:67], v80 offset:4096
	s_waitcnt lgkmcnt(0)
	v_mfma_f32_32x32x16_bf16 v[16:31], v[64:67], v[68:71], v[16:31]
	v_mfma_f32_32x32x16_bf16 v[0:15], v[64:67], v[72:75], v[0:15]
	ds_read_b128 v[64:67], v81
	ds_read_b128 v[68:71], v83 offset:16384
	ds_read_b128 v[72:75], v83 offset:20480
	s_waitcnt lgkmcnt(0)
	v_mfma_f32_32x32x16_bf16 v[48:63], v[64:67], v[68:71], v[48:63]
	v_mfma_f32_32x32x16_bf16 v[32:47], v[64:67], v[72:75], v[32:47]
	ds_read_b128 v[64:67], v81 offset:4096
	s_waitcnt lgkmcnt(0)
	v_mfma_f32_32x32x16_bf16 v[16:31], v[64:67], v[68:71], v[16:31]
	v_mfma_f32_32x32x16_bf16 v[0:15], v[64:67], v[72:75], v[0:15]
	ds_read_b128 v[64:67], v84
	ds_read_b128 v[68:71], v85 offset:16384
	ds_read_b128 v[72:75], v85 offset:20480
	s_waitcnt lgkmcnt(0)
	v_mfma_f32_32x32x16_bf16 v[48:63], v[64:67], v[68:71], v[48:63]
	v_mfma_f32_32x32x16_bf16 v[32:47], v[64:67], v[72:75], v[32:47]
	ds_read_b128 v[64:67], v84 offset:4096
	s_waitcnt lgkmcnt(0)
	v_mfma_f32_32x32x16_bf16 v[16:31], v[64:67], v[68:71], v[16:31]
	v_mfma_f32_32x32x16_bf16 v[0:15], v[64:67], v[72:75], v[0:15]
	ds_read_b128 v[64:67], v86
	ds_read_b128 v[68:71], v87 offset:16384
	ds_read_b128 v[72:75], v87 offset:20480
	s_waitcnt lgkmcnt(0)
	v_mfma_f32_32x32x16_bf16 v[48:63], v[64:67], v[68:71], v[48:63]
	v_mfma_f32_32x32x16_bf16 v[32:47], v[64:67], v[72:75], v[32:47]
	ds_read_b128 v[64:67], v86 offset:4096
	s_waitcnt vmcnt(0)
	s_waitcnt vmcnt(0) lgkmcnt(0)
	s_barrier
	v_mfma_f32_32x32x16_bf16 v[16:31], v[64:67], v[68:71], v[16:31]
	v_mfma_f32_32x32x16_bf16 v[0:15], v[64:67], v[72:75], v[0:15]
	ds_read_b128 v[64:67], v80 offset:32768
	ds_read_b128 v[68:71], v82 offset:49152
	ds_read_b128 v[72:75], v82 offset:53248
	s_waitcnt lgkmcnt(1)
	v_mfma_f32_32x32x16_bf16 v[48:63], v[64:67], v[68:71], v[48:63]
	s_waitcnt lgkmcnt(0)
	v_mfma_f32_32x32x16_bf16 v[32:47], v[64:67], v[72:75], v[32:47]
	ds_read_b128 v[64:67], v80 offset:36864
	s_waitcnt lgkmcnt(0)
	v_mfma_f32_32x32x16_bf16 v[16:31], v[64:67], v[68:71], v[16:31]
	v_mfma_f32_32x32x16_bf16 v[0:15], v[64:67], v[72:75], v[0:15]
	ds_read_b128 v[64:67], v81 offset:32768
	ds_read_b128 v[68:71], v83 offset:49152
	ds_read_b128 v[72:75], v83 offset:53248
	s_waitcnt lgkmcnt(1)
	v_mfma_f32_32x32x16_bf16 v[48:63], v[64:67], v[68:71], v[48:63]
	s_waitcnt lgkmcnt(0)
	v_mfma_f32_32x32x16_bf16 v[32:47], v[64:67], v[72:75], v[32:47]
	ds_read_b128 v[64:67], v81 offset:36864
	s_waitcnt lgkmcnt(0)
	v_mfma_f32_32x32x16_bf16 v[16:31], v[64:67], v[68:71], v[16:31]
	ds_read_b128 v[68:71], v84 offset:32768
	ds_read_b128 v[76:79], v84 offset:36864
	v_mfma_f32_32x32x16_bf16 v[0:15], v[64:67], v[72:75], v[0:15]
	ds_read_b128 v[64:67], v85 offset:49152
	ds_read_b128 v[72:75], v85 offset:53248
	ds_read_b128 v[80:83], v86 offset:32768
	ds_read_b128 v[88:91], v86 offset:36864
	ds_read_b128 v[92:95], v87 offset:49152
	ds_read_b128 v[84:87], v87 offset:53248
	s_waitcnt vmcnt(0)
	s_waitcnt lgkmcnt(0)
	s_barrier
	v_mfma_f32_32x32x16_bf16 v[48:63], v[68:71], v[64:67], v[48:63]
	v_mfma_f32_32x32x16_bf16 v[48:63], v[80:83], v[92:95], v[48:63]
	v_mfma_f32_32x32x16_bf16 v[32:47], v[68:71], v[72:75], v[32:47]
	v_lshrrev_b32_e32 v69, 3, v96
	v_lshrrev_b32_e32 v68, 1, v97
	v_and_b32_e32 v69, 4, v69
	v_and_b32_e32 v70, 31, v96
	v_and_or_b32 v68, v68, s7, v69
	s_nop 5
	v_cvt_f16_f32_e32 v69, v48
	v_and_or_b32 v70, v97, 64, v70
	v_or_b32_e32 v71, s1, v70
	v_cmp_gt_u32_e64 s[40:41], s45, v71
	v_cvt_pk_bf16_f32 v48, v48, s0
	v_mfma_f32_32x32x16_bf16 v[16:31], v[76:79], v[64:67], v[16:31]
	v_cndmask_b32_e64 v69, v48, v69, s[40:41]
	v_mul_lo_u32 v48, v68, s97
	v_cvt_f16_f32_e32 v68, v49
	v_cvt_pk_bf16_f32 v49, v49, s0
	v_lshl_add_u32 v48, v70, 1, v48
	v_cvt_f16_f32_e32 v64, v51
	v_cndmask_b32_e64 v49, v49, v68, s[40:41]
	ds_write_b16 v48, v49 offset:272
	v_cvt_f16_f32_e32 v49, v50
	v_cvt_pk_bf16_f32 v50, v50, s0
	v_mfma_f32_32x32x16_bf16 v[0:15], v[76:79], v[72:75], v[0:15]
	ds_write_b16 v48, v69
	v_cndmask_b32_e64 v49, v50, v49, s[40:41]
	ds_write_b16 v48, v49 offset:544
	v_cvt_pk_bf16_f32 v49, v51, s0
	v_cndmask_b32_e64 v49, v49, v64, s[40:41]
	ds_write_b16 v48, v49 offset:816
	v_cvt_f16_f32_e32 v49, v52
	v_cvt_f16_f32_e32 v51, v53
	v_cvt_pk_bf16_f32 v50, v52, s0
	v_mfma_f32_32x32x16_bf16 v[32:47], v[80:83], v[84:87], v[32:47]
	v_cndmask_b32_e64 v49, v50, v49, s[40:41]
	v_cvt_f16_f32_e32 v50, v54
	ds_write_b16 v48, v49 offset:2176
; template <class F>
; DI void epi_foreach(const f32x16 (&acc)[2][2], F f) {
;     ...
;       for (int r = 0; r < 16; ++r) {
;         const int row = wm * 64 + mb * 32 + (r & 3) + 8 * (r >> 2) + 4 * (lane >> 5);
;         const int col = wn * 64 + nb * 32 + (lane & 31);
;         f(row, col, acc[mb][nb][r]);
;         if ((r & 7) == 7) __builtin_amdgcn_sched_barrier(0);
; DI void phase_gemm_in(const Params& P, int layer, char* smem) {
;     ...
;     epi_foreach(acc, [&](int row, int col, float v) __attribute__((always_inline)) {
;       const int c = n0 + col;
;       Cs[row * 136 + col] = (c >= C_QI && c < C_CQ) ? f2h(v) : f2bf(v);
;     });
	v_cvt_pk_bf16_f32 v49, v53, s0
	v_cndmask_b32_e64 v49, v49, v51, s[40:41]
	v_cvt_f16_f32_e32 v51, v55
	ds_write_b16 v48, v49 offset:2448
	v_cvt_pk_bf16_f32 v49, v54, s0
	v_cndmask_b32_e64 v49, v49, v50, s[40:41]
	ds_write_b16 v48, v49 offset:2720
	v_cvt_pk_bf16_f32 v49, v55, s0
	v_cndmask_b32_e64 v49, v49, v51, s[40:41]
	v_mfma_f32_32x32x16_bf16 v[16:31], v[88:91], v[92:95], v[16:31]
	ds_write_b16 v48, v49 offset:2992
	v_mfma_f32_32x32x16_bf16 v[0:15], v[88:91], v[84:87], v[0:15]
	v_cvt_f16_f32_e32 v49, v56
	v_cvt_pk_bf16_f32 v50, v56, s0
	v_cndmask_b32_e64 v49, v50, v49, s[40:41]
	ds_write_b16 v48, v49 offset:4352
	v_cvt_f16_f32_e32 v49, v57
	v_cvt_pk_bf16_f32 v50, v57, s0
	v_cndmask_b32_e64 v49, v50, v49, s[40:41]
	ds_write_b16 v48, v49 offset:4624
	v_cvt_f16_f32_e32 v49, v58
	v_cvt_pk_bf16_f32 v50, v58, s0
	v_cndmask_b32_e64 v49, v50, v49, s[40:41]
	ds_write_b16 v48, v49 offset:4896
	v_cvt_f16_f32_e32 v49, v59
	v_cvt_pk_bf16_f32 v50, v59, s0
	v_cndmask_b32_e64 v49, v50, v49, s[40:41]
	ds_write_b16 v48, v49 offset:5168
	v_cvt_f16_f32_e32 v49, v60
	v_cvt_pk_bf16_f32 v50, v60, s0
	v_cndmask_b32_e64 v49, v50, v49, s[40:41]
	ds_write_b16 v48, v49 offset:6528
	v_cvt_f16_f32_e32 v49, v61
	v_cvt_pk_bf16_f32 v50, v61, s0
	v_cndmask_b32_e64 v49, v50, v49, s[40:41]
	ds_write_b16 v48, v49 offset:6800
	v_cvt_f16_f32_e32 v49, v62
	v_cvt_pk_bf16_f32 v50, v62, s0
	v_cndmask_b32_e64 v49, v50, v49, s[40:41]
	ds_write_b16 v48, v49 offset:7072
	v_cvt_f16_f32_e32 v49, v63
	v_cvt_pk_bf16_f32 v50, v63, s0
	v_cndmask_b32_e64 v49, v50, v49, s[40:41]
	ds_write_b16 v48, v49 offset:7344
	s_add_i32 s1, s10, 0xfffffa20
	v_or_b32_e32 v49, s1, v70
	v_cmp_gt_u32_e32 vcc, s45, v49
	v_cvt_f16_f32_e32 v49, v32
	v_cvt_pk_bf16_f32 v32, v32, s0
	v_cndmask_b32_e32 v32, v32, v49, vcc
	ds_write_b16 v48, v32 offset:64
	v_cvt_f16_f32_e32 v32, v33
	v_cvt_pk_bf16_f32 v33, v33, s0
	v_cndmask_b32_e32 v32, v33, v32, vcc
	ds_write_b16 v48, v32 offset:336
	v_cvt_f16_f32_e32 v32, v34
	v_cvt_pk_bf16_f32 v33, v34, s0
	v_cndmask_b32_e32 v32, v33, v32, vcc
	ds_write_b16 v48, v32 offset:608
	v_cvt_f16_f32_e32 v32, v35
	v_cvt_pk_bf16_f32 v33, v35, s0
	v_cndmask_b32_e32 v32, v33, v32, vcc
	ds_write_b16 v48, v32 offset:880
	v_cvt_f16_f32_e32 v32, v36
	v_cvt_pk_bf16_f32 v33, v36, s0
	v_cndmask_b32_e32 v32, v33, v32, vcc
	ds_write_b16 v48, v32 offset:2240
	v_cvt_f16_f32_e32 v32, v37
	v_cvt_pk_bf16_f32 v33, v37, s0
	v_cndmask_b32_e32 v32, v33, v32, vcc
	ds_write_b16 v48, v32 offset:2512
	v_cvt_f16_f32_e32 v32, v38
	v_cvt_pk_bf16_f32 v33, v38, s0
	v_cndmask_b32_e32 v32, v33, v32, vcc
	ds_write_b16 v48, v32 offset:2784
	v_cvt_f16_f32_e32 v32, v39
	v_cvt_pk_bf16_f32 v33, v39, s0
	v_cndmask_b32_e32 v32, v33, v32, vcc
	ds_write_b16 v48, v32 offset:3056
	v_cvt_f16_f32_e32 v32, v40
	v_cvt_pk_bf16_f32 v33, v40, s0
	v_cndmask_b32_e32 v32, v33, v32, vcc
	ds_write_b16 v48, v32 offset:4416
	v_cvt_f16_f32_e32 v32, v41
	v_cvt_pk_bf16_f32 v33, v41, s0
	v_cndmask_b32_e32 v32, v33, v32, vcc
	ds_write_b16 v48, v32 offset:4688
	v_cvt_f16_f32_e32 v32, v42
	v_cvt_pk_bf16_f32 v33, v42, s0
	v_cndmask_b32_e32 v32, v33, v32, vcc
	ds_write_b16 v48, v32 offset:4960
	v_cvt_f16_f32_e32 v32, v43
	v_cvt_pk_bf16_f32 v33, v43, s0
	v_cndmask_b32_e32 v32, v33, v32, vcc
	ds_write_b16 v48, v32 offset:5232
	v_cvt_f16_f32_e32 v32, v44
	v_cvt_pk_bf16_f32 v33, v44, s0
	v_cndmask_b32_e32 v32, v33, v32, vcc
	ds_write_b16 v48, v32 offset:6592
	v_cvt_f16_f32_e32 v32, v45
	v_cvt_pk_bf16_f32 v33, v45, s0
	v_cndmask_b32_e32 v32, v33, v32, vcc
	ds_write_b16 v48, v32 offset:6864
	v_cvt_f16_f32_e32 v32, v46
	v_cvt_pk_bf16_f32 v33, v46, s0
	v_cndmask_b32_e32 v32, v33, v32, vcc
	ds_write_b16 v48, v32 offset:7136
	v_cvt_f16_f32_e32 v32, v47
	v_cvt_pk_bf16_f32 v33, v47, s0
	v_cndmask_b32_e32 v32, v33, v32, vcc
	ds_write_b16 v48, v32 offset:7408
	v_cvt_f16_f32_e32 v32, v16
	v_cvt_pk_bf16_f32 v16, v16, s0
	v_cndmask_b32_e64 v16, v16, v32, s[40:41]
	ds_write_b16 v48, v16 offset:8704
	v_cvt_f16_f32_e32 v16, v17
	v_cvt_pk_bf16_f32 v17, v17, s0
	v_cndmask_b32_e64 v16, v17, v16, s[40:41]
	ds_write_b16 v48, v16 offset:8976
	v_cvt_f16_f32_e32 v16, v18
	v_cvt_pk_bf16_f32 v17, v18, s0
	v_cndmask_b32_e64 v16, v17, v16, s[40:41]
	ds_write_b16 v48, v16 offset:9248
	v_cvt_f16_f32_e32 v16, v19
	v_cvt_pk_bf16_f32 v17, v19, s0
	v_cndmask_b32_e64 v16, v17, v16, s[40:41]
	ds_write_b16 v48, v16 offset:9520
	v_cvt_f16_f32_e32 v16, v20
	v_cvt_pk_bf16_f32 v17, v20, s0
	v_cndmask_b32_e64 v16, v17, v16, s[40:41]
	ds_write_b16 v48, v16 offset:10880
	v_cvt_f16_f32_e32 v16, v21
	v_cvt_pk_bf16_f32 v17, v21, s0
	v_cndmask_b32_e64 v16, v17, v16, s[40:41]
	ds_write_b16 v48, v16 offset:11152
	v_cvt_f16_f32_e32 v16, v22
	v_cvt_pk_bf16_f32 v17, v22, s0
	v_cndmask_b32_e64 v16, v17, v16, s[40:41]
	ds_write_b16 v48, v16 offset:11424
	v_cvt_f16_f32_e32 v16, v23
	v_cvt_pk_bf16_f32 v17, v23, s0
	v_cndmask_b32_e64 v16, v17, v16, s[40:41]
	ds_write_b16 v48, v16 offset:11696
	v_cvt_f16_f32_e32 v16, v24
	v_cvt_pk_bf16_f32 v17, v24, s0
	v_cndmask_b32_e64 v16, v17, v16, s[40:41]
	ds_write_b16 v48, v16 offset:13056
	v_cvt_f16_f32_e32 v16, v25
	v_cvt_pk_bf16_f32 v17, v25, s0
	v_cndmask_b32_e64 v16, v17, v16, s[40:41]
	ds_write_b16 v48, v16 offset:13328
	v_cvt_f16_f32_e32 v16, v26
	v_cvt_pk_bf16_f32 v17, v26, s0
; DI int ltid() { int t = threadIdx.x; asm volatile("" : "+v"(t)); return t; }
; DI void store_tile16(const unsigned short* Cs, unsigned short* dst, int ldd) {
;   const int tid = ltid();
; #pragma unroll
;   for (int i = 0; i < 8; ++i) {
;     const int idx = tid + 256 * i;
;     const int row = idx >> 4, c8 = (idx & 15) * 8;
;     *(u32x4*)(dst + (size_t)row * ldd + c8) = *(const u32x4*)(Cs + row * 136 + c8);
;   }
; DI void phase_gemm_in(const Params& P, int layer, char* smem) {
;     ...
;     epi_foreach(acc, [&](int row, int col, float v) __attribute__((always_inline)) {
;       const int c = n0 + col;
;       Cs[row * 136 + col] = (c >= C_QI && c < C_CQ) ? f2h(v) : f2bf(v);
;     });
;     __syncthreads();
;     store_tile16(Cs, Z + (size_t)m0 * ZLD + n0, ZLD);
	v_cndmask_b32_e64 v16, v17, v16, s[40:41]
	ds_write_b16 v48, v16 offset:13600
	v_cvt_f16_f32_e32 v16, v27
	v_cvt_pk_bf16_f32 v17, v27, s0
	v_cndmask_b32_e64 v16, v17, v16, s[40:41]
	ds_write_b16 v48, v16 offset:13872
	v_cvt_f16_f32_e32 v16, v28
	v_cvt_pk_bf16_f32 v17, v28, s0
	v_cndmask_b32_e64 v16, v17, v16, s[40:41]
	ds_write_b16 v48, v16 offset:15232
	v_cvt_f16_f32_e32 v16, v29
	v_cvt_pk_bf16_f32 v17, v29, s0
	v_cndmask_b32_e64 v16, v17, v16, s[40:41]
	ds_write_b16 v48, v16 offset:15504
	v_cvt_f16_f32_e32 v16, v30
	v_cvt_pk_bf16_f32 v17, v30, s0
	v_cndmask_b32_e64 v16, v17, v16, s[40:41]
	ds_write_b16 v48, v16 offset:15776
	v_cvt_f16_f32_e32 v16, v31
	v_cvt_pk_bf16_f32 v17, v31, s0
	v_cndmask_b32_e64 v16, v17, v16, s[40:41]
	ds_write_b16 v48, v16 offset:16048
	v_cvt_f16_f32_e32 v16, v0
	v_cvt_pk_bf16_f32 v0, v0, s0
	v_cndmask_b32_e32 v0, v0, v16, vcc
	ds_write_b16 v48, v0 offset:8768
	v_cvt_f16_f32_e32 v0, v1
	v_cvt_pk_bf16_f32 v1, v1, s0
	v_cndmask_b32_e32 v0, v1, v0, vcc
	ds_write_b16 v48, v0 offset:9040
	v_cvt_f16_f32_e32 v0, v2
	v_cvt_pk_bf16_f32 v1, v2, s0
	v_cndmask_b32_e32 v0, v1, v0, vcc
	ds_write_b16 v48, v0 offset:9312
	v_cvt_f16_f32_e32 v0, v3
	v_cvt_pk_bf16_f32 v1, v3, s0
	v_cndmask_b32_e32 v0, v1, v0, vcc
	ds_write_b16 v48, v0 offset:9584
	v_cvt_f16_f32_e32 v0, v4
	v_cvt_pk_bf16_f32 v1, v4, s0
	v_cndmask_b32_e32 v0, v1, v0, vcc
	ds_write_b16 v48, v0 offset:10944
	v_cvt_f16_f32_e32 v0, v5
	v_cvt_pk_bf16_f32 v1, v5, s0
	v_cndmask_b32_e32 v0, v1, v0, vcc
	ds_write_b16 v48, v0 offset:11216
	v_cvt_f16_f32_e32 v0, v6
	v_cvt_pk_bf16_f32 v1, v6, s0
	v_cndmask_b32_e32 v0, v1, v0, vcc
	ds_write_b16 v48, v0 offset:11488
	v_cvt_f16_f32_e32 v0, v7
	v_cvt_pk_bf16_f32 v1, v7, s0
	v_cndmask_b32_e32 v0, v1, v0, vcc
	ds_write_b16 v48, v0 offset:11760
	v_cvt_f16_f32_e32 v0, v8
	v_cvt_pk_bf16_f32 v1, v8, s0
	v_cndmask_b32_e32 v0, v1, v0, vcc
	ds_write_b16 v48, v0 offset:13120
	v_cvt_f16_f32_e32 v0, v9
	v_cvt_pk_bf16_f32 v1, v9, s0
	v_cndmask_b32_e32 v0, v1, v0, vcc
	ds_write_b16 v48, v0 offset:13392
	v_cvt_f16_f32_e32 v0, v10
	v_cvt_pk_bf16_f32 v1, v10, s0
	v_cndmask_b32_e32 v0, v1, v0, vcc
	ds_write_b16 v48, v0 offset:13664
	v_cvt_f16_f32_e32 v0, v11
	v_cvt_pk_bf16_f32 v1, v11, s0
	v_cndmask_b32_e32 v0, v1, v0, vcc
	ds_write_b16 v48, v0 offset:13936
	v_cvt_f16_f32_e32 v0, v12
	v_cvt_pk_bf16_f32 v1, v12, s0
	v_cndmask_b32_e32 v0, v1, v0, vcc
	ds_write_b16 v48, v0 offset:15296
	v_cvt_f16_f32_e32 v0, v13
	v_cvt_pk_bf16_f32 v1, v13, s0
	v_cndmask_b32_e32 v0, v1, v0, vcc
	ds_write_b16 v48, v0 offset:15568
	v_cvt_f16_f32_e32 v0, v14
	v_cvt_pk_bf16_f32 v1, v14, s0
	v_cndmask_b32_e32 v0, v1, v0, vcc
	ds_write_b16 v48, v0 offset:15840
	v_cvt_f16_f32_e32 v0, v15
	v_cvt_pk_bf16_f32 v1, v15, s0
	v_cndmask_b32_e32 v0, v1, v0, vcc
	ds_write_b16 v48, v0 offset:16112
	s_mul_i32 s15, s15, 0xb0000
	s_mul_hi_i32 s0, s0, 0x1600
	s_add_u32 s15, s86, s15
	s_addc_u32 s16, s87, s0
	s_lshl_b64 s[0:1], s[10:11], 1
	v_mov_b32_e32 v8, v161
	s_waitcnt lgkmcnt(0)
	s_barrier
	s_add_u32 s0, s15, s0
	s_addc_u32 s1, s16, s1
	v_lshlrev_b32_e32 v0, 4, v8
	v_and_b32_e32 v136, 0xf0, v0
	v_ashrrev_i32_e32 v6, 4, v8
	v_lshl_add_u64 v[4:5], s[0:1], 0, v[136:137]
	v_mad_u64_u32 v[0:1], s[0:1], v6, s97, v[136:137]
	ds_read_b128 v[0:3], v0
	v_mad_i64_i32 v[6:7], s[0:1], v6, s33, v[4:5]
	s_add_i32 s14, s14, s70
	s_add_i32 s13, s13, s3
	s_waitcnt lgkmcnt(0)
	global_store_dwordx4 v[6:7], v[0:3], off
	s_cmpk_gt_i32 s14, 0x15ff
	s_nop 0
	v_add_u32_e32 v0, 0x100, v8
	v_ashrrev_i32_e32 v6, 4, v0
	v_mad_u64_u32 v[0:1], s[0:1], v6, s97, v[136:137]
	ds_read_b128 v[0:3], v0
	v_mad_i64_i32 v[6:7], s[0:1], v6, s33, v[4:5]
	s_waitcnt lgkmcnt(0)
	global_store_dwordx4 v[6:7], v[0:3], off
	s_nop 1
	v_add_u32_e32 v0, 0x200, v8
	v_ashrrev_i32_e32 v6, 4, v0
	v_mad_u64_u32 v[0:1], s[0:1], v6, s97, v[136:137]
	ds_read_b128 v[0:3], v0
	v_mad_i64_i32 v[6:7], s[0:1], v6, s33, v[4:5]
	s_waitcnt lgkmcnt(0)
	global_store_dwordx4 v[6:7], v[0:3], off
	s_nop 1
	v_add_u32_e32 v0, 0x300, v8
	v_ashrrev_i32_e32 v6, 4, v0
	v_mad_u64_u32 v[0:1], s[0:1], v6, s97, v[136:137]
	ds_read_b128 v[0:3], v0
	v_mad_i64_i32 v[6:7], s[0:1], v6, s33, v[4:5]
	s_waitcnt lgkmcnt(0)
	global_store_dwordx4 v[6:7], v[0:3], off
	s_nop 1
	v_add_u32_e32 v0, 0x400, v8
	v_ashrrev_i32_e32 v6, 4, v0
	v_mad_u64_u32 v[0:1], s[0:1], v6, s97, v[136:137]
	ds_read_b128 v[0:3], v0
	v_mad_i64_i32 v[6:7], s[0:1], v6, s33, v[4:5]
	s_waitcnt lgkmcnt(0)
	global_store_dwordx4 v[6:7], v[0:3], off
	s_nop 1
	v_add_u32_e32 v0, 0x500, v8
	v_ashrrev_i32_e32 v6, 4, v0
	v_mad_u64_u32 v[0:1], s[0:1], v6, s97, v[136:137]
	ds_read_b128 v[0:3], v0
	v_mad_i64_i32 v[6:7], s[0:1], v6, s33, v[4:5]
	s_waitcnt lgkmcnt(0)
	global_store_dwordx4 v[6:7], v[0:3], off
	s_nop 1
	v_add_u32_e32 v0, 0x600, v8
	v_ashrrev_i32_e32 v6, 4, v0
	v_mad_u64_u32 v[0:1], s[0:1], v6, s97, v[136:137]
	ds_read_b128 v[0:3], v0
	v_mad_i64_i32 v[6:7], s[0:1], v6, s33, v[4:5]
	s_waitcnt lgkmcnt(0)
	global_store_dwordx4 v[6:7], v[0:3], off
	s_nop 1
	v_add_u32_e32 v0, 0x700, v8
	v_ashrrev_i32_e32 v6, 4, v0
	v_mad_u64_u32 v[0:1], s[0:1], v6, s97, v[136:137]
	ds_read_b128 v[0:3], v0
	v_mad_i64_i32 v[4:5], s[0:1], v6, s33, v[4:5]
	s_waitcnt lgkmcnt(0)
	global_store_dwordx4 v[4:5], v[0:3], off
	s_barrier
	s_cbranch_scc0 .LBB0_436
